# P10 top-k: four sort groups' score rows in flight (group loops unrolled x4 over four load register sets)
# speedup vs baseline: 1.0029x; 1.0029x over previous
; DI void topk_half(const _Float16* __restrict__ sp, unsigned (&R)[16]) {
; #pragma unroll
;   for (int e = 0; e < 16; ++e) R[e] = 0u;
; #pragma unroll 1
;   for (int gi = 0; gi < 8; ++gi) {
;     unsigned Gk[16];
; #pragma unroll
;     for (int e = 0; e < 16; ++e) {
;       const int n = gi * 16 + e;
;       const unsigned bits = __builtin_bit_cast(unsigned short, sp[(long)n * NTOK]);
;       const unsigned o = (bits & 0x8000u) ? (~bits & 0xffffu) : (bits | 0x8000u);
;       Gk[e] = (o << 16) | (unsigned)(127 - n);
; DI void phase10(const Params& P, char* smem) {
;     ...
;     topk_half(ST + ((long)(h * 2 + 0) * 128) * NTOK + t, R1);
.LBB0_1183:
	v_alignbit_b32 v1, v129, v128, 15
	v_lshlrev_b32_e32 v4, 1, v1
	v_ashrrev_i32_e32 v5, 31, v4
	v_lshlrev_b64 v[4:5], 23, v[4:5]
	v_and_b32_e32 v1, 0x7fff, v26
	v_lshrrev_b64 v[2:3], 15, v[128:129]
	v_lshl_or_b32 v4, v1, 1, v4
	v_lshl_add_u64 v[6:7], s[40:41], 0, v[4:5]
	s_movk_i32 s91, 0x70
	v_mov_b32_e32 v35, 0
	v_mov_b32_e32 v24, 0
	v_mov_b32_e32 v40, 0
	v_mov_b32_e32 v41, 0
	v_mov_b32_e32 v39, 0
	v_mov_b32_e32 v25, 0
	v_mov_b32_e32 v38, 0
	v_mov_b32_e32 v36, 0
	v_mov_b32_e32 v33, 0
	v_mov_b32_e32 v32, 0
	v_mov_b32_e32 v31, 0
	v_mov_b32_e32 v30, 0
	v_mov_b32_e32 v3, 0
	v_mov_b32_e32 v1, 0
	v_mov_b32_e32 v34, 0
	v_mov_b32_e32 v37, 0
	v_lshrrev_b32_e32 v88, 3, v208
	v_and_b32_e32 v89, 7, v208
	v_lshlrev_b32_e32 v88, 16, v88
	v_lshl_add_u32 v88, v89, 4, v88
	v_lshlrev_b32_e32 v89, 1, v208
	v_sub_u32_e32 v88, v88, v89
	v_add_u32_e32 v86, v4, v88
	v_and_b32_e32 v100, 0x3c00, v209
	v_lshlrev_b32_e32 v100, 1, v100
	v_add_u32_e32 v101, v100, v89
	v_lshl_add_u32 v100, v208, 4, v100
	global_load_dwordx4 v[90:93], v86, s[40:41]
	v_add_u32_e32 v87, 0x80000, v86
	global_load_dwordx4 v[94:97], v87, s[40:41]
	v_add_u32_e32 v86, 0x100000, v86
	global_load_dwordx4 v[144:147], v86, s[40:41]
	v_add_u32_e32 v87, 0x80000, v86
	global_load_dwordx4 v[148:151], v87, s[40:41]
	v_add_u32_e32 v86, 0x100000, v86
	global_load_dwordx4 v[152:155], v86, s[40:41]
	v_add_u32_e32 v87, 0x80000, v86
	global_load_dwordx4 v[156:159], v87, s[40:41]
	v_add_u32_e32 v86, 0x100000, v86
	global_load_dwordx4 v[160:163], v86, s[40:41]
	v_add_u32_e32 v87, 0x80000, v86
	global_load_dwordx4 v[164:167], v87, s[40:41]
	v_add_u32_e32 v86, 0x100000, v86
.LBB0_1184:
	s_waitcnt vmcnt(6)
	ds_write_b128 v100, v[90:93]
	ds_write_b128 v100, v[94:97] offset:1024
	s_waitcnt lgkmcnt(0)
	global_load_dwordx4 v[90:93], v86, s[40:41]
	v_add_u32_e32 v87, 0x80000, v86
	global_load_dwordx4 v[94:97], v87, s[40:41]
	v_add_u32_e32 v86, 0x100000, v86
	ds_read_u16 v42, v101
	ds_read_u16 v47, v101 offset:128
	ds_read_u16 v46, v101 offset:256
	ds_read_u16 v45, v101 offset:384
	ds_read_u16 v44, v101 offset:512
	ds_read_u16 v43, v101 offset:640
	ds_read_u16 v17, v101 offset:768
	ds_read_u16 v16, v101 offset:896
	ds_read_u16 v14, v101 offset:1024
	ds_read_u16 v13, v101 offset:1152
	ds_read_u16 v12, v101 offset:1280
	ds_read_u16 v11, v101 offset:1408
	ds_read_u16 v10, v101 offset:1536
	ds_read_u16 v9, v101 offset:1664
	ds_read_u16 v8, v101 offset:1792
	ds_read_u16 v15, v101 offset:1920
	s_waitcnt lgkmcnt(0)
	v_and_b32_e32 v18, 0xffff, v42
	v_bitop3_b32 v19, v18, s57, v18 bitop3:0xc
	v_or_b32_e32 v18, 0x8000, v18
	v_cmp_gt_i16_e32 vcc, 0, v42
	v_and_b32_e32 v20, 0xffff, v47
	v_and_b32_e32 v21, 0xffff, v46
	v_and_b32_e32 v22, 0xffff, v45
	v_and_b32_e32 v23, 0xffff, v44
	v_and_b32_e32 v48, 0xffff, v43
	v_and_b32_e32 v49, 0xffff, v17
	v_and_b32_e32 v50, 0xffff, v16
	v_and_b32_e32 v51, 0xffff, v14
	v_and_b32_e32 v52, 0xffff, v13
	v_and_b32_e32 v53, 0xffff, v12
	v_and_b32_e32 v54, 0xffff, v11
	v_and_b32_e32 v55, 0xffff, v10
	v_and_b32_e32 v56, 0xffff, v9
	v_and_b32_e32 v57, 0xffff, v8
	v_and_b32_e32 v58, 0xffff, v15
	v_cndmask_b32_e32 v18, v18, v19, vcc
	v_bitop3_b32 v19, v20, s57, v20 bitop3:0xc
	v_or_b32_e32 v20, 0x8000, v20
	v_cmp_gt_i16_e32 vcc, 0, v47
	v_bitop3_b32 v42, v21, s57, v21 bitop3:0xc
	v_or_b32_e32 v21, 0x8000, v21
	v_cmp_gt_i16_e64 s[0:1], 0, v46
	v_bitop3_b32 v46, v22, s57, v22 bitop3:0xc
	v_or_b32_e32 v22, 0x8000, v22
	v_cmp_gt_i16_e64 s[6:7], 0, v45
	v_bitop3_b32 v45, v23, s57, v23 bitop3:0xc
	v_or_b32_e32 v23, 0x8000, v23
	v_cmp_gt_i16_e64 s[8:9], 0, v44
	v_bitop3_b32 v44, v48, s57, v48 bitop3:0xc
	v_or_b32_e32 v47, 0x8000, v48
	v_cmp_gt_i16_e64 s[10:11], 0, v43
	v_bitop3_b32 v43, v49, s57, v49 bitop3:0xc
	v_or_b32_e32 v48, 0x8000, v49
	v_cmp_gt_i16_e64 s[12:13], 0, v17
	v_bitop3_b32 v17, v50, s57, v50 bitop3:0xc
	v_or_b32_e32 v49, 0x8000, v50
	v_cmp_gt_i16_e64 s[14:15], 0, v16
	v_bitop3_b32 v16, v51, s57, v51 bitop3:0xc
	v_or_b32_e32 v50, 0x8000, v51
	v_cmp_gt_i16_e64 s[16:17], 0, v14
	v_bitop3_b32 v14, v52, s57, v52 bitop3:0xc
	v_or_b32_e32 v51, 0x8000, v52
	v_cmp_gt_i16_e64 s[18:19], 0, v13
	v_bitop3_b32 v13, v53, s57, v53 bitop3:0xc
	v_or_b32_e32 v52, 0x8000, v53
	v_cmp_gt_i16_e64 s[20:21], 0, v12
	v_bitop3_b32 v12, v54, s57, v54 bitop3:0xc
	v_or_b32_e32 v53, 0x8000, v54
	v_cmp_gt_i16_e64 s[24:25], 0, v11
	v_bitop3_b32 v11, v55, s57, v55 bitop3:0xc
	v_or_b32_e32 v54, 0x8000, v55
	v_cmp_gt_i16_e64 s[26:27], 0, v10
	v_bitop3_b32 v10, v56, s57, v56 bitop3:0xc
	v_or_b32_e32 v55, 0x8000, v56
	v_cmp_gt_i16_e64 s[28:29], 0, v9
	v_bitop3_b32 v9, v57, s57, v57 bitop3:0xc
	v_or_b32_e32 v56, 0x8000, v57
	v_cmp_gt_i16_e64 s[30:31], 0, v8
	v_bitop3_b32 v8, v58, s57, v58 bitop3:0xc
	v_or_b32_e32 v57, 0x8000, v58
	v_cmp_gt_i16_e64 s[34:35], 0, v15
	v_lshlrev_b32_e32 v15, 16, v18
	v_cndmask_b32_e32 v18, v20, v19, vcc
	v_cndmask_b32_e64 v19, v21, v42, s[0:1]
	v_cndmask_b32_e64 v20, v22, v46, s[6:7]
	v_cndmask_b32_e64 v21, v23, v45, s[8:9]
	v_cndmask_b32_e64 v22, v47, v44, s[10:11]
	v_cndmask_b32_e64 v23, v48, v43, s[12:13]
	v_cndmask_b32_e64 v17, v49, v17, s[14:15]
	v_cndmask_b32_e64 v16, v50, v16, s[16:17]
	v_cndmask_b32_e64 v14, v51, v14, s[18:19]
	v_cndmask_b32_e64 v13, v52, v13, s[20:21]
	v_cndmask_b32_e64 v12, v53, v12, s[24:25]
	v_cndmask_b32_e64 v11, v54, v11, s[26:27]
	v_cndmask_b32_e64 v10, v55, v10, s[28:29]
	v_cndmask_b32_e64 v9, v56, v9, s[30:31]
	v_cndmask_b32_e64 v8, v57, v8, s[34:35]
	v_lshlrev_b32_e32 v18, 16, v18
	v_lshlrev_b32_e32 v19, 16, v19
	v_lshlrev_b32_e32 v20, 16, v20
	v_lshlrev_b32_e32 v21, 16, v21
	v_lshlrev_b32_e32 v22, 16, v22
	v_lshlrev_b32_e32 v23, 16, v23
; DI void topk_half(const _Float16* __restrict__ sp, unsigned (&R)[16]) {
;     ...
;     for (int e = 0; e < 16; ++e) {
;       const int n = gi * 16 + e;
;       const unsigned bits = __builtin_bit_cast(unsigned short, sp[(long)n * NTOK]);
;       const unsigned o = (bits & 0x8000u) ? (~bits & 0xffffu) : (bits | 0x8000u);
;       Gk[e] = (o << 16) | (unsigned)(127 - n);
;     }
;     SORT16(Gk)
;     MERGE16(R, Gk)
	v_lshlrev_b32_e32 v17, 16, v17
	v_lshlrev_b32_e32 v16, 16, v16
	v_lshlrev_b32_e32 v14, 16, v14
	v_lshlrev_b32_e32 v13, 16, v13
	v_lshlrev_b32_e32 v12, 16, v12
	v_lshlrev_b32_e32 v11, 16, v11
	v_lshlrev_b32_e32 v10, 16, v10
	v_lshlrev_b32_e32 v9, 16, v9
	v_add3_u32 v15, s91, v15, 15
	v_lshl_add_u32 v8, v8, 16, s91
	v_add3_u32 v18, s91, v18, 14
	v_add3_u32 v19, s91, v19, 13
	v_add3_u32 v20, s91, v20, 12
	v_add3_u32 v21, s91, v21, 11
	v_add3_u32 v22, s91, v22, 10
	v_add3_u32 v23, s91, v23, 9
	v_add3_u32 v17, s91, v17, 8
	v_add3_u32 v16, s91, v16, 7
	v_add3_u32 v14, s91, v14, 6
	v_add3_u32 v13, s91, v13, 5
	v_add3_u32 v12, s91, v12, 4
	v_add3_u32 v11, s91, v11, 3
	v_add3_u32 v10, s91, v10, 2
	v_add3_u32 v9, s91, v9, 1
	v_max_u32_e32 v42, v15, v18
	v_min_u32_e32 v15, v15, v18
	v_max_u32_e32 v18, v19, v20
	v_min_u32_e32 v19, v19, v20
	v_max_u32_e32 v20, v21, v22
	v_min_u32_e32 v21, v21, v22
	v_max_u32_e32 v22, v23, v17
	v_min_u32_e32 v17, v23, v17
	v_max_u32_e32 v23, v16, v14
	v_min_u32_e32 v14, v16, v14
	v_max_u32_e32 v16, v13, v12
	v_min_u32_e32 v12, v13, v12
	v_max_u32_e32 v13, v11, v10
	v_min_u32_e32 v10, v11, v10
	v_max_u32_e32 v11, v9, v8
	v_min_u32_e32 v8, v9, v8
	v_max_u32_e32 v9, v42, v18
	v_min_u32_e32 v18, v42, v18
	v_max_u32_e32 v42, v15, v19
	v_min_u32_e32 v15, v15, v19
	v_max_u32_e32 v19, v20, v22
	v_min_u32_e32 v20, v20, v22
	v_max_u32_e32 v22, v21, v17
	v_min_u32_e32 v17, v21, v17
	v_max_u32_e32 v21, v23, v16
	v_min_u32_e32 v16, v23, v16
	v_max_u32_e32 v23, v14, v12
	v_min_u32_e32 v12, v14, v12
	v_max_u32_e32 v14, v13, v11
	v_min_u32_e32 v11, v13, v11
	v_max_u32_e32 v13, v10, v8
	v_min_u32_e32 v8, v10, v8
	v_max_u32_e32 v10, v42, v18
	v_min_u32_e32 v18, v42, v18
	v_max_u32_e32 v42, v22, v20
	v_min_u32_e32 v20, v22, v20
	v_max_u32_e32 v22, v23, v16
	v_min_u32_e32 v16, v23, v16
	v_max_u32_e32 v23, v13, v11
	v_min_u32_e32 v11, v13, v11
	v_max_u32_e32 v13, v9, v19
	v_min_u32_e32 v9, v9, v19
	v_max_u32_e32 v19, v15, v17
	v_min_u32_e32 v15, v15, v17
	v_max_u32_e32 v17, v21, v14
	v_min_u32_e32 v14, v21, v14
	v_max_u32_e32 v21, v12, v8
	v_min_u32_e32 v8, v12, v8
	v_max_u32_e32 v12, v10, v42
	v_min_u32_e32 v10, v10, v42
	v_max_u32_e32 v42, v18, v20
	v_min_u32_e32 v18, v18, v20
	v_max_u32_e32 v20, v22, v23
	v_min_u32_e32 v22, v22, v23
	v_max_u32_e32 v23, v16, v11
	v_min_u32_e32 v11, v16, v11
	v_min_u32_e32 v16, v13, v17
	v_max_u32_e32 v43, v15, v8
	v_min_u32_e32 v8, v15, v8
	v_max3_u32 v13, v37, v13, v17
	v_max_u32_e32 v15, v42, v9
	v_min_u32_e32 v9, v42, v9
	v_max_u32_e32 v17, v19, v10
	v_min_u32_e32 v10, v19, v10
	v_max_u32_e32 v19, v23, v14
	v_min_u32_e32 v14, v23, v14
	v_max_u32_e32 v23, v21, v22
	v_min_u32_e32 v21, v21, v22
	v_max_u32_e32 v22, v12, v15
	v_min_u32_e32 v12, v12, v15
	v_max_u32_e32 v15, v17, v9
	v_min_u32_e32 v9, v17, v9
	v_max_u32_e32 v17, v10, v18
	v_min_u32_e32 v10, v10, v18
	v_max_u32_e32 v18, v20, v19
	v_min_u32_e32 v19, v20, v19
	v_max_u32_e32 v20, v23, v14
	v_min_u32_e32 v14, v23, v14
	v_max_u32_e32 v23, v21, v11
	v_min_u32_e32 v11, v21, v11
	v_max_u32_e32 v21, v22, v18
	v_min_u32_e32 v18, v22, v18
	v_max_u32_e32 v22, v12, v19
	v_min_u32_e32 v12, v12, v19
	v_max_u32_e32 v19, v15, v20
	v_min_u32_e32 v15, v15, v20
	v_max_u32_e32 v20, v9, v14
	v_min_u32_e32 v9, v9, v14
	v_max_u32_e32 v14, v17, v23
	v_min_u32_e32 v17, v17, v23
	v_max_u32_e32 v23, v10, v11
	v_min_u32_e32 v10, v10, v11
	v_max_u32_e32 v11, v20, v16
	v_min_u32_e32 v16, v20, v16
	v_max_u32_e32 v20, v14, v18
	v_min_u32_e32 v14, v14, v18
	v_max_u32_e32 v18, v23, v12
	v_min_u32_e32 v12, v23, v12
	v_max_u32_e32 v23, v43, v15
	v_min_u32_e32 v15, v43, v15
	v_max_u32_e32 v8, v35, v8
	v_max_u32_e32 v35, v22, v11
	v_min_u32_e32 v11, v22, v11
	v_max_u32_e32 v22, v19, v20
	v_min_u32_e32 v19, v19, v20
	v_max_u32_e32 v20, v18, v16
	v_min_u32_e32 v16, v18, v16
	v_max_u32_e32 v18, v23, v14
	v_min_u32_e32 v14, v23, v14
	v_max_u32_e32 v23, v12, v9
	v_min_u32_e32 v9, v12, v9
	v_max_u32_e32 v12, v15, v17
	v_min_u32_e32 v15, v15, v17
	v_min_u32_e32 v17, v21, v35
	v_min_u32_e32 v37, v22, v11
	v_min_u32_e32 v42, v19, v20
	v_min_u32_e32 v43, v18, v16
	v_min_u32_e32 v44, v14, v23
	v_min_u32_e32 v45, v12, v9
	v_min_u32_e32 v46, v15, v10
	v_max3_u32 v10, v40, v15, v10
	v_max3_u32 v9, v39, v12, v9
	v_max3_u32 v12, v38, v14, v23
	v_max3_u32 v14, v33, v18, v16
	v_max3_u32 v15, v31, v19, v20
	v_max3_u32 v3, v3, v22, v11
	v_max3_u32 v11, v34, v21, v35
	v_max_u32_e32 v16, v24, v46
	v_max_u32_e32 v18, v41, v45
	v_max_u32_e32 v19, v25, v44
	v_max_u32_e32 v20, v36, v43
	v_max_u32_e32 v21, v32, v42
	v_max_u32_e32 v22, v30, v37
	v_max_u32_e32 v1, v1, v17
	v_max_u32_e32 v17, v8, v14
	v_min_u32_e32 v8, v8, v14
	v_max_u32_e32 v14, v10, v15
	v_min_u32_e32 v10, v10, v15
	v_max_u32_e32 v15, v9, v3
	v_min_u32_e32 v3, v9, v3
	v_max_u32_e32 v9, v12, v11
	v_min_u32_e32 v11, v12, v11
	v_max_u32_e32 v12, v16, v21
	v_min_u32_e32 v16, v16, v21
	v_max_u32_e32 v21, v18, v22
	v_min_u32_e32 v18, v18, v22
	v_max_u32_e32 v22, v19, v1
	v_min_u32_e32 v1, v19, v1
	v_max_u32_e32 v19, v20, v13
	v_min_u32_e32 v13, v20, v13
	v_max_u32_e32 v20, v17, v15
	v_min_u32_e32 v15, v17, v15
	v_max_u32_e32 v17, v14, v9
	v_min_u32_e32 v9, v14, v9
	v_max_u32_e32 v14, v8, v3
	v_min_u32_e32 v3, v8, v3
	v_max_u32_e32 v8, v10, v11
	v_min_u32_e32 v10, v10, v11
	v_max_u32_e32 v11, v12, v22
	v_min_u32_e32 v12, v12, v22
	v_max_u32_e32 v22, v21, v19
	v_min_u32_e32 v19, v21, v19
	v_max_u32_e32 v21, v16, v1
	v_min_u32_e32 v1, v16, v1
	v_max_u32_e32 v16, v18, v13
	v_min_u32_e32 v13, v18, v13
	s_add_i32 s91, s91, -16
	v_max_u32_e32 v18, v20, v17
	v_min_u32_e32 v17, v20, v17
	v_max_u32_e32 v20, v15, v9
	v_min_u32_e32 v9, v15, v9
	v_max_u32_e32 v15, v14, v8
	v_min_u32_e32 v8, v14, v8
	v_max_u32_e32 v14, v3, v10
	v_min_u32_e32 v10, v3, v10
	v_max_u32_e32 v3, v11, v22
	v_min_u32_e32 v11, v11, v22
	v_max_u32_e32 v22, v12, v19
	v_min_u32_e32 v12, v12, v19
	v_max_u32_e32 v19, v21, v16
	v_min_u32_e32 v16, v21, v16
	v_max_u32_e32 v21, v1, v13
	v_min_u32_e32 v13, v1, v13
	v_max_u32_e32 v35, v18, v3
	v_min_u32_e32 v24, v18, v3
	v_max_u32_e32 v40, v17, v11
	v_min_u32_e32 v41, v17, v11
	v_max_u32_e32 v39, v20, v22
	v_min_u32_e32 v25, v20, v22
	v_max_u32_e32 v38, v9, v12
	v_min_u32_e32 v36, v9, v12
	v_max_u32_e32 v33, v15, v19
	v_min_u32_e32 v32, v15, v19
	v_max_u32_e32 v31, v8, v16
	v_min_u32_e32 v30, v8, v16
	v_max_u32_e32 v3, v14, v21
	v_min_u32_e32 v1, v14, v21
	v_max_u32_e32 v34, v10, v13
	v_min_u32_e32 v37, v10, v13
	s_waitcnt vmcnt(6)
; DI void topk_half(const _Float16* __restrict__ sp, unsigned (&R)[16]) {
;     ...
;     for (int e = 0; e < 16; ++e) {
;       const int n = gi * 16 + e;
;       const unsigned bits = __builtin_bit_cast(unsigned short, sp[(long)n * NTOK]);
;       const unsigned o = (bits & 0x8000u) ? (~bits & 0xffffu) : (bits | 0x8000u);
;       Gk[e] = (o << 16) | (unsigned)(127 - n);
;     }
;     SORT16(Gk)
;     MERGE16(R, Gk)
	ds_write_b128 v100, v[144:147]
	ds_write_b128 v100, v[148:151] offset:1024
	s_waitcnt lgkmcnt(0)
	global_load_dwordx4 v[144:147], v86, s[40:41]
	v_add_u32_e32 v87, 0x80000, v86
	global_load_dwordx4 v[148:151], v87, s[40:41]
	v_add_u32_e32 v86, 0x100000, v86
	ds_read_u16 v42, v101
	ds_read_u16 v47, v101 offset:128
	ds_read_u16 v46, v101 offset:256
	ds_read_u16 v45, v101 offset:384
	ds_read_u16 v44, v101 offset:512
	ds_read_u16 v43, v101 offset:640
	ds_read_u16 v17, v101 offset:768
	ds_read_u16 v16, v101 offset:896
	ds_read_u16 v14, v101 offset:1024
	ds_read_u16 v13, v101 offset:1152
	ds_read_u16 v12, v101 offset:1280
	ds_read_u16 v11, v101 offset:1408
	ds_read_u16 v10, v101 offset:1536
	ds_read_u16 v9, v101 offset:1664
	ds_read_u16 v8, v101 offset:1792
	ds_read_u16 v15, v101 offset:1920
	s_waitcnt lgkmcnt(0)
	v_and_b32_e32 v18, 0xffff, v42
	v_bitop3_b32 v19, v18, s57, v18 bitop3:0xc
	v_or_b32_e32 v18, 0x8000, v18
	v_cmp_gt_i16_e32 vcc, 0, v42
	v_and_b32_e32 v20, 0xffff, v47
	v_and_b32_e32 v21, 0xffff, v46
	v_and_b32_e32 v22, 0xffff, v45
	v_and_b32_e32 v23, 0xffff, v44
	v_and_b32_e32 v48, 0xffff, v43
	v_and_b32_e32 v49, 0xffff, v17
	v_and_b32_e32 v50, 0xffff, v16
	v_and_b32_e32 v51, 0xffff, v14
	v_and_b32_e32 v52, 0xffff, v13
	v_and_b32_e32 v53, 0xffff, v12
	v_and_b32_e32 v54, 0xffff, v11
	v_and_b32_e32 v55, 0xffff, v10
	v_and_b32_e32 v56, 0xffff, v9
	v_and_b32_e32 v57, 0xffff, v8
	v_and_b32_e32 v58, 0xffff, v15
	v_cndmask_b32_e32 v18, v18, v19, vcc
	v_bitop3_b32 v19, v20, s57, v20 bitop3:0xc
	v_or_b32_e32 v20, 0x8000, v20
	v_cmp_gt_i16_e32 vcc, 0, v47
	v_bitop3_b32 v42, v21, s57, v21 bitop3:0xc
	v_or_b32_e32 v21, 0x8000, v21
	v_cmp_gt_i16_e64 s[0:1], 0, v46
	v_bitop3_b32 v46, v22, s57, v22 bitop3:0xc
	v_or_b32_e32 v22, 0x8000, v22
	v_cmp_gt_i16_e64 s[6:7], 0, v45
	v_bitop3_b32 v45, v23, s57, v23 bitop3:0xc
	v_or_b32_e32 v23, 0x8000, v23
	v_cmp_gt_i16_e64 s[8:9], 0, v44
	v_bitop3_b32 v44, v48, s57, v48 bitop3:0xc
	v_or_b32_e32 v47, 0x8000, v48
	v_cmp_gt_i16_e64 s[10:11], 0, v43
	v_bitop3_b32 v43, v49, s57, v49 bitop3:0xc
	v_or_b32_e32 v48, 0x8000, v49
	v_cmp_gt_i16_e64 s[12:13], 0, v17
	v_bitop3_b32 v17, v50, s57, v50 bitop3:0xc
	v_or_b32_e32 v49, 0x8000, v50
	v_cmp_gt_i16_e64 s[14:15], 0, v16
	v_bitop3_b32 v16, v51, s57, v51 bitop3:0xc
	v_or_b32_e32 v50, 0x8000, v51
	v_cmp_gt_i16_e64 s[16:17], 0, v14
	v_bitop3_b32 v14, v52, s57, v52 bitop3:0xc
	v_or_b32_e32 v51, 0x8000, v52
	v_cmp_gt_i16_e64 s[18:19], 0, v13
	v_bitop3_b32 v13, v53, s57, v53 bitop3:0xc
	v_or_b32_e32 v52, 0x8000, v53
	v_cmp_gt_i16_e64 s[20:21], 0, v12
	v_bitop3_b32 v12, v54, s57, v54 bitop3:0xc
	v_or_b32_e32 v53, 0x8000, v54
	v_cmp_gt_i16_e64 s[24:25], 0, v11
	v_bitop3_b32 v11, v55, s57, v55 bitop3:0xc
	v_or_b32_e32 v54, 0x8000, v55
	v_cmp_gt_i16_e64 s[26:27], 0, v10
	v_bitop3_b32 v10, v56, s57, v56 bitop3:0xc
	v_or_b32_e32 v55, 0x8000, v56
	v_cmp_gt_i16_e64 s[28:29], 0, v9
	v_bitop3_b32 v9, v57, s57, v57 bitop3:0xc
	v_or_b32_e32 v56, 0x8000, v57
	v_cmp_gt_i16_e64 s[30:31], 0, v8
	v_bitop3_b32 v8, v58, s57, v58 bitop3:0xc
	v_or_b32_e32 v57, 0x8000, v58
	v_cmp_gt_i16_e64 s[34:35], 0, v15
	v_lshlrev_b32_e32 v15, 16, v18
	v_cndmask_b32_e32 v18, v20, v19, vcc
	v_cndmask_b32_e64 v19, v21, v42, s[0:1]
	v_cndmask_b32_e64 v20, v22, v46, s[6:7]
	v_cndmask_b32_e64 v21, v23, v45, s[8:9]
	v_cndmask_b32_e64 v22, v47, v44, s[10:11]
	v_cndmask_b32_e64 v23, v48, v43, s[12:13]
	v_cndmask_b32_e64 v17, v49, v17, s[14:15]
	v_cndmask_b32_e64 v16, v50, v16, s[16:17]
	v_cndmask_b32_e64 v14, v51, v14, s[18:19]
	v_cndmask_b32_e64 v13, v52, v13, s[20:21]
	v_cndmask_b32_e64 v12, v53, v12, s[24:25]
	v_cndmask_b32_e64 v11, v54, v11, s[26:27]
	v_cndmask_b32_e64 v10, v55, v10, s[28:29]
	v_cndmask_b32_e64 v9, v56, v9, s[30:31]
	v_cndmask_b32_e64 v8, v57, v8, s[34:35]
	v_lshlrev_b32_e32 v18, 16, v18
	v_lshlrev_b32_e32 v19, 16, v19
	v_lshlrev_b32_e32 v20, 16, v20
	v_lshlrev_b32_e32 v21, 16, v21
	v_lshlrev_b32_e32 v22, 16, v22
	v_lshlrev_b32_e32 v23, 16, v23
	v_lshlrev_b32_e32 v17, 16, v17
	v_lshlrev_b32_e32 v16, 16, v16
	v_lshlrev_b32_e32 v14, 16, v14
	v_lshlrev_b32_e32 v13, 16, v13
	v_lshlrev_b32_e32 v12, 16, v12
	v_lshlrev_b32_e32 v11, 16, v11
	v_lshlrev_b32_e32 v10, 16, v10
	v_lshlrev_b32_e32 v9, 16, v9
	v_add3_u32 v15, s91, v15, 15
	v_lshl_add_u32 v8, v8, 16, s91
	v_add3_u32 v18, s91, v18, 14
	v_add3_u32 v19, s91, v19, 13
	v_add3_u32 v20, s91, v20, 12
	v_add3_u32 v21, s91, v21, 11
	v_add3_u32 v22, s91, v22, 10
	v_add3_u32 v23, s91, v23, 9
	v_add3_u32 v17, s91, v17, 8
	v_add3_u32 v16, s91, v16, 7
	v_add3_u32 v14, s91, v14, 6
	v_add3_u32 v13, s91, v13, 5
	v_add3_u32 v12, s91, v12, 4
	v_add3_u32 v11, s91, v11, 3
	v_add3_u32 v10, s91, v10, 2
	v_add3_u32 v9, s91, v9, 1
	v_max_u32_e32 v42, v15, v18
	v_min_u32_e32 v15, v15, v18
	v_max_u32_e32 v18, v19, v20
	v_min_u32_e32 v19, v19, v20
	v_max_u32_e32 v20, v21, v22
	v_min_u32_e32 v21, v21, v22
	v_max_u32_e32 v22, v23, v17
	v_min_u32_e32 v17, v23, v17
	v_max_u32_e32 v23, v16, v14
	v_min_u32_e32 v14, v16, v14
	v_max_u32_e32 v16, v13, v12
	v_min_u32_e32 v12, v13, v12
	v_max_u32_e32 v13, v11, v10
	v_min_u32_e32 v10, v11, v10
	v_max_u32_e32 v11, v9, v8
	v_min_u32_e32 v8, v9, v8
	v_max_u32_e32 v9, v42, v18
	v_min_u32_e32 v18, v42, v18
	v_max_u32_e32 v42, v15, v19
	v_min_u32_e32 v15, v15, v19
	v_max_u32_e32 v19, v20, v22
	v_min_u32_e32 v20, v20, v22
	v_max_u32_e32 v22, v21, v17
	v_min_u32_e32 v17, v21, v17
	v_max_u32_e32 v21, v23, v16
	v_min_u32_e32 v16, v23, v16
	v_max_u32_e32 v23, v14, v12
	v_min_u32_e32 v12, v14, v12
	v_max_u32_e32 v14, v13, v11
	v_min_u32_e32 v11, v13, v11
	v_max_u32_e32 v13, v10, v8
	v_min_u32_e32 v8, v10, v8
	v_max_u32_e32 v10, v42, v18
; DI void topk_half(const _Float16* __restrict__ sp, unsigned (&R)[16]) {
;     ...
;   for (int gi = 0; gi < 8; ++gi) {
;     unsigned Gk[16];
; #pragma unroll
;     for (int e = 0; e < 16; ++e) {
;       const int n = gi * 16 + e;
;       const unsigned bits = __builtin_bit_cast(unsigned short, sp[(long)n * NTOK]);
	v_min_u32_e32 v18, v42, v18
	v_max_u32_e32 v42, v22, v20
	v_min_u32_e32 v20, v22, v20
	v_max_u32_e32 v22, v23, v16
	v_min_u32_e32 v16, v23, v16
	v_max_u32_e32 v23, v13, v11
	v_min_u32_e32 v11, v13, v11
	v_max_u32_e32 v13, v9, v19
	v_min_u32_e32 v9, v9, v19
	v_max_u32_e32 v19, v15, v17
	v_min_u32_e32 v15, v15, v17
	v_max_u32_e32 v17, v21, v14
	v_min_u32_e32 v14, v21, v14
	v_max_u32_e32 v21, v12, v8
	v_min_u32_e32 v8, v12, v8
	v_max_u32_e32 v12, v10, v42
	v_min_u32_e32 v10, v10, v42
	v_max_u32_e32 v42, v18, v20
	v_min_u32_e32 v18, v18, v20
	v_max_u32_e32 v20, v22, v23
	v_min_u32_e32 v22, v22, v23
	v_max_u32_e32 v23, v16, v11
	v_min_u32_e32 v11, v16, v11
	v_min_u32_e32 v16, v13, v17
	v_max_u32_e32 v43, v15, v8
	v_min_u32_e32 v8, v15, v8
	v_max3_u32 v13, v37, v13, v17
	v_max_u32_e32 v15, v42, v9
	v_min_u32_e32 v9, v42, v9
	v_max_u32_e32 v17, v19, v10
	v_min_u32_e32 v10, v19, v10
	v_max_u32_e32 v19, v23, v14
	v_min_u32_e32 v14, v23, v14
	v_max_u32_e32 v23, v21, v22
	v_min_u32_e32 v21, v21, v22
	v_max_u32_e32 v22, v12, v15
	v_min_u32_e32 v12, v12, v15
	v_max_u32_e32 v15, v17, v9
	v_min_u32_e32 v9, v17, v9
	v_max_u32_e32 v17, v10, v18
	v_min_u32_e32 v10, v10, v18
	v_max_u32_e32 v18, v20, v19
	v_min_u32_e32 v19, v20, v19
	v_max_u32_e32 v20, v23, v14
	v_min_u32_e32 v14, v23, v14
	v_max_u32_e32 v23, v21, v11
	v_min_u32_e32 v11, v21, v11
	v_max_u32_e32 v21, v22, v18
	v_min_u32_e32 v18, v22, v18
	v_max_u32_e32 v22, v12, v19
	v_min_u32_e32 v12, v12, v19
	v_max_u32_e32 v19, v15, v20
	v_min_u32_e32 v15, v15, v20
	v_max_u32_e32 v20, v9, v14
	v_min_u32_e32 v9, v9, v14
	v_max_u32_e32 v14, v17, v23
	v_min_u32_e32 v17, v17, v23
	v_max_u32_e32 v23, v10, v11
	v_min_u32_e32 v10, v10, v11
	v_max_u32_e32 v11, v20, v16
	v_min_u32_e32 v16, v20, v16
	v_max_u32_e32 v20, v14, v18
	v_min_u32_e32 v14, v14, v18
	v_max_u32_e32 v18, v23, v12
	v_min_u32_e32 v12, v23, v12
	v_max_u32_e32 v23, v43, v15
	v_min_u32_e32 v15, v43, v15
	v_max_u32_e32 v8, v35, v8
	v_max_u32_e32 v35, v22, v11
	v_min_u32_e32 v11, v22, v11
	v_max_u32_e32 v22, v19, v20
	v_min_u32_e32 v19, v19, v20
	v_max_u32_e32 v20, v18, v16
	v_min_u32_e32 v16, v18, v16
	v_max_u32_e32 v18, v23, v14
	v_min_u32_e32 v14, v23, v14
	v_max_u32_e32 v23, v12, v9
	v_min_u32_e32 v9, v12, v9
	v_max_u32_e32 v12, v15, v17
	v_min_u32_e32 v15, v15, v17
	v_min_u32_e32 v17, v21, v35
	v_min_u32_e32 v37, v22, v11
	v_min_u32_e32 v42, v19, v20
	v_min_u32_e32 v43, v18, v16
	v_min_u32_e32 v44, v14, v23
	v_min_u32_e32 v45, v12, v9
	v_min_u32_e32 v46, v15, v10
	v_max3_u32 v10, v40, v15, v10
	v_max3_u32 v9, v39, v12, v9
	v_max3_u32 v12, v38, v14, v23
	v_max3_u32 v14, v33, v18, v16
	v_max3_u32 v15, v31, v19, v20
	v_max3_u32 v3, v3, v22, v11
	v_max3_u32 v11, v34, v21, v35
	v_max_u32_e32 v16, v24, v46
	v_max_u32_e32 v18, v41, v45
	v_max_u32_e32 v19, v25, v44
	v_max_u32_e32 v20, v36, v43
	v_max_u32_e32 v21, v32, v42
	v_max_u32_e32 v22, v30, v37
	v_max_u32_e32 v1, v1, v17
	v_max_u32_e32 v17, v8, v14
	v_min_u32_e32 v8, v8, v14
	v_max_u32_e32 v14, v10, v15
	v_min_u32_e32 v10, v10, v15
	v_max_u32_e32 v15, v9, v3
	v_min_u32_e32 v3, v9, v3
	v_max_u32_e32 v9, v12, v11
	v_min_u32_e32 v11, v12, v11
	v_max_u32_e32 v12, v16, v21
	v_min_u32_e32 v16, v16, v21
	v_max_u32_e32 v21, v18, v22
	v_min_u32_e32 v18, v18, v22
	v_max_u32_e32 v22, v19, v1
	v_min_u32_e32 v1, v19, v1
	v_max_u32_e32 v19, v20, v13
	v_min_u32_e32 v13, v20, v13
	v_max_u32_e32 v20, v17, v15
	v_min_u32_e32 v15, v17, v15
	v_max_u32_e32 v17, v14, v9
	v_min_u32_e32 v9, v14, v9
	v_max_u32_e32 v14, v8, v3
	v_min_u32_e32 v3, v8, v3
	v_max_u32_e32 v8, v10, v11
	v_min_u32_e32 v10, v10, v11
	v_max_u32_e32 v11, v12, v22
	v_min_u32_e32 v12, v12, v22
	v_max_u32_e32 v22, v21, v19
	v_min_u32_e32 v19, v21, v19
	v_max_u32_e32 v21, v16, v1
	v_min_u32_e32 v1, v16, v1
	v_max_u32_e32 v16, v18, v13
	v_min_u32_e32 v13, v18, v13
	s_add_i32 s91, s91, -16
	v_max_u32_e32 v18, v20, v17
	v_min_u32_e32 v17, v20, v17
	v_max_u32_e32 v20, v15, v9
	v_min_u32_e32 v9, v15, v9
	v_max_u32_e32 v15, v14, v8
	v_min_u32_e32 v8, v14, v8
	v_max_u32_e32 v14, v3, v10
	v_min_u32_e32 v10, v3, v10
	v_max_u32_e32 v3, v11, v22
	v_min_u32_e32 v11, v11, v22
	v_max_u32_e32 v22, v12, v19
	v_min_u32_e32 v12, v12, v19
	v_max_u32_e32 v19, v21, v16
	v_min_u32_e32 v16, v21, v16
	v_max_u32_e32 v21, v1, v13
	v_min_u32_e32 v13, v1, v13
	v_max_u32_e32 v35, v18, v3
	v_min_u32_e32 v24, v18, v3
	v_max_u32_e32 v40, v17, v11
	v_min_u32_e32 v41, v17, v11
	v_max_u32_e32 v39, v20, v22
	v_min_u32_e32 v25, v20, v22
	v_max_u32_e32 v38, v9, v12
	v_min_u32_e32 v36, v9, v12
	v_max_u32_e32 v33, v15, v19
	v_min_u32_e32 v32, v15, v19
	v_max_u32_e32 v31, v8, v16
	v_min_u32_e32 v30, v8, v16
	v_max_u32_e32 v3, v14, v21
	v_min_u32_e32 v1, v14, v21
	v_max_u32_e32 v34, v10, v13
	v_min_u32_e32 v37, v10, v13
	s_waitcnt vmcnt(6)
	ds_write_b128 v100, v[152:155]
	ds_write_b128 v100, v[156:159] offset:1024
	s_waitcnt lgkmcnt(0)
	global_load_dwordx4 v[152:155], v86, s[40:41]
	v_add_u32_e32 v87, 0x80000, v86
	global_load_dwordx4 v[156:159], v87, s[40:41]
	v_add_u32_e32 v86, 0x100000, v86
	ds_read_u16 v42, v101
	ds_read_u16 v47, v101 offset:128
	ds_read_u16 v46, v101 offset:256
	ds_read_u16 v45, v101 offset:384
	ds_read_u16 v44, v101 offset:512
	ds_read_u16 v43, v101 offset:640
	ds_read_u16 v17, v101 offset:768
	ds_read_u16 v16, v101 offset:896
	ds_read_u16 v14, v101 offset:1024
	ds_read_u16 v13, v101 offset:1152
	ds_read_u16 v12, v101 offset:1280
	ds_read_u16 v11, v101 offset:1408
	ds_read_u16 v10, v101 offset:1536
	ds_read_u16 v9, v101 offset:1664
	ds_read_u16 v8, v101 offset:1792
	ds_read_u16 v15, v101 offset:1920
	s_waitcnt lgkmcnt(0)
; DI void topk_half(const _Float16* __restrict__ sp, unsigned (&R)[16]) {
;     ...
;     for (int e = 0; e < 16; ++e) {
;       const int n = gi * 16 + e;
;       const unsigned bits = __builtin_bit_cast(unsigned short, sp[(long)n * NTOK]);
;       const unsigned o = (bits & 0x8000u) ? (~bits & 0xffffu) : (bits | 0x8000u);
;       Gk[e] = (o << 16) | (unsigned)(127 - n);
;     }
;     SORT16(Gk)
;     MERGE16(R, Gk)
	v_and_b32_e32 v18, 0xffff, v42
	v_bitop3_b32 v19, v18, s57, v18 bitop3:0xc
	v_or_b32_e32 v18, 0x8000, v18
	v_cmp_gt_i16_e32 vcc, 0, v42
	v_and_b32_e32 v20, 0xffff, v47
	v_and_b32_e32 v21, 0xffff, v46
	v_and_b32_e32 v22, 0xffff, v45
	v_and_b32_e32 v23, 0xffff, v44
	v_and_b32_e32 v48, 0xffff, v43
	v_and_b32_e32 v49, 0xffff, v17
	v_and_b32_e32 v50, 0xffff, v16
	v_and_b32_e32 v51, 0xffff, v14
	v_and_b32_e32 v52, 0xffff, v13
	v_and_b32_e32 v53, 0xffff, v12
	v_and_b32_e32 v54, 0xffff, v11
	v_and_b32_e32 v55, 0xffff, v10
	v_and_b32_e32 v56, 0xffff, v9
	v_and_b32_e32 v57, 0xffff, v8
	v_and_b32_e32 v58, 0xffff, v15
	v_cndmask_b32_e32 v18, v18, v19, vcc
	v_bitop3_b32 v19, v20, s57, v20 bitop3:0xc
	v_or_b32_e32 v20, 0x8000, v20
	v_cmp_gt_i16_e32 vcc, 0, v47
	v_bitop3_b32 v42, v21, s57, v21 bitop3:0xc
	v_or_b32_e32 v21, 0x8000, v21
	v_cmp_gt_i16_e64 s[0:1], 0, v46
	v_bitop3_b32 v46, v22, s57, v22 bitop3:0xc
	v_or_b32_e32 v22, 0x8000, v22
	v_cmp_gt_i16_e64 s[6:7], 0, v45
	v_bitop3_b32 v45, v23, s57, v23 bitop3:0xc
	v_or_b32_e32 v23, 0x8000, v23
	v_cmp_gt_i16_e64 s[8:9], 0, v44
	v_bitop3_b32 v44, v48, s57, v48 bitop3:0xc
	v_or_b32_e32 v47, 0x8000, v48
	v_cmp_gt_i16_e64 s[10:11], 0, v43
	v_bitop3_b32 v43, v49, s57, v49 bitop3:0xc
	v_or_b32_e32 v48, 0x8000, v49
	v_cmp_gt_i16_e64 s[12:13], 0, v17
	v_bitop3_b32 v17, v50, s57, v50 bitop3:0xc
	v_or_b32_e32 v49, 0x8000, v50
	v_cmp_gt_i16_e64 s[14:15], 0, v16
	v_bitop3_b32 v16, v51, s57, v51 bitop3:0xc
	v_or_b32_e32 v50, 0x8000, v51
	v_cmp_gt_i16_e64 s[16:17], 0, v14
	v_bitop3_b32 v14, v52, s57, v52 bitop3:0xc
	v_or_b32_e32 v51, 0x8000, v52
	v_cmp_gt_i16_e64 s[18:19], 0, v13
	v_bitop3_b32 v13, v53, s57, v53 bitop3:0xc
	v_or_b32_e32 v52, 0x8000, v53
	v_cmp_gt_i16_e64 s[20:21], 0, v12
	v_bitop3_b32 v12, v54, s57, v54 bitop3:0xc
	v_or_b32_e32 v53, 0x8000, v54
	v_cmp_gt_i16_e64 s[24:25], 0, v11
	v_bitop3_b32 v11, v55, s57, v55 bitop3:0xc
	v_or_b32_e32 v54, 0x8000, v55
	v_cmp_gt_i16_e64 s[26:27], 0, v10
	v_bitop3_b32 v10, v56, s57, v56 bitop3:0xc
	v_or_b32_e32 v55, 0x8000, v56
	v_cmp_gt_i16_e64 s[28:29], 0, v9
	v_bitop3_b32 v9, v57, s57, v57 bitop3:0xc
	v_or_b32_e32 v56, 0x8000, v57
	v_cmp_gt_i16_e64 s[30:31], 0, v8
	v_bitop3_b32 v8, v58, s57, v58 bitop3:0xc
	v_or_b32_e32 v57, 0x8000, v58
	v_cmp_gt_i16_e64 s[34:35], 0, v15
	v_lshlrev_b32_e32 v15, 16, v18
	v_cndmask_b32_e32 v18, v20, v19, vcc
	v_cndmask_b32_e64 v19, v21, v42, s[0:1]
	v_cndmask_b32_e64 v20, v22, v46, s[6:7]
	v_cndmask_b32_e64 v21, v23, v45, s[8:9]
	v_cndmask_b32_e64 v22, v47, v44, s[10:11]
	v_cndmask_b32_e64 v23, v48, v43, s[12:13]
	v_cndmask_b32_e64 v17, v49, v17, s[14:15]
	v_cndmask_b32_e64 v16, v50, v16, s[16:17]
	v_cndmask_b32_e64 v14, v51, v14, s[18:19]
	v_cndmask_b32_e64 v13, v52, v13, s[20:21]
	v_cndmask_b32_e64 v12, v53, v12, s[24:25]
	v_cndmask_b32_e64 v11, v54, v11, s[26:27]
	v_cndmask_b32_e64 v10, v55, v10, s[28:29]
	v_cndmask_b32_e64 v9, v56, v9, s[30:31]
	v_cndmask_b32_e64 v8, v57, v8, s[34:35]
	v_lshlrev_b32_e32 v18, 16, v18
	v_lshlrev_b32_e32 v19, 16, v19
	v_lshlrev_b32_e32 v20, 16, v20
	v_lshlrev_b32_e32 v21, 16, v21
	v_lshlrev_b32_e32 v22, 16, v22
	v_lshlrev_b32_e32 v23, 16, v23
	v_lshlrev_b32_e32 v17, 16, v17
	v_lshlrev_b32_e32 v16, 16, v16
	v_lshlrev_b32_e32 v14, 16, v14
	v_lshlrev_b32_e32 v13, 16, v13
	v_lshlrev_b32_e32 v12, 16, v12
	v_lshlrev_b32_e32 v11, 16, v11
	v_lshlrev_b32_e32 v10, 16, v10
	v_lshlrev_b32_e32 v9, 16, v9
	v_add3_u32 v15, s91, v15, 15
	v_lshl_add_u32 v8, v8, 16, s91
	v_add3_u32 v18, s91, v18, 14
	v_add3_u32 v19, s91, v19, 13
	v_add3_u32 v20, s91, v20, 12
	v_add3_u32 v21, s91, v21, 11
	v_add3_u32 v22, s91, v22, 10
	v_add3_u32 v23, s91, v23, 9
	v_add3_u32 v17, s91, v17, 8
	v_add3_u32 v16, s91, v16, 7
	v_add3_u32 v14, s91, v14, 6
	v_add3_u32 v13, s91, v13, 5
	v_add3_u32 v12, s91, v12, 4
	v_add3_u32 v11, s91, v11, 3
	v_add3_u32 v10, s91, v10, 2
	v_add3_u32 v9, s91, v9, 1
	v_max_u32_e32 v42, v15, v18
	v_min_u32_e32 v15, v15, v18
	v_max_u32_e32 v18, v19, v20
	v_min_u32_e32 v19, v19, v20
	v_max_u32_e32 v20, v21, v22
	v_min_u32_e32 v21, v21, v22
	v_max_u32_e32 v22, v23, v17
	v_min_u32_e32 v17, v23, v17
	v_max_u32_e32 v23, v16, v14
	v_min_u32_e32 v14, v16, v14
	v_max_u32_e32 v16, v13, v12
	v_min_u32_e32 v12, v13, v12
	v_max_u32_e32 v13, v11, v10
	v_min_u32_e32 v10, v11, v10
	v_max_u32_e32 v11, v9, v8
	v_min_u32_e32 v8, v9, v8
	v_max_u32_e32 v9, v42, v18
	v_min_u32_e32 v18, v42, v18
	v_max_u32_e32 v42, v15, v19
	v_min_u32_e32 v15, v15, v19
	v_max_u32_e32 v19, v20, v22
	v_min_u32_e32 v20, v20, v22
	v_max_u32_e32 v22, v21, v17
	v_min_u32_e32 v17, v21, v17
	v_max_u32_e32 v21, v23, v16
	v_min_u32_e32 v16, v23, v16
	v_max_u32_e32 v23, v14, v12
	v_min_u32_e32 v12, v14, v12
	v_max_u32_e32 v14, v13, v11
	v_min_u32_e32 v11, v13, v11
	v_max_u32_e32 v13, v10, v8
	v_min_u32_e32 v8, v10, v8
	v_max_u32_e32 v10, v42, v18
	v_min_u32_e32 v18, v42, v18
	v_max_u32_e32 v42, v22, v20
	v_min_u32_e32 v20, v22, v20
	v_max_u32_e32 v22, v23, v16
	v_min_u32_e32 v16, v23, v16
	v_max_u32_e32 v23, v13, v11
	v_min_u32_e32 v11, v13, v11
	v_max_u32_e32 v13, v9, v19
	v_min_u32_e32 v9, v9, v19
	v_max_u32_e32 v19, v15, v17
	v_min_u32_e32 v15, v15, v17
	v_max_u32_e32 v17, v21, v14
	v_min_u32_e32 v14, v21, v14
	v_max_u32_e32 v21, v12, v8
	v_min_u32_e32 v8, v12, v8
	v_max_u32_e32 v12, v10, v42
	v_min_u32_e32 v10, v10, v42
	v_max_u32_e32 v42, v18, v20
	v_min_u32_e32 v18, v18, v20
	v_max_u32_e32 v20, v22, v23
	v_min_u32_e32 v22, v22, v23
	v_max_u32_e32 v23, v16, v11
	v_min_u32_e32 v11, v16, v11
	v_min_u32_e32 v16, v13, v17
	v_max_u32_e32 v43, v15, v8
	v_min_u32_e32 v8, v15, v8
	v_max3_u32 v13, v37, v13, v17
	v_max_u32_e32 v15, v42, v9
	v_min_u32_e32 v9, v42, v9
; DI void topk_half(const _Float16* __restrict__ sp, unsigned (&R)[16]) {
;     ...
;   for (int gi = 0; gi < 8; ++gi) {
;     unsigned Gk[16];
; #pragma unroll
;     for (int e = 0; e < 16; ++e) {
;       const int n = gi * 16 + e;
;       const unsigned bits = __builtin_bit_cast(unsigned short, sp[(long)n * NTOK]);
	v_max_u32_e32 v17, v19, v10
	v_min_u32_e32 v10, v19, v10
	v_max_u32_e32 v19, v23, v14
	v_min_u32_e32 v14, v23, v14
	v_max_u32_e32 v23, v21, v22
	v_min_u32_e32 v21, v21, v22
	v_max_u32_e32 v22, v12, v15
	v_min_u32_e32 v12, v12, v15
	v_max_u32_e32 v15, v17, v9
	v_min_u32_e32 v9, v17, v9
	v_max_u32_e32 v17, v10, v18
	v_min_u32_e32 v10, v10, v18
	v_max_u32_e32 v18, v20, v19
	v_min_u32_e32 v19, v20, v19
	v_max_u32_e32 v20, v23, v14
	v_min_u32_e32 v14, v23, v14
	v_max_u32_e32 v23, v21, v11
	v_min_u32_e32 v11, v21, v11
	v_max_u32_e32 v21, v22, v18
	v_min_u32_e32 v18, v22, v18
	v_max_u32_e32 v22, v12, v19
	v_min_u32_e32 v12, v12, v19
	v_max_u32_e32 v19, v15, v20
	v_min_u32_e32 v15, v15, v20
	v_max_u32_e32 v20, v9, v14
	v_min_u32_e32 v9, v9, v14
	v_max_u32_e32 v14, v17, v23
	v_min_u32_e32 v17, v17, v23
	v_max_u32_e32 v23, v10, v11
	v_min_u32_e32 v10, v10, v11
	v_max_u32_e32 v11, v20, v16
	v_min_u32_e32 v16, v20, v16
	v_max_u32_e32 v20, v14, v18
	v_min_u32_e32 v14, v14, v18
	v_max_u32_e32 v18, v23, v12
	v_min_u32_e32 v12, v23, v12
	v_max_u32_e32 v23, v43, v15
	v_min_u32_e32 v15, v43, v15
	v_max_u32_e32 v8, v35, v8
	v_max_u32_e32 v35, v22, v11
	v_min_u32_e32 v11, v22, v11
	v_max_u32_e32 v22, v19, v20
	v_min_u32_e32 v19, v19, v20
	v_max_u32_e32 v20, v18, v16
	v_min_u32_e32 v16, v18, v16
	v_max_u32_e32 v18, v23, v14
	v_min_u32_e32 v14, v23, v14
	v_max_u32_e32 v23, v12, v9
	v_min_u32_e32 v9, v12, v9
	v_max_u32_e32 v12, v15, v17
	v_min_u32_e32 v15, v15, v17
	v_min_u32_e32 v17, v21, v35
	v_min_u32_e32 v37, v22, v11
	v_min_u32_e32 v42, v19, v20
	v_min_u32_e32 v43, v18, v16
	v_min_u32_e32 v44, v14, v23
	v_min_u32_e32 v45, v12, v9
	v_min_u32_e32 v46, v15, v10
	v_max3_u32 v10, v40, v15, v10
	v_max3_u32 v9, v39, v12, v9
	v_max3_u32 v12, v38, v14, v23
	v_max3_u32 v14, v33, v18, v16
	v_max3_u32 v15, v31, v19, v20
	v_max3_u32 v3, v3, v22, v11
	v_max3_u32 v11, v34, v21, v35
	v_max_u32_e32 v16, v24, v46
	v_max_u32_e32 v18, v41, v45
	v_max_u32_e32 v19, v25, v44
	v_max_u32_e32 v20, v36, v43
	v_max_u32_e32 v21, v32, v42
	v_max_u32_e32 v22, v30, v37
	v_max_u32_e32 v1, v1, v17
	v_max_u32_e32 v17, v8, v14
	v_min_u32_e32 v8, v8, v14
	v_max_u32_e32 v14, v10, v15
	v_min_u32_e32 v10, v10, v15
	v_max_u32_e32 v15, v9, v3
	v_min_u32_e32 v3, v9, v3
	v_max_u32_e32 v9, v12, v11
	v_min_u32_e32 v11, v12, v11
	v_max_u32_e32 v12, v16, v21
	v_min_u32_e32 v16, v16, v21
	v_max_u32_e32 v21, v18, v22
	v_min_u32_e32 v18, v18, v22
	v_max_u32_e32 v22, v19, v1
	v_min_u32_e32 v1, v19, v1
	v_max_u32_e32 v19, v20, v13
	v_min_u32_e32 v13, v20, v13
	v_max_u32_e32 v20, v17, v15
	v_min_u32_e32 v15, v17, v15
	v_max_u32_e32 v17, v14, v9
	v_min_u32_e32 v9, v14, v9
	v_max_u32_e32 v14, v8, v3
	v_min_u32_e32 v3, v8, v3
	v_max_u32_e32 v8, v10, v11
	v_min_u32_e32 v10, v10, v11
	v_max_u32_e32 v11, v12, v22
	v_min_u32_e32 v12, v12, v22
	v_max_u32_e32 v22, v21, v19
	v_min_u32_e32 v19, v21, v19
	v_max_u32_e32 v21, v16, v1
	v_min_u32_e32 v1, v16, v1
	v_max_u32_e32 v16, v18, v13
	v_min_u32_e32 v13, v18, v13
	s_add_i32 s91, s91, -16
	v_max_u32_e32 v18, v20, v17
	v_min_u32_e32 v17, v20, v17
	v_max_u32_e32 v20, v15, v9
	v_min_u32_e32 v9, v15, v9
	v_max_u32_e32 v15, v14, v8
	v_min_u32_e32 v8, v14, v8
	v_max_u32_e32 v14, v3, v10
	v_min_u32_e32 v10, v3, v10
	v_max_u32_e32 v3, v11, v22
	v_min_u32_e32 v11, v11, v22
	v_max_u32_e32 v22, v12, v19
	v_min_u32_e32 v12, v12, v19
	v_max_u32_e32 v19, v21, v16
	v_min_u32_e32 v16, v21, v16
	v_max_u32_e32 v21, v1, v13
	v_min_u32_e32 v13, v1, v13
	v_max_u32_e32 v35, v18, v3
	v_min_u32_e32 v24, v18, v3
	v_max_u32_e32 v40, v17, v11
	v_min_u32_e32 v41, v17, v11
	v_max_u32_e32 v39, v20, v22
	v_min_u32_e32 v25, v20, v22
	v_max_u32_e32 v38, v9, v12
	v_min_u32_e32 v36, v9, v12
	v_max_u32_e32 v33, v15, v19
	v_min_u32_e32 v32, v15, v19
	v_max_u32_e32 v31, v8, v16
	v_min_u32_e32 v30, v8, v16
	v_max_u32_e32 v3, v14, v21
	v_min_u32_e32 v1, v14, v21
	v_max_u32_e32 v34, v10, v13
	v_min_u32_e32 v37, v10, v13
	s_waitcnt vmcnt(6)
	ds_write_b128 v100, v[160:163]
	ds_write_b128 v100, v[164:167] offset:1024
	s_waitcnt lgkmcnt(0)
	global_load_dwordx4 v[160:163], v86, s[40:41]
	v_add_u32_e32 v87, 0x80000, v86
	global_load_dwordx4 v[164:167], v87, s[40:41]
	v_add_u32_e32 v86, 0x100000, v86
	ds_read_u16 v42, v101
	ds_read_u16 v47, v101 offset:128
	ds_read_u16 v46, v101 offset:256
	ds_read_u16 v45, v101 offset:384
	ds_read_u16 v44, v101 offset:512
	ds_read_u16 v43, v101 offset:640
	ds_read_u16 v17, v101 offset:768
	ds_read_u16 v16, v101 offset:896
	ds_read_u16 v14, v101 offset:1024
	ds_read_u16 v13, v101 offset:1152
	ds_read_u16 v12, v101 offset:1280
	ds_read_u16 v11, v101 offset:1408
	ds_read_u16 v10, v101 offset:1536
	ds_read_u16 v9, v101 offset:1664
	ds_read_u16 v8, v101 offset:1792
	ds_read_u16 v15, v101 offset:1920
	s_waitcnt lgkmcnt(0)
; DI void topk_half(const _Float16* __restrict__ sp, unsigned (&R)[16]) {
;     ...
;     for (int e = 0; e < 16; ++e) {
;       const int n = gi * 16 + e;
;       const unsigned bits = __builtin_bit_cast(unsigned short, sp[(long)n * NTOK]);
;       const unsigned o = (bits & 0x8000u) ? (~bits & 0xffffu) : (bits | 0x8000u);
;       Gk[e] = (o << 16) | (unsigned)(127 - n);
;     }
;     SORT16(Gk)
;     MERGE16(R, Gk)
	v_and_b32_e32 v18, 0xffff, v42
	v_bitop3_b32 v19, v18, s57, v18 bitop3:0xc
	v_or_b32_e32 v18, 0x8000, v18
	v_cmp_gt_i16_e32 vcc, 0, v42
	v_and_b32_e32 v20, 0xffff, v47
	v_and_b32_e32 v21, 0xffff, v46
	v_and_b32_e32 v22, 0xffff, v45
	v_and_b32_e32 v23, 0xffff, v44
	v_and_b32_e32 v48, 0xffff, v43
	v_and_b32_e32 v49, 0xffff, v17
	v_and_b32_e32 v50, 0xffff, v16
	v_and_b32_e32 v51, 0xffff, v14
	v_and_b32_e32 v52, 0xffff, v13
	v_and_b32_e32 v53, 0xffff, v12
	v_and_b32_e32 v54, 0xffff, v11
	v_and_b32_e32 v55, 0xffff, v10
	v_and_b32_e32 v56, 0xffff, v9
	v_and_b32_e32 v57, 0xffff, v8
	v_and_b32_e32 v58, 0xffff, v15
	v_cndmask_b32_e32 v18, v18, v19, vcc
	v_bitop3_b32 v19, v20, s57, v20 bitop3:0xc
	v_or_b32_e32 v20, 0x8000, v20
	v_cmp_gt_i16_e32 vcc, 0, v47
	v_bitop3_b32 v42, v21, s57, v21 bitop3:0xc
	v_or_b32_e32 v21, 0x8000, v21
	v_cmp_gt_i16_e64 s[0:1], 0, v46
	v_bitop3_b32 v46, v22, s57, v22 bitop3:0xc
	v_or_b32_e32 v22, 0x8000, v22
	v_cmp_gt_i16_e64 s[6:7], 0, v45
	v_bitop3_b32 v45, v23, s57, v23 bitop3:0xc
	v_or_b32_e32 v23, 0x8000, v23
	v_cmp_gt_i16_e64 s[8:9], 0, v44
	v_bitop3_b32 v44, v48, s57, v48 bitop3:0xc
	v_or_b32_e32 v47, 0x8000, v48
	v_cmp_gt_i16_e64 s[10:11], 0, v43
	v_bitop3_b32 v43, v49, s57, v49 bitop3:0xc
	v_or_b32_e32 v48, 0x8000, v49
	v_cmp_gt_i16_e64 s[12:13], 0, v17
	v_bitop3_b32 v17, v50, s57, v50 bitop3:0xc
	v_or_b32_e32 v49, 0x8000, v50
	v_cmp_gt_i16_e64 s[14:15], 0, v16
	v_bitop3_b32 v16, v51, s57, v51 bitop3:0xc
	v_or_b32_e32 v50, 0x8000, v51
	v_cmp_gt_i16_e64 s[16:17], 0, v14
	v_bitop3_b32 v14, v52, s57, v52 bitop3:0xc
	v_or_b32_e32 v51, 0x8000, v52
	v_cmp_gt_i16_e64 s[18:19], 0, v13
	v_bitop3_b32 v13, v53, s57, v53 bitop3:0xc
	v_or_b32_e32 v52, 0x8000, v53
	v_cmp_gt_i16_e64 s[20:21], 0, v12
	v_bitop3_b32 v12, v54, s57, v54 bitop3:0xc
	v_or_b32_e32 v53, 0x8000, v54
	v_cmp_gt_i16_e64 s[24:25], 0, v11
	v_bitop3_b32 v11, v55, s57, v55 bitop3:0xc
	v_or_b32_e32 v54, 0x8000, v55
	v_cmp_gt_i16_e64 s[26:27], 0, v10
	v_bitop3_b32 v10, v56, s57, v56 bitop3:0xc
	v_or_b32_e32 v55, 0x8000, v56
	v_cmp_gt_i16_e64 s[28:29], 0, v9
	v_bitop3_b32 v9, v57, s57, v57 bitop3:0xc
	v_or_b32_e32 v56, 0x8000, v57
	v_cmp_gt_i16_e64 s[30:31], 0, v8
	v_bitop3_b32 v8, v58, s57, v58 bitop3:0xc
	v_or_b32_e32 v57, 0x8000, v58
	v_cmp_gt_i16_e64 s[34:35], 0, v15
	v_lshlrev_b32_e32 v15, 16, v18
	v_cndmask_b32_e32 v18, v20, v19, vcc
	v_cndmask_b32_e64 v19, v21, v42, s[0:1]
	v_cndmask_b32_e64 v20, v22, v46, s[6:7]
	v_cndmask_b32_e64 v21, v23, v45, s[8:9]
	v_cndmask_b32_e64 v22, v47, v44, s[10:11]
	v_cndmask_b32_e64 v23, v48, v43, s[12:13]
	v_cndmask_b32_e64 v17, v49, v17, s[14:15]
	v_cndmask_b32_e64 v16, v50, v16, s[16:17]
	v_cndmask_b32_e64 v14, v51, v14, s[18:19]
	v_cndmask_b32_e64 v13, v52, v13, s[20:21]
	v_cndmask_b32_e64 v12, v53, v12, s[24:25]
	v_cndmask_b32_e64 v11, v54, v11, s[26:27]
	v_cndmask_b32_e64 v10, v55, v10, s[28:29]
	v_cndmask_b32_e64 v9, v56, v9, s[30:31]
	v_cndmask_b32_e64 v8, v57, v8, s[34:35]
	v_lshlrev_b32_e32 v18, 16, v18
	v_lshlrev_b32_e32 v19, 16, v19
	v_lshlrev_b32_e32 v20, 16, v20
	v_lshlrev_b32_e32 v21, 16, v21
	v_lshlrev_b32_e32 v22, 16, v22
	v_lshlrev_b32_e32 v23, 16, v23
	v_lshlrev_b32_e32 v17, 16, v17
	v_lshlrev_b32_e32 v16, 16, v16
	v_lshlrev_b32_e32 v14, 16, v14
	v_lshlrev_b32_e32 v13, 16, v13
	v_lshlrev_b32_e32 v12, 16, v12
	v_lshlrev_b32_e32 v11, 16, v11
	v_lshlrev_b32_e32 v10, 16, v10
	v_lshlrev_b32_e32 v9, 16, v9
	v_add3_u32 v15, s91, v15, 15
	v_lshl_add_u32 v8, v8, 16, s91
	v_add3_u32 v18, s91, v18, 14
	v_add3_u32 v19, s91, v19, 13
	v_add3_u32 v20, s91, v20, 12
	v_add3_u32 v21, s91, v21, 11
	v_add3_u32 v22, s91, v22, 10
	v_add3_u32 v23, s91, v23, 9
	v_add3_u32 v17, s91, v17, 8
	v_add3_u32 v16, s91, v16, 7
	v_add3_u32 v14, s91, v14, 6
	v_add3_u32 v13, s91, v13, 5
	v_add3_u32 v12, s91, v12, 4
	v_add3_u32 v11, s91, v11, 3
	v_add3_u32 v10, s91, v10, 2
	v_add3_u32 v9, s91, v9, 1
	v_max_u32_e32 v42, v15, v18
	v_min_u32_e32 v15, v15, v18
	v_max_u32_e32 v18, v19, v20
	v_min_u32_e32 v19, v19, v20
	v_max_u32_e32 v20, v21, v22
	v_min_u32_e32 v21, v21, v22
	v_max_u32_e32 v22, v23, v17
	v_min_u32_e32 v17, v23, v17
	v_max_u32_e32 v23, v16, v14
	v_min_u32_e32 v14, v16, v14
	v_max_u32_e32 v16, v13, v12
	v_min_u32_e32 v12, v13, v12
	v_max_u32_e32 v13, v11, v10
	v_min_u32_e32 v10, v11, v10
	v_max_u32_e32 v11, v9, v8
	v_min_u32_e32 v8, v9, v8
	v_max_u32_e32 v9, v42, v18
	v_min_u32_e32 v18, v42, v18
	v_max_u32_e32 v42, v15, v19
	v_min_u32_e32 v15, v15, v19
	v_max_u32_e32 v19, v20, v22
	v_min_u32_e32 v20, v20, v22
	v_max_u32_e32 v22, v21, v17
	v_min_u32_e32 v17, v21, v17
	v_max_u32_e32 v21, v23, v16
	v_min_u32_e32 v16, v23, v16
	v_max_u32_e32 v23, v14, v12
	v_min_u32_e32 v12, v14, v12
	v_max_u32_e32 v14, v13, v11
	v_min_u32_e32 v11, v13, v11
	v_max_u32_e32 v13, v10, v8
	v_min_u32_e32 v8, v10, v8
	v_max_u32_e32 v10, v42, v18
	v_min_u32_e32 v18, v42, v18
	v_max_u32_e32 v42, v22, v20
	v_min_u32_e32 v20, v22, v20
	v_max_u32_e32 v22, v23, v16
	v_min_u32_e32 v16, v23, v16
	v_max_u32_e32 v23, v13, v11
	v_min_u32_e32 v11, v13, v11
	v_max_u32_e32 v13, v9, v19
	v_min_u32_e32 v9, v9, v19
	v_max_u32_e32 v19, v15, v17
	v_min_u32_e32 v15, v15, v17
	v_max_u32_e32 v17, v21, v14
	v_min_u32_e32 v14, v21, v14
	v_max_u32_e32 v21, v12, v8
	v_min_u32_e32 v8, v12, v8
	v_max_u32_e32 v12, v10, v42
	v_min_u32_e32 v10, v10, v42
	v_max_u32_e32 v42, v18, v20
	v_min_u32_e32 v18, v18, v20
	v_max_u32_e32 v20, v22, v23
	v_min_u32_e32 v22, v22, v23
	v_max_u32_e32 v23, v16, v11
	v_min_u32_e32 v11, v16, v11
	v_min_u32_e32 v16, v13, v17
	v_max_u32_e32 v43, v15, v8
	v_min_u32_e32 v8, v15, v8
	v_max3_u32 v13, v37, v13, v17
	v_max_u32_e32 v15, v42, v9
	v_min_u32_e32 v9, v42, v9
; DI void phase10(const Params& P, char* smem) {
;     ...
;     topk_half(ST + ((long)(h * 2 + 0) * 128) * NTOK + t, R1);
;     topk_half(ST + ((long)(h * 2 + 1) * 128) * NTOK + t, R2);
	v_max_u32_e32 v17, v19, v10
	v_min_u32_e32 v10, v19, v10
	v_max_u32_e32 v19, v23, v14
	v_min_u32_e32 v14, v23, v14
	v_max_u32_e32 v23, v21, v22
	v_min_u32_e32 v21, v21, v22
	v_max_u32_e32 v22, v12, v15
	v_min_u32_e32 v12, v12, v15
	v_max_u32_e32 v15, v17, v9
	v_min_u32_e32 v9, v17, v9
	v_max_u32_e32 v17, v10, v18
	v_min_u32_e32 v10, v10, v18
	v_max_u32_e32 v18, v20, v19
	v_min_u32_e32 v19, v20, v19
	v_max_u32_e32 v20, v23, v14
	v_min_u32_e32 v14, v23, v14
	v_max_u32_e32 v23, v21, v11
	v_min_u32_e32 v11, v21, v11
	v_max_u32_e32 v21, v22, v18
	v_min_u32_e32 v18, v22, v18
	v_max_u32_e32 v22, v12, v19
	v_min_u32_e32 v12, v12, v19
	v_max_u32_e32 v19, v15, v20
	v_min_u32_e32 v15, v15, v20
	v_max_u32_e32 v20, v9, v14
	v_min_u32_e32 v9, v9, v14
	v_max_u32_e32 v14, v17, v23
	v_min_u32_e32 v17, v17, v23
	v_max_u32_e32 v23, v10, v11
	v_min_u32_e32 v10, v10, v11
	v_max_u32_e32 v11, v20, v16
	v_min_u32_e32 v16, v20, v16
	v_max_u32_e32 v20, v14, v18
	v_min_u32_e32 v14, v14, v18
	v_max_u32_e32 v18, v23, v12
	v_min_u32_e32 v12, v23, v12
	v_max_u32_e32 v23, v43, v15
	v_min_u32_e32 v15, v43, v15
	v_max_u32_e32 v8, v35, v8
	v_max_u32_e32 v35, v22, v11
	v_min_u32_e32 v11, v22, v11
	v_max_u32_e32 v22, v19, v20
	v_min_u32_e32 v19, v19, v20
	v_max_u32_e32 v20, v18, v16
	v_min_u32_e32 v16, v18, v16
	v_max_u32_e32 v18, v23, v14
	v_min_u32_e32 v14, v23, v14
	v_max_u32_e32 v23, v12, v9
	v_min_u32_e32 v9, v12, v9
	v_max_u32_e32 v12, v15, v17
	v_min_u32_e32 v15, v15, v17
	v_min_u32_e32 v17, v21, v35
	v_min_u32_e32 v37, v22, v11
	v_min_u32_e32 v42, v19, v20
	v_min_u32_e32 v43, v18, v16
	v_min_u32_e32 v44, v14, v23
	v_min_u32_e32 v45, v12, v9
	v_min_u32_e32 v46, v15, v10
	v_max3_u32 v10, v40, v15, v10
	v_max3_u32 v9, v39, v12, v9
	v_max3_u32 v12, v38, v14, v23
	v_max3_u32 v14, v33, v18, v16
	v_max3_u32 v15, v31, v19, v20
	v_max3_u32 v3, v3, v22, v11
	v_max3_u32 v11, v34, v21, v35
	v_max_u32_e32 v16, v24, v46
	v_max_u32_e32 v18, v41, v45
	v_max_u32_e32 v19, v25, v44
	v_max_u32_e32 v20, v36, v43
	v_max_u32_e32 v21, v32, v42
	v_max_u32_e32 v22, v30, v37
	v_max_u32_e32 v1, v1, v17
	v_max_u32_e32 v17, v8, v14
	v_min_u32_e32 v8, v8, v14
	v_max_u32_e32 v14, v10, v15
	v_min_u32_e32 v10, v10, v15
	v_max_u32_e32 v15, v9, v3
	v_min_u32_e32 v3, v9, v3
	v_max_u32_e32 v9, v12, v11
	v_min_u32_e32 v11, v12, v11
	v_max_u32_e32 v12, v16, v21
	v_min_u32_e32 v16, v16, v21
	v_max_u32_e32 v21, v18, v22
	v_min_u32_e32 v18, v18, v22
	v_max_u32_e32 v22, v19, v1
	v_min_u32_e32 v1, v19, v1
	v_max_u32_e32 v19, v20, v13
	v_min_u32_e32 v13, v20, v13
	v_max_u32_e32 v20, v17, v15
	v_min_u32_e32 v15, v17, v15
	v_max_u32_e32 v17, v14, v9
	v_min_u32_e32 v9, v14, v9
	v_max_u32_e32 v14, v8, v3
	v_min_u32_e32 v3, v8, v3
	v_max_u32_e32 v8, v10, v11
	v_min_u32_e32 v10, v10, v11
	v_max_u32_e32 v11, v12, v22
	v_min_u32_e32 v12, v12, v22
	v_max_u32_e32 v22, v21, v19
	v_min_u32_e32 v19, v21, v19
	v_max_u32_e32 v21, v16, v1
	v_min_u32_e32 v1, v16, v1
	v_max_u32_e32 v16, v18, v13
	v_min_u32_e32 v13, v18, v13
	s_add_i32 s91, s91, -16
	v_max_u32_e32 v18, v20, v17
	v_min_u32_e32 v17, v20, v17
	v_max_u32_e32 v20, v15, v9
	v_min_u32_e32 v9, v15, v9
	v_max_u32_e32 v15, v14, v8
	v_min_u32_e32 v8, v14, v8
	v_max_u32_e32 v14, v3, v10
	v_min_u32_e32 v10, v3, v10
	v_max_u32_e32 v3, v11, v22
	v_min_u32_e32 v11, v11, v22
	v_max_u32_e32 v22, v12, v19
	v_min_u32_e32 v12, v12, v19
	v_max_u32_e32 v19, v21, v16
	v_min_u32_e32 v16, v21, v16
	v_max_u32_e32 v21, v1, v13
	v_min_u32_e32 v13, v1, v13
	s_cmp_lg_u32 s91, -16
	v_max_u32_e32 v35, v18, v3
	v_min_u32_e32 v24, v18, v3
	v_max_u32_e32 v40, v17, v11
	v_min_u32_e32 v41, v17, v11
	v_max_u32_e32 v39, v20, v22
	v_min_u32_e32 v25, v20, v22
	v_max_u32_e32 v38, v9, v12
	v_min_u32_e32 v36, v9, v12
	v_max_u32_e32 v33, v15, v19
	v_min_u32_e32 v32, v15, v19
	v_max_u32_e32 v31, v8, v16
	v_min_u32_e32 v30, v8, v16
	v_max_u32_e32 v3, v14, v21
	v_min_u32_e32 v1, v14, v21
	v_max_u32_e32 v34, v10, v13
	v_min_u32_e32 v37, v10, v13
	s_cbranch_scc1 .LBB0_1184
	v_lshl_add_u64 v[4:5], s[46:47], 0, v[4:5]
	v_mov_b32_e32 v55, 0
	s_movk_i32 s91, 0x70
	v_mov_b32_e32 v49, 0
	v_mov_b32_e32 v54, 0
	v_mov_b32_e32 v46, 0
	v_mov_b32_e32 v52, 0
	v_mov_b32_e32 v45, 0
	v_mov_b32_e32 v53, 0
	v_mov_b32_e32 v44, 0
	v_mov_b32_e32 v50, 0
	v_mov_b32_e32 v43, 0
	v_mov_b32_e32 v51, 0
	v_mov_b32_e32 v42, 0
	v_mov_b32_e32 v47, 0
	v_mov_b32_e32 v23, 0
	v_mov_b32_e32 v48, 0
	v_mov_b32_e32 v56, 0
; DI void topk_half(const _Float16* __restrict__ sp, unsigned (&R)[16]) {
;     ...
;   for (int gi = 0; gi < 8; ++gi) {
;     unsigned Gk[16];
; #pragma unroll
;     for (int e = 0; e < 16; ++e) {
;       const int n = gi * 16 + e;
;       const unsigned bits = __builtin_bit_cast(unsigned short, sp[(long)n * NTOK]);
;       const unsigned o = (bits & 0x8000u) ? (~bits & 0xffffu) : (bits | 0x8000u);
;       Gk[e] = (o << 16) | (unsigned)(127 - n);
;     }
;     SORT16(Gk)
;     MERGE16(R, Gk)
.LBB0_1186:
	s_waitcnt vmcnt(6)
	ds_write_b128 v100, v[90:93]
	ds_write_b128 v100, v[94:97] offset:1024
	s_waitcnt lgkmcnt(0)
	global_load_dwordx4 v[90:93], v86, s[40:41]
	v_add_u32_e32 v87, 0x80000, v86
	global_load_dwordx4 v[94:97], v87, s[40:41]
	v_add_u32_e32 v86, 0x100000, v86
	ds_read_u16 v22, v101
	ds_read_u16 v61, v101 offset:128
	ds_read_u16 v60, v101 offset:256
	ds_read_u16 v59, v101 offset:384
	ds_read_u16 v58, v101 offset:512
	ds_read_u16 v57, v101 offset:640
	ds_read_u16 v15, v101 offset:768
	ds_read_u16 v14, v101 offset:896
	ds_read_u16 v12, v101 offset:1024
	ds_read_u16 v11, v101 offset:1152
	ds_read_u16 v10, v101 offset:1280
	ds_read_u16 v9, v101 offset:1408
	ds_read_u16 v8, v101 offset:1536
	ds_read_u16 v7, v101 offset:1664
	ds_read_u16 v6, v101 offset:1792
	ds_read_u16 v13, v101 offset:1920
	s_waitcnt lgkmcnt(0)
	v_and_b32_e32 v16, 0xffff, v22
	v_bitop3_b32 v17, v16, s57, v16 bitop3:0xc
	v_or_b32_e32 v16, 0x8000, v16
	v_cmp_gt_i16_e32 vcc, 0, v22
	v_and_b32_e32 v18, 0xffff, v61
	v_and_b32_e32 v19, 0xffff, v60
	v_and_b32_e32 v20, 0xffff, v59
	v_and_b32_e32 v21, 0xffff, v58
	v_and_b32_e32 v62, 0xffff, v57
	v_and_b32_e32 v63, 0xffff, v15
	v_and_b32_e32 v64, 0xffff, v14
	v_and_b32_e32 v65, 0xffff, v12
	v_and_b32_e32 v66, 0xffff, v11
	v_and_b32_e32 v67, 0xffff, v10
	v_and_b32_e32 v68, 0xffff, v9
	v_and_b32_e32 v69, 0xffff, v8
	v_and_b32_e32 v70, 0xffff, v7
	v_and_b32_e32 v71, 0xffff, v6
	v_and_b32_e32 v72, 0xffff, v13
	v_cndmask_b32_e32 v16, v16, v17, vcc
	v_bitop3_b32 v17, v18, s57, v18 bitop3:0xc
	v_or_b32_e32 v18, 0x8000, v18
	v_cmp_gt_i16_e32 vcc, 0, v61
	v_bitop3_b32 v22, v19, s57, v19 bitop3:0xc
	v_or_b32_e32 v19, 0x8000, v19
	v_cmp_gt_i16_e64 s[0:1], 0, v60
	v_bitop3_b32 v60, v20, s57, v20 bitop3:0xc
	v_or_b32_e32 v20, 0x8000, v20
	v_cmp_gt_i16_e64 s[6:7], 0, v59
	v_bitop3_b32 v59, v21, s57, v21 bitop3:0xc
	v_or_b32_e32 v21, 0x8000, v21
	v_cmp_gt_i16_e64 s[8:9], 0, v58
	v_bitop3_b32 v58, v62, s57, v62 bitop3:0xc
	v_or_b32_e32 v61, 0x8000, v62
	v_cmp_gt_i16_e64 s[10:11], 0, v57
	v_bitop3_b32 v57, v63, s57, v63 bitop3:0xc
	v_or_b32_e32 v62, 0x8000, v63
	v_cmp_gt_i16_e64 s[12:13], 0, v15
	v_bitop3_b32 v15, v64, s57, v64 bitop3:0xc
	v_or_b32_e32 v63, 0x8000, v64
	v_cmp_gt_i16_e64 s[14:15], 0, v14
	v_bitop3_b32 v14, v65, s57, v65 bitop3:0xc
	v_or_b32_e32 v64, 0x8000, v65
	v_cmp_gt_i16_e64 s[16:17], 0, v12
	v_bitop3_b32 v12, v66, s57, v66 bitop3:0xc
	v_or_b32_e32 v65, 0x8000, v66
	v_cmp_gt_i16_e64 s[18:19], 0, v11
	v_bitop3_b32 v11, v67, s57, v67 bitop3:0xc
	v_or_b32_e32 v66, 0x8000, v67
	v_cmp_gt_i16_e64 s[20:21], 0, v10
	v_bitop3_b32 v10, v68, s57, v68 bitop3:0xc
	v_or_b32_e32 v67, 0x8000, v68
	v_cmp_gt_i16_e64 s[24:25], 0, v9
	v_bitop3_b32 v9, v69, s57, v69 bitop3:0xc
	v_or_b32_e32 v68, 0x8000, v69
	v_cmp_gt_i16_e64 s[26:27], 0, v8
	v_bitop3_b32 v8, v70, s57, v70 bitop3:0xc
	v_or_b32_e32 v69, 0x8000, v70
	v_cmp_gt_i16_e64 s[28:29], 0, v7
	v_bitop3_b32 v7, v71, s57, v71 bitop3:0xc
	v_or_b32_e32 v70, 0x8000, v71
	v_cmp_gt_i16_e64 s[30:31], 0, v6
	v_bitop3_b32 v6, v72, s57, v72 bitop3:0xc
	v_or_b32_e32 v71, 0x8000, v72
	v_cmp_gt_i16_e64 s[34:35], 0, v13
	v_lshlrev_b32_e32 v13, 16, v16
	v_cndmask_b32_e32 v16, v18, v17, vcc
	v_cndmask_b32_e64 v17, v19, v22, s[0:1]
	v_cndmask_b32_e64 v18, v20, v60, s[6:7]
	v_cndmask_b32_e64 v19, v21, v59, s[8:9]
	v_cndmask_b32_e64 v20, v61, v58, s[10:11]
	v_cndmask_b32_e64 v21, v62, v57, s[12:13]
	v_cndmask_b32_e64 v15, v63, v15, s[14:15]
	v_cndmask_b32_e64 v14, v64, v14, s[16:17]
	v_cndmask_b32_e64 v12, v65, v12, s[18:19]
	v_cndmask_b32_e64 v11, v66, v11, s[20:21]
	v_cndmask_b32_e64 v10, v67, v10, s[24:25]
	v_cndmask_b32_e64 v9, v68, v9, s[26:27]
	v_cndmask_b32_e64 v8, v69, v8, s[28:29]
	v_cndmask_b32_e64 v7, v70, v7, s[30:31]
	v_cndmask_b32_e64 v6, v71, v6, s[34:35]
	v_lshlrev_b32_e32 v16, 16, v16
	v_lshlrev_b32_e32 v17, 16, v17
	v_lshlrev_b32_e32 v18, 16, v18
	v_lshlrev_b32_e32 v19, 16, v19
	v_lshlrev_b32_e32 v20, 16, v20
	v_lshlrev_b32_e32 v21, 16, v21
	v_lshlrev_b32_e32 v15, 16, v15
	v_lshlrev_b32_e32 v14, 16, v14
	v_lshlrev_b32_e32 v12, 16, v12
	v_lshlrev_b32_e32 v11, 16, v11
	v_lshlrev_b32_e32 v10, 16, v10
	v_lshlrev_b32_e32 v9, 16, v9
	v_lshlrev_b32_e32 v8, 16, v8
	v_lshlrev_b32_e32 v7, 16, v7
	v_add3_u32 v13, s91, v13, 15
	v_lshl_add_u32 v6, v6, 16, s91
	v_add3_u32 v16, s91, v16, 14
	v_add3_u32 v17, s91, v17, 13
	v_add3_u32 v18, s91, v18, 12
	v_add3_u32 v19, s91, v19, 11
	v_add3_u32 v20, s91, v20, 10
	v_add3_u32 v21, s91, v21, 9
	v_add3_u32 v15, s91, v15, 8
	v_add3_u32 v14, s91, v14, 7
	v_add3_u32 v12, s91, v12, 6
	v_add3_u32 v11, s91, v11, 5
	v_add3_u32 v10, s91, v10, 4
	v_add3_u32 v9, s91, v9, 3
	v_add3_u32 v8, s91, v8, 2
	v_add3_u32 v7, s91, v7, 1
	v_max_u32_e32 v22, v13, v16
	v_min_u32_e32 v13, v13, v16
	v_max_u32_e32 v16, v17, v18
	v_min_u32_e32 v17, v17, v18
	v_max_u32_e32 v18, v19, v20
	v_min_u32_e32 v19, v19, v20
	v_max_u32_e32 v20, v21, v15
	v_min_u32_e32 v15, v21, v15
	v_max_u32_e32 v21, v14, v12
	v_min_u32_e32 v12, v14, v12
	v_max_u32_e32 v14, v11, v10
	v_min_u32_e32 v10, v11, v10
	v_max_u32_e32 v11, v9, v8
	v_min_u32_e32 v8, v9, v8
	v_max_u32_e32 v9, v7, v6
	v_min_u32_e32 v6, v7, v6
	v_max_u32_e32 v7, v22, v16
	v_min_u32_e32 v16, v22, v16
	v_max_u32_e32 v22, v13, v17
	v_min_u32_e32 v13, v13, v17
	v_max_u32_e32 v17, v18, v20
	v_min_u32_e32 v18, v18, v20
	v_max_u32_e32 v20, v19, v15
	v_min_u32_e32 v15, v19, v15
	v_max_u32_e32 v19, v21, v14
	v_min_u32_e32 v14, v21, v14
	v_max_u32_e32 v21, v12, v10
	v_min_u32_e32 v10, v12, v10
	v_max_u32_e32 v12, v11, v9
	v_min_u32_e32 v9, v11, v9
	v_max_u32_e32 v11, v8, v6
	v_min_u32_e32 v6, v8, v6
	v_max_u32_e32 v8, v22, v16
; DI void topk_half(const _Float16* __restrict__ sp, unsigned (&R)[16]) {
;     ...
;   for (int gi = 0; gi < 8; ++gi) {
;     unsigned Gk[16];
; #pragma unroll
;     for (int e = 0; e < 16; ++e) {
;       const int n = gi * 16 + e;
;       const unsigned bits = __builtin_bit_cast(unsigned short, sp[(long)n * NTOK]);
	v_min_u32_e32 v16, v22, v16
	v_max_u32_e32 v22, v20, v18
	v_min_u32_e32 v18, v20, v18
	v_max_u32_e32 v20, v21, v14
	v_min_u32_e32 v14, v21, v14
	v_max_u32_e32 v21, v11, v9
	v_min_u32_e32 v9, v11, v9
	v_max_u32_e32 v11, v7, v17
	v_min_u32_e32 v7, v7, v17
	v_max_u32_e32 v17, v13, v15
	v_min_u32_e32 v13, v13, v15
	v_max_u32_e32 v15, v19, v12
	v_min_u32_e32 v12, v19, v12
	v_max_u32_e32 v19, v10, v6
	v_min_u32_e32 v6, v10, v6
	v_max_u32_e32 v10, v8, v22
	v_min_u32_e32 v8, v8, v22
	v_max_u32_e32 v22, v16, v18
	v_min_u32_e32 v16, v16, v18
	v_max_u32_e32 v18, v20, v21
	v_min_u32_e32 v20, v20, v21
	v_max_u32_e32 v21, v14, v9
	v_min_u32_e32 v9, v14, v9
	v_min_u32_e32 v14, v11, v15
	v_max_u32_e32 v57, v13, v6
	v_min_u32_e32 v6, v13, v6
	v_max3_u32 v11, v56, v11, v15
	v_max_u32_e32 v13, v22, v7
	v_min_u32_e32 v7, v22, v7
	v_max_u32_e32 v15, v17, v8
	v_min_u32_e32 v8, v17, v8
	v_max_u32_e32 v17, v21, v12
	v_min_u32_e32 v12, v21, v12
	v_max_u32_e32 v21, v19, v20
	v_min_u32_e32 v19, v19, v20
	v_max_u32_e32 v20, v10, v13
	v_min_u32_e32 v10, v10, v13
	v_max_u32_e32 v13, v15, v7
	v_min_u32_e32 v7, v15, v7
	v_max_u32_e32 v15, v8, v16
	v_min_u32_e32 v8, v8, v16
	v_max_u32_e32 v16, v18, v17
	v_min_u32_e32 v17, v18, v17
	v_max_u32_e32 v18, v21, v12
	v_min_u32_e32 v12, v21, v12
	v_max_u32_e32 v21, v19, v9
	v_min_u32_e32 v9, v19, v9
	v_max_u32_e32 v19, v20, v16
	v_min_u32_e32 v16, v20, v16
	v_max_u32_e32 v20, v10, v17
	v_min_u32_e32 v10, v10, v17
	v_max_u32_e32 v17, v13, v18
	v_min_u32_e32 v13, v13, v18
	v_max_u32_e32 v18, v7, v12
	v_min_u32_e32 v7, v7, v12
	v_max_u32_e32 v12, v15, v21
	v_min_u32_e32 v15, v15, v21
	v_max_u32_e32 v21, v8, v9
	v_min_u32_e32 v8, v8, v9
	v_max_u32_e32 v9, v18, v14
	v_min_u32_e32 v14, v18, v14
	v_max_u32_e32 v18, v12, v16
	v_min_u32_e32 v12, v12, v16
	v_max_u32_e32 v16, v21, v10
	v_min_u32_e32 v10, v21, v10
	v_max_u32_e32 v21, v57, v13
	v_min_u32_e32 v13, v57, v13
	v_max_u32_e32 v22, v20, v9
	v_min_u32_e32 v9, v20, v9
	v_max_u32_e32 v20, v17, v18
	v_min_u32_e32 v17, v17, v18
	v_max_u32_e32 v18, v16, v14
	v_min_u32_e32 v14, v16, v14
	v_max_u32_e32 v16, v21, v12
	v_min_u32_e32 v12, v21, v12
	v_max_u32_e32 v21, v10, v7
	v_min_u32_e32 v7, v10, v7
	v_max_u32_e32 v10, v13, v15
	v_min_u32_e32 v13, v13, v15
	v_max_u32_e32 v6, v55, v6
	v_min_u32_e32 v15, v19, v22
	v_min_u32_e32 v55, v20, v9
	v_min_u32_e32 v56, v17, v18
	v_min_u32_e32 v57, v16, v14
	v_min_u32_e32 v58, v12, v21
	v_min_u32_e32 v59, v10, v7
	v_min_u32_e32 v60, v13, v8
	v_max3_u32 v8, v54, v13, v8
	v_max3_u32 v7, v52, v10, v7
	v_max3_u32 v10, v53, v12, v21
	v_max3_u32 v12, v50, v16, v14
	v_max3_u32 v13, v51, v17, v18
	v_max3_u32 v9, v47, v20, v9
	v_max3_u32 v14, v48, v19, v22
	v_max_u32_e32 v16, v49, v60
	v_max_u32_e32 v17, v46, v59
	v_max_u32_e32 v18, v45, v58
	v_max_u32_e32 v19, v44, v57
	v_max_u32_e32 v20, v43, v56
	v_max_u32_e32 v21, v42, v55
	v_max_u32_e32 v15, v23, v15
	v_max_u32_e32 v22, v6, v12
	v_min_u32_e32 v6, v6, v12
	v_max_u32_e32 v12, v8, v13
	v_min_u32_e32 v8, v8, v13
	v_max_u32_e32 v13, v7, v9
	v_min_u32_e32 v7, v7, v9
	v_max_u32_e32 v9, v10, v14
	v_min_u32_e32 v10, v10, v14
	v_max_u32_e32 v14, v16, v20
	v_min_u32_e32 v16, v16, v20
	v_max_u32_e32 v20, v17, v21
	v_min_u32_e32 v17, v17, v21
	v_max_u32_e32 v21, v18, v15
	v_min_u32_e32 v15, v18, v15
	v_max_u32_e32 v18, v19, v11
	v_min_u32_e32 v11, v19, v11
	v_max_u32_e32 v19, v22, v13
	v_min_u32_e32 v13, v22, v13
	v_max_u32_e32 v22, v12, v9
	v_min_u32_e32 v9, v12, v9
	v_max_u32_e32 v12, v6, v7
	v_min_u32_e32 v6, v6, v7
	v_max_u32_e32 v7, v8, v10
	v_min_u32_e32 v8, v8, v10
	v_max_u32_e32 v10, v14, v21
	v_min_u32_e32 v14, v14, v21
	v_max_u32_e32 v21, v20, v18
	v_min_u32_e32 v18, v20, v18
	v_max_u32_e32 v20, v16, v15
	v_min_u32_e32 v15, v16, v15
	v_max_u32_e32 v16, v17, v11
	v_min_u32_e32 v11, v17, v11
	s_add_i32 s91, s91, -16
	v_max_u32_e32 v17, v19, v22
	v_min_u32_e32 v19, v19, v22
	v_max_u32_e32 v22, v13, v9
	v_min_u32_e32 v9, v13, v9
	v_max_u32_e32 v13, v12, v7
	v_min_u32_e32 v7, v12, v7
	v_max_u32_e32 v12, v6, v8
	v_min_u32_e32 v6, v6, v8
	v_max_u32_e32 v8, v10, v21
	v_min_u32_e32 v10, v10, v21
	v_max_u32_e32 v21, v14, v18
	v_min_u32_e32 v14, v14, v18
	v_max_u32_e32 v18, v20, v16
	v_min_u32_e32 v16, v20, v16
	v_max_u32_e32 v20, v15, v11
	v_min_u32_e32 v11, v15, v11
	v_max_u32_e32 v55, v17, v8
	v_min_u32_e32 v49, v17, v8
	v_max_u32_e32 v54, v19, v10
	v_min_u32_e32 v46, v19, v10
	v_max_u32_e32 v52, v22, v21
	v_min_u32_e32 v45, v22, v21
	v_max_u32_e32 v53, v9, v14
	v_min_u32_e32 v44, v9, v14
	v_max_u32_e32 v50, v13, v18
	v_min_u32_e32 v43, v13, v18
	v_max_u32_e32 v51, v7, v16
	v_min_u32_e32 v42, v7, v16
	v_max_u32_e32 v47, v12, v20
	v_min_u32_e32 v23, v12, v20
	v_max_u32_e32 v48, v6, v11
	v_min_u32_e32 v56, v6, v11
	s_waitcnt vmcnt(6)
	ds_write_b128 v100, v[144:147]
	ds_write_b128 v100, v[148:151] offset:1024
	s_waitcnt lgkmcnt(0)
	global_load_dwordx4 v[144:147], v86, s[40:41]
	v_add_u32_e32 v87, 0x80000, v86
	global_load_dwordx4 v[148:151], v87, s[40:41]
	v_add_u32_e32 v86, 0x100000, v86
	ds_read_u16 v22, v101
	ds_read_u16 v61, v101 offset:128
	ds_read_u16 v60, v101 offset:256
	ds_read_u16 v59, v101 offset:384
	ds_read_u16 v58, v101 offset:512
	ds_read_u16 v57, v101 offset:640
	ds_read_u16 v15, v101 offset:768
	ds_read_u16 v14, v101 offset:896
	ds_read_u16 v12, v101 offset:1024
	ds_read_u16 v11, v101 offset:1152
	ds_read_u16 v10, v101 offset:1280
	ds_read_u16 v9, v101 offset:1408
	ds_read_u16 v8, v101 offset:1536
	ds_read_u16 v7, v101 offset:1664
	ds_read_u16 v6, v101 offset:1792
	ds_read_u16 v13, v101 offset:1920
	s_waitcnt lgkmcnt(0)
; DI void topk_half(const _Float16* __restrict__ sp, unsigned (&R)[16]) {
;     ...
;     for (int e = 0; e < 16; ++e) {
;       const int n = gi * 16 + e;
;       const unsigned bits = __builtin_bit_cast(unsigned short, sp[(long)n * NTOK]);
;       const unsigned o = (bits & 0x8000u) ? (~bits & 0xffffu) : (bits | 0x8000u);
;       Gk[e] = (o << 16) | (unsigned)(127 - n);
;     }
;     SORT16(Gk)
;     MERGE16(R, Gk)
	v_and_b32_e32 v16, 0xffff, v22
	v_bitop3_b32 v17, v16, s57, v16 bitop3:0xc
	v_or_b32_e32 v16, 0x8000, v16
	v_cmp_gt_i16_e32 vcc, 0, v22
	v_and_b32_e32 v18, 0xffff, v61
	v_and_b32_e32 v19, 0xffff, v60
	v_and_b32_e32 v20, 0xffff, v59
	v_and_b32_e32 v21, 0xffff, v58
	v_and_b32_e32 v62, 0xffff, v57
	v_and_b32_e32 v63, 0xffff, v15
	v_and_b32_e32 v64, 0xffff, v14
	v_and_b32_e32 v65, 0xffff, v12
	v_and_b32_e32 v66, 0xffff, v11
	v_and_b32_e32 v67, 0xffff, v10
	v_and_b32_e32 v68, 0xffff, v9
	v_and_b32_e32 v69, 0xffff, v8
	v_and_b32_e32 v70, 0xffff, v7
	v_and_b32_e32 v71, 0xffff, v6
	v_and_b32_e32 v72, 0xffff, v13
	v_cndmask_b32_e32 v16, v16, v17, vcc
	v_bitop3_b32 v17, v18, s57, v18 bitop3:0xc
	v_or_b32_e32 v18, 0x8000, v18
	v_cmp_gt_i16_e32 vcc, 0, v61
	v_bitop3_b32 v22, v19, s57, v19 bitop3:0xc
	v_or_b32_e32 v19, 0x8000, v19
	v_cmp_gt_i16_e64 s[0:1], 0, v60
	v_bitop3_b32 v60, v20, s57, v20 bitop3:0xc
	v_or_b32_e32 v20, 0x8000, v20
	v_cmp_gt_i16_e64 s[6:7], 0, v59
	v_bitop3_b32 v59, v21, s57, v21 bitop3:0xc
	v_or_b32_e32 v21, 0x8000, v21
	v_cmp_gt_i16_e64 s[8:9], 0, v58
	v_bitop3_b32 v58, v62, s57, v62 bitop3:0xc
	v_or_b32_e32 v61, 0x8000, v62
	v_cmp_gt_i16_e64 s[10:11], 0, v57
	v_bitop3_b32 v57, v63, s57, v63 bitop3:0xc
	v_or_b32_e32 v62, 0x8000, v63
	v_cmp_gt_i16_e64 s[12:13], 0, v15
	v_bitop3_b32 v15, v64, s57, v64 bitop3:0xc
	v_or_b32_e32 v63, 0x8000, v64
	v_cmp_gt_i16_e64 s[14:15], 0, v14
	v_bitop3_b32 v14, v65, s57, v65 bitop3:0xc
	v_or_b32_e32 v64, 0x8000, v65
	v_cmp_gt_i16_e64 s[16:17], 0, v12
	v_bitop3_b32 v12, v66, s57, v66 bitop3:0xc
	v_or_b32_e32 v65, 0x8000, v66
	v_cmp_gt_i16_e64 s[18:19], 0, v11
	v_bitop3_b32 v11, v67, s57, v67 bitop3:0xc
	v_or_b32_e32 v66, 0x8000, v67
	v_cmp_gt_i16_e64 s[20:21], 0, v10
	v_bitop3_b32 v10, v68, s57, v68 bitop3:0xc
	v_or_b32_e32 v67, 0x8000, v68
	v_cmp_gt_i16_e64 s[24:25], 0, v9
	v_bitop3_b32 v9, v69, s57, v69 bitop3:0xc
	v_or_b32_e32 v68, 0x8000, v69
	v_cmp_gt_i16_e64 s[26:27], 0, v8
	v_bitop3_b32 v8, v70, s57, v70 bitop3:0xc
	v_or_b32_e32 v69, 0x8000, v70
	v_cmp_gt_i16_e64 s[28:29], 0, v7
	v_bitop3_b32 v7, v71, s57, v71 bitop3:0xc
	v_or_b32_e32 v70, 0x8000, v71
	v_cmp_gt_i16_e64 s[30:31], 0, v6
	v_bitop3_b32 v6, v72, s57, v72 bitop3:0xc
	v_or_b32_e32 v71, 0x8000, v72
	v_cmp_gt_i16_e64 s[34:35], 0, v13
	v_lshlrev_b32_e32 v13, 16, v16
	v_cndmask_b32_e32 v16, v18, v17, vcc
	v_cndmask_b32_e64 v17, v19, v22, s[0:1]
	v_cndmask_b32_e64 v18, v20, v60, s[6:7]
	v_cndmask_b32_e64 v19, v21, v59, s[8:9]
	v_cndmask_b32_e64 v20, v61, v58, s[10:11]
	v_cndmask_b32_e64 v21, v62, v57, s[12:13]
	v_cndmask_b32_e64 v15, v63, v15, s[14:15]
	v_cndmask_b32_e64 v14, v64, v14, s[16:17]
	v_cndmask_b32_e64 v12, v65, v12, s[18:19]
	v_cndmask_b32_e64 v11, v66, v11, s[20:21]
	v_cndmask_b32_e64 v10, v67, v10, s[24:25]
	v_cndmask_b32_e64 v9, v68, v9, s[26:27]
	v_cndmask_b32_e64 v8, v69, v8, s[28:29]
	v_cndmask_b32_e64 v7, v70, v7, s[30:31]
	v_cndmask_b32_e64 v6, v71, v6, s[34:35]
	v_lshlrev_b32_e32 v16, 16, v16
	v_lshlrev_b32_e32 v17, 16, v17
	v_lshlrev_b32_e32 v18, 16, v18
	v_lshlrev_b32_e32 v19, 16, v19
	v_lshlrev_b32_e32 v20, 16, v20
	v_lshlrev_b32_e32 v21, 16, v21
	v_lshlrev_b32_e32 v15, 16, v15
	v_lshlrev_b32_e32 v14, 16, v14
	v_lshlrev_b32_e32 v12, 16, v12
	v_lshlrev_b32_e32 v11, 16, v11
	v_lshlrev_b32_e32 v10, 16, v10
	v_lshlrev_b32_e32 v9, 16, v9
	v_lshlrev_b32_e32 v8, 16, v8
	v_lshlrev_b32_e32 v7, 16, v7
	v_add3_u32 v13, s91, v13, 15
	v_lshl_add_u32 v6, v6, 16, s91
	v_add3_u32 v16, s91, v16, 14
	v_add3_u32 v17, s91, v17, 13
	v_add3_u32 v18, s91, v18, 12
	v_add3_u32 v19, s91, v19, 11
	v_add3_u32 v20, s91, v20, 10
	v_add3_u32 v21, s91, v21, 9
	v_add3_u32 v15, s91, v15, 8
	v_add3_u32 v14, s91, v14, 7
	v_add3_u32 v12, s91, v12, 6
	v_add3_u32 v11, s91, v11, 5
	v_add3_u32 v10, s91, v10, 4
	v_add3_u32 v9, s91, v9, 3
	v_add3_u32 v8, s91, v8, 2
	v_add3_u32 v7, s91, v7, 1
	v_max_u32_e32 v22, v13, v16
	v_min_u32_e32 v13, v13, v16
	v_max_u32_e32 v16, v17, v18
	v_min_u32_e32 v17, v17, v18
	v_max_u32_e32 v18, v19, v20
	v_min_u32_e32 v19, v19, v20
	v_max_u32_e32 v20, v21, v15
	v_min_u32_e32 v15, v21, v15
	v_max_u32_e32 v21, v14, v12
	v_min_u32_e32 v12, v14, v12
	v_max_u32_e32 v14, v11, v10
	v_min_u32_e32 v10, v11, v10
	v_max_u32_e32 v11, v9, v8
	v_min_u32_e32 v8, v9, v8
	v_max_u32_e32 v9, v7, v6
	v_min_u32_e32 v6, v7, v6
	v_max_u32_e32 v7, v22, v16
	v_min_u32_e32 v16, v22, v16
	v_max_u32_e32 v22, v13, v17
	v_min_u32_e32 v13, v13, v17
	v_max_u32_e32 v17, v18, v20
	v_min_u32_e32 v18, v18, v20
	v_max_u32_e32 v20, v19, v15
	v_min_u32_e32 v15, v19, v15
	v_max_u32_e32 v19, v21, v14
	v_min_u32_e32 v14, v21, v14
	v_max_u32_e32 v21, v12, v10
	v_min_u32_e32 v10, v12, v10
	v_max_u32_e32 v12, v11, v9
	v_min_u32_e32 v9, v11, v9
	v_max_u32_e32 v11, v8, v6
	v_min_u32_e32 v6, v8, v6
	v_max_u32_e32 v8, v22, v16
	v_min_u32_e32 v16, v22, v16
	v_max_u32_e32 v22, v20, v18
	v_min_u32_e32 v18, v20, v18
	v_max_u32_e32 v20, v21, v14
	v_min_u32_e32 v14, v21, v14
	v_max_u32_e32 v21, v11, v9
	v_min_u32_e32 v9, v11, v9
	v_max_u32_e32 v11, v7, v17
	v_min_u32_e32 v7, v7, v17
	v_max_u32_e32 v17, v13, v15
	v_min_u32_e32 v13, v13, v15
	v_max_u32_e32 v15, v19, v12
	v_min_u32_e32 v12, v19, v12
	v_max_u32_e32 v19, v10, v6
	v_min_u32_e32 v6, v10, v6
	v_max_u32_e32 v10, v8, v22
	v_min_u32_e32 v8, v8, v22
	v_max_u32_e32 v22, v16, v18
	v_min_u32_e32 v16, v16, v18
	v_max_u32_e32 v18, v20, v21
	v_min_u32_e32 v20, v20, v21
	v_max_u32_e32 v21, v14, v9
	v_min_u32_e32 v9, v14, v9
	v_min_u32_e32 v14, v11, v15
	v_max_u32_e32 v57, v13, v6
	v_min_u32_e32 v6, v13, v6
	v_max3_u32 v11, v56, v11, v15
	v_max_u32_e32 v13, v22, v7
	v_min_u32_e32 v7, v22, v7
	v_max_u32_e32 v15, v17, v8
; DI void topk_half(const _Float16* __restrict__ sp, unsigned (&R)[16]) {
;     ...
;   for (int gi = 0; gi < 8; ++gi) {
;     unsigned Gk[16];
; #pragma unroll
;     for (int e = 0; e < 16; ++e) {
;       const int n = gi * 16 + e;
;       const unsigned bits = __builtin_bit_cast(unsigned short, sp[(long)n * NTOK]);
	v_min_u32_e32 v8, v17, v8
	v_max_u32_e32 v17, v21, v12
	v_min_u32_e32 v12, v21, v12
	v_max_u32_e32 v21, v19, v20
	v_min_u32_e32 v19, v19, v20
	v_max_u32_e32 v20, v10, v13
	v_min_u32_e32 v10, v10, v13
	v_max_u32_e32 v13, v15, v7
	v_min_u32_e32 v7, v15, v7
	v_max_u32_e32 v15, v8, v16
	v_min_u32_e32 v8, v8, v16
	v_max_u32_e32 v16, v18, v17
	v_min_u32_e32 v17, v18, v17
	v_max_u32_e32 v18, v21, v12
	v_min_u32_e32 v12, v21, v12
	v_max_u32_e32 v21, v19, v9
	v_min_u32_e32 v9, v19, v9
	v_max_u32_e32 v19, v20, v16
	v_min_u32_e32 v16, v20, v16
	v_max_u32_e32 v20, v10, v17
	v_min_u32_e32 v10, v10, v17
	v_max_u32_e32 v17, v13, v18
	v_min_u32_e32 v13, v13, v18
	v_max_u32_e32 v18, v7, v12
	v_min_u32_e32 v7, v7, v12
	v_max_u32_e32 v12, v15, v21
	v_min_u32_e32 v15, v15, v21
	v_max_u32_e32 v21, v8, v9
	v_min_u32_e32 v8, v8, v9
	v_max_u32_e32 v9, v18, v14
	v_min_u32_e32 v14, v18, v14
	v_max_u32_e32 v18, v12, v16
	v_min_u32_e32 v12, v12, v16
	v_max_u32_e32 v16, v21, v10
	v_min_u32_e32 v10, v21, v10
	v_max_u32_e32 v21, v57, v13
	v_min_u32_e32 v13, v57, v13
	v_max_u32_e32 v22, v20, v9
	v_min_u32_e32 v9, v20, v9
	v_max_u32_e32 v20, v17, v18
	v_min_u32_e32 v17, v17, v18
	v_max_u32_e32 v18, v16, v14
	v_min_u32_e32 v14, v16, v14
	v_max_u32_e32 v16, v21, v12
	v_min_u32_e32 v12, v21, v12
	v_max_u32_e32 v21, v10, v7
	v_min_u32_e32 v7, v10, v7
	v_max_u32_e32 v10, v13, v15
	v_min_u32_e32 v13, v13, v15
	v_max_u32_e32 v6, v55, v6
	v_min_u32_e32 v15, v19, v22
	v_min_u32_e32 v55, v20, v9
	v_min_u32_e32 v56, v17, v18
	v_min_u32_e32 v57, v16, v14
	v_min_u32_e32 v58, v12, v21
	v_min_u32_e32 v59, v10, v7
	v_min_u32_e32 v60, v13, v8
	v_max3_u32 v8, v54, v13, v8
	v_max3_u32 v7, v52, v10, v7
	v_max3_u32 v10, v53, v12, v21
	v_max3_u32 v12, v50, v16, v14
	v_max3_u32 v13, v51, v17, v18
	v_max3_u32 v9, v47, v20, v9
	v_max3_u32 v14, v48, v19, v22
	v_max_u32_e32 v16, v49, v60
	v_max_u32_e32 v17, v46, v59
	v_max_u32_e32 v18, v45, v58
	v_max_u32_e32 v19, v44, v57
	v_max_u32_e32 v20, v43, v56
	v_max_u32_e32 v21, v42, v55
	v_max_u32_e32 v15, v23, v15
	v_max_u32_e32 v22, v6, v12
	v_min_u32_e32 v6, v6, v12
	v_max_u32_e32 v12, v8, v13
	v_min_u32_e32 v8, v8, v13
	v_max_u32_e32 v13, v7, v9
	v_min_u32_e32 v7, v7, v9
	v_max_u32_e32 v9, v10, v14
	v_min_u32_e32 v10, v10, v14
	v_max_u32_e32 v14, v16, v20
	v_min_u32_e32 v16, v16, v20
	v_max_u32_e32 v20, v17, v21
	v_min_u32_e32 v17, v17, v21
	v_max_u32_e32 v21, v18, v15
	v_min_u32_e32 v15, v18, v15
	v_max_u32_e32 v18, v19, v11
	v_min_u32_e32 v11, v19, v11
	v_max_u32_e32 v19, v22, v13
	v_min_u32_e32 v13, v22, v13
	v_max_u32_e32 v22, v12, v9
	v_min_u32_e32 v9, v12, v9
	v_max_u32_e32 v12, v6, v7
	v_min_u32_e32 v6, v6, v7
	v_max_u32_e32 v7, v8, v10
	v_min_u32_e32 v8, v8, v10
	v_max_u32_e32 v10, v14, v21
	v_min_u32_e32 v14, v14, v21
	v_max_u32_e32 v21, v20, v18
	v_min_u32_e32 v18, v20, v18
	v_max_u32_e32 v20, v16, v15
	v_min_u32_e32 v15, v16, v15
	v_max_u32_e32 v16, v17, v11
	v_min_u32_e32 v11, v17, v11
	s_add_i32 s91, s91, -16
	v_max_u32_e32 v17, v19, v22
	v_min_u32_e32 v19, v19, v22
	v_max_u32_e32 v22, v13, v9
	v_min_u32_e32 v9, v13, v9
	v_max_u32_e32 v13, v12, v7
	v_min_u32_e32 v7, v12, v7
	v_max_u32_e32 v12, v6, v8
	v_min_u32_e32 v6, v6, v8
	v_max_u32_e32 v8, v10, v21
	v_min_u32_e32 v10, v10, v21
	v_max_u32_e32 v21, v14, v18
	v_min_u32_e32 v14, v14, v18
	v_max_u32_e32 v18, v20, v16
	v_min_u32_e32 v16, v20, v16
	v_max_u32_e32 v20, v15, v11
	v_min_u32_e32 v11, v15, v11
	v_max_u32_e32 v55, v17, v8
	v_min_u32_e32 v49, v17, v8
	v_max_u32_e32 v54, v19, v10
	v_min_u32_e32 v46, v19, v10
	v_max_u32_e32 v52, v22, v21
	v_min_u32_e32 v45, v22, v21
	v_max_u32_e32 v53, v9, v14
	v_min_u32_e32 v44, v9, v14
	v_max_u32_e32 v50, v13, v18
	v_min_u32_e32 v43, v13, v18
	v_max_u32_e32 v51, v7, v16
	v_min_u32_e32 v42, v7, v16
	v_max_u32_e32 v47, v12, v20
	v_min_u32_e32 v23, v12, v20
	v_max_u32_e32 v48, v6, v11
	v_min_u32_e32 v56, v6, v11
	s_waitcnt vmcnt(6)
	ds_write_b128 v100, v[152:155]
	ds_write_b128 v100, v[156:159] offset:1024
	s_waitcnt lgkmcnt(0)
	global_load_dwordx4 v[152:155], v86, s[40:41]
	v_add_u32_e32 v87, 0x80000, v86
	global_load_dwordx4 v[156:159], v87, s[40:41]
	v_add_u32_e32 v86, 0x100000, v86
	ds_read_u16 v22, v101
	ds_read_u16 v61, v101 offset:128
	ds_read_u16 v60, v101 offset:256
	ds_read_u16 v59, v101 offset:384
	ds_read_u16 v58, v101 offset:512
	ds_read_u16 v57, v101 offset:640
	ds_read_u16 v15, v101 offset:768
	ds_read_u16 v14, v101 offset:896
	ds_read_u16 v12, v101 offset:1024
	ds_read_u16 v11, v101 offset:1152
	ds_read_u16 v10, v101 offset:1280
	ds_read_u16 v9, v101 offset:1408
	ds_read_u16 v8, v101 offset:1536
	ds_read_u16 v7, v101 offset:1664
	ds_read_u16 v6, v101 offset:1792
	ds_read_u16 v13, v101 offset:1920
	s_waitcnt lgkmcnt(0)
; DI void topk_half(const _Float16* __restrict__ sp, unsigned (&R)[16]) {
; #pragma unroll
;   for (int e = 0; e < 16; ++e) R[e] = 0u;
; #pragma unroll 1
;   for (int gi = 0; gi < 8; ++gi) {
;     unsigned Gk[16];
; #pragma unroll
;     for (int e = 0; e < 16; ++e) {
;       const int n = gi * 16 + e;
;       const unsigned bits = __builtin_bit_cast(unsigned short, sp[(long)n * NTOK]);
;       const unsigned o = (bits & 0x8000u) ? (~bits & 0xffffu) : (bits | 0x8000u);
;       Gk[e] = (o << 16) | (unsigned)(127 - n);
;     }
;     SORT16(Gk)
;     MERGE16(R, Gk)
	v_and_b32_e32 v16, 0xffff, v22
	v_bitop3_b32 v17, v16, s57, v16 bitop3:0xc
	v_or_b32_e32 v16, 0x8000, v16
	v_cmp_gt_i16_e32 vcc, 0, v22
	v_and_b32_e32 v18, 0xffff, v61
	v_and_b32_e32 v19, 0xffff, v60
	v_and_b32_e32 v20, 0xffff, v59
	v_and_b32_e32 v21, 0xffff, v58
	v_and_b32_e32 v62, 0xffff, v57
	v_and_b32_e32 v63, 0xffff, v15
	v_and_b32_e32 v64, 0xffff, v14
	v_and_b32_e32 v65, 0xffff, v12
	v_and_b32_e32 v66, 0xffff, v11
	v_and_b32_e32 v67, 0xffff, v10
	v_and_b32_e32 v68, 0xffff, v9
	v_and_b32_e32 v69, 0xffff, v8
	v_and_b32_e32 v70, 0xffff, v7
	v_and_b32_e32 v71, 0xffff, v6
	v_and_b32_e32 v72, 0xffff, v13
	v_cndmask_b32_e32 v16, v16, v17, vcc
	v_bitop3_b32 v17, v18, s57, v18 bitop3:0xc
	v_or_b32_e32 v18, 0x8000, v18
	v_cmp_gt_i16_e32 vcc, 0, v61
	v_bitop3_b32 v22, v19, s57, v19 bitop3:0xc
	v_or_b32_e32 v19, 0x8000, v19
	v_cmp_gt_i16_e64 s[0:1], 0, v60
	v_bitop3_b32 v60, v20, s57, v20 bitop3:0xc
	v_or_b32_e32 v20, 0x8000, v20
	v_cmp_gt_i16_e64 s[6:7], 0, v59
	v_bitop3_b32 v59, v21, s57, v21 bitop3:0xc
	v_or_b32_e32 v21, 0x8000, v21
	v_cmp_gt_i16_e64 s[8:9], 0, v58
	v_bitop3_b32 v58, v62, s57, v62 bitop3:0xc
	v_or_b32_e32 v61, 0x8000, v62
	v_cmp_gt_i16_e64 s[10:11], 0, v57
	v_bitop3_b32 v57, v63, s57, v63 bitop3:0xc
	v_or_b32_e32 v62, 0x8000, v63
	v_cmp_gt_i16_e64 s[12:13], 0, v15
	v_bitop3_b32 v15, v64, s57, v64 bitop3:0xc
	v_or_b32_e32 v63, 0x8000, v64
	v_cmp_gt_i16_e64 s[14:15], 0, v14
	v_bitop3_b32 v14, v65, s57, v65 bitop3:0xc
	v_or_b32_e32 v64, 0x8000, v65
	v_cmp_gt_i16_e64 s[16:17], 0, v12
	v_bitop3_b32 v12, v66, s57, v66 bitop3:0xc
	v_or_b32_e32 v65, 0x8000, v66
	v_cmp_gt_i16_e64 s[18:19], 0, v11
	v_bitop3_b32 v11, v67, s57, v67 bitop3:0xc
	v_or_b32_e32 v66, 0x8000, v67
	v_cmp_gt_i16_e64 s[20:21], 0, v10
	v_bitop3_b32 v10, v68, s57, v68 bitop3:0xc
	v_or_b32_e32 v67, 0x8000, v68
	v_cmp_gt_i16_e64 s[24:25], 0, v9
	v_bitop3_b32 v9, v69, s57, v69 bitop3:0xc
	v_or_b32_e32 v68, 0x8000, v69
	v_cmp_gt_i16_e64 s[26:27], 0, v8
	v_bitop3_b32 v8, v70, s57, v70 bitop3:0xc
	v_or_b32_e32 v69, 0x8000, v70
	v_cmp_gt_i16_e64 s[28:29], 0, v7
	v_bitop3_b32 v7, v71, s57, v71 bitop3:0xc
	v_or_b32_e32 v70, 0x8000, v71
	v_cmp_gt_i16_e64 s[30:31], 0, v6
	v_bitop3_b32 v6, v72, s57, v72 bitop3:0xc
	v_or_b32_e32 v71, 0x8000, v72
	v_cmp_gt_i16_e64 s[34:35], 0, v13
	v_lshlrev_b32_e32 v13, 16, v16
	v_cndmask_b32_e32 v16, v18, v17, vcc
	v_cndmask_b32_e64 v17, v19, v22, s[0:1]
	v_cndmask_b32_e64 v18, v20, v60, s[6:7]
	v_cndmask_b32_e64 v19, v21, v59, s[8:9]
	v_cndmask_b32_e64 v20, v61, v58, s[10:11]
	v_cndmask_b32_e64 v21, v62, v57, s[12:13]
	v_cndmask_b32_e64 v15, v63, v15, s[14:15]
	v_cndmask_b32_e64 v14, v64, v14, s[16:17]
	v_cndmask_b32_e64 v12, v65, v12, s[18:19]
	v_cndmask_b32_e64 v11, v66, v11, s[20:21]
	v_cndmask_b32_e64 v10, v67, v10, s[24:25]
	v_cndmask_b32_e64 v9, v68, v9, s[26:27]
	v_cndmask_b32_e64 v8, v69, v8, s[28:29]
	v_cndmask_b32_e64 v7, v70, v7, s[30:31]
	v_cndmask_b32_e64 v6, v71, v6, s[34:35]
	v_lshlrev_b32_e32 v16, 16, v16
	v_lshlrev_b32_e32 v17, 16, v17
	v_lshlrev_b32_e32 v18, 16, v18
	v_lshlrev_b32_e32 v19, 16, v19
	v_lshlrev_b32_e32 v20, 16, v20
	v_lshlrev_b32_e32 v21, 16, v21
	v_lshlrev_b32_e32 v15, 16, v15
	v_lshlrev_b32_e32 v14, 16, v14
	v_lshlrev_b32_e32 v12, 16, v12
	v_lshlrev_b32_e32 v11, 16, v11
	v_lshlrev_b32_e32 v10, 16, v10
	v_lshlrev_b32_e32 v9, 16, v9
	v_lshlrev_b32_e32 v8, 16, v8
	v_lshlrev_b32_e32 v7, 16, v7
	v_add3_u32 v13, s91, v13, 15
	v_lshl_add_u32 v6, v6, 16, s91
	v_add3_u32 v16, s91, v16, 14
	v_add3_u32 v17, s91, v17, 13
	v_add3_u32 v18, s91, v18, 12
	v_add3_u32 v19, s91, v19, 11
	v_add3_u32 v20, s91, v20, 10
	v_add3_u32 v21, s91, v21, 9
	v_add3_u32 v15, s91, v15, 8
	v_add3_u32 v14, s91, v14, 7
	v_add3_u32 v12, s91, v12, 6
	v_add3_u32 v11, s91, v11, 5
	v_add3_u32 v10, s91, v10, 4
	v_add3_u32 v9, s91, v9, 3
	v_add3_u32 v8, s91, v8, 2
	v_add3_u32 v7, s91, v7, 1
	v_max_u32_e32 v22, v13, v16
	v_min_u32_e32 v13, v13, v16
	v_max_u32_e32 v16, v17, v18
	v_min_u32_e32 v17, v17, v18
	v_max_u32_e32 v18, v19, v20
	v_min_u32_e32 v19, v19, v20
	v_max_u32_e32 v20, v21, v15
	v_min_u32_e32 v15, v21, v15
	v_max_u32_e32 v21, v14, v12
	v_min_u32_e32 v12, v14, v12
	v_max_u32_e32 v14, v11, v10
	v_min_u32_e32 v10, v11, v10
	v_max_u32_e32 v11, v9, v8
	v_min_u32_e32 v8, v9, v8
	v_max_u32_e32 v9, v7, v6
	v_min_u32_e32 v6, v7, v6
	v_max_u32_e32 v7, v22, v16
	v_min_u32_e32 v16, v22, v16
	v_max_u32_e32 v22, v13, v17
	v_min_u32_e32 v13, v13, v17
	v_max_u32_e32 v17, v18, v20
	v_min_u32_e32 v18, v18, v20
	v_max_u32_e32 v20, v19, v15
	v_min_u32_e32 v15, v19, v15
	v_max_u32_e32 v19, v21, v14
	v_min_u32_e32 v14, v21, v14
	v_max_u32_e32 v21, v12, v10
	v_min_u32_e32 v10, v12, v10
	v_max_u32_e32 v12, v11, v9
	v_min_u32_e32 v9, v11, v9
	v_max_u32_e32 v11, v8, v6
	v_min_u32_e32 v6, v8, v6
	v_max_u32_e32 v8, v22, v16
	v_min_u32_e32 v16, v22, v16
	v_max_u32_e32 v22, v20, v18
	v_min_u32_e32 v18, v20, v18
	v_max_u32_e32 v20, v21, v14
	v_min_u32_e32 v14, v21, v14
	v_max_u32_e32 v21, v11, v9
	v_min_u32_e32 v9, v11, v9
	v_max_u32_e32 v11, v7, v17
	v_min_u32_e32 v7, v7, v17
	v_max_u32_e32 v17, v13, v15
	v_min_u32_e32 v13, v13, v15
	v_max_u32_e32 v15, v19, v12
	v_min_u32_e32 v12, v19, v12
	v_max_u32_e32 v19, v10, v6
	v_min_u32_e32 v6, v10, v6
	v_max_u32_e32 v10, v8, v22
	v_min_u32_e32 v8, v8, v22
	v_max_u32_e32 v22, v16, v18
	v_min_u32_e32 v16, v16, v18
	v_max_u32_e32 v18, v20, v21
	v_min_u32_e32 v20, v20, v21
	v_max_u32_e32 v21, v14, v9
	v_min_u32_e32 v9, v14, v9
	v_min_u32_e32 v14, v11, v15
	v_max_u32_e32 v57, v13, v6
	v_min_u32_e32 v6, v13, v6
	v_max3_u32 v11, v56, v11, v15
	v_max_u32_e32 v13, v22, v7
	v_min_u32_e32 v7, v22, v7
	v_max_u32_e32 v15, v17, v8
; DI void topk_half(const _Float16* __restrict__ sp, unsigned (&R)[16]) {
; #pragma unroll
;   for (int e = 0; e < 16; ++e) R[e] = 0u;
; #pragma unroll 1
;   for (int gi = 0; gi < 8; ++gi) {
;     unsigned Gk[16];
; #pragma unroll
;     for (int e = 0; e < 16; ++e) {
;       const int n = gi * 16 + e;
;       const unsigned bits = __builtin_bit_cast(unsigned short, sp[(long)n * NTOK]);
;       const unsigned o = (bits & 0x8000u) ? (~bits & 0xffffu) : (bits | 0x8000u);
;       Gk[e] = (o << 16) | (unsigned)(127 - n);
;     }
;     SORT16(Gk)
;     MERGE16(R, Gk)
	v_min_u32_e32 v8, v17, v8
	v_max_u32_e32 v17, v21, v12
	v_min_u32_e32 v12, v21, v12
	v_max_u32_e32 v21, v19, v20
	v_min_u32_e32 v19, v19, v20
	v_max_u32_e32 v20, v10, v13
	v_min_u32_e32 v10, v10, v13
	v_max_u32_e32 v13, v15, v7
	v_min_u32_e32 v7, v15, v7
	v_max_u32_e32 v15, v8, v16
	v_min_u32_e32 v8, v8, v16
	v_max_u32_e32 v16, v18, v17
	v_min_u32_e32 v17, v18, v17
	v_max_u32_e32 v18, v21, v12
	v_min_u32_e32 v12, v21, v12
	v_max_u32_e32 v21, v19, v9
	v_min_u32_e32 v9, v19, v9
	v_max_u32_e32 v19, v20, v16
	v_min_u32_e32 v16, v20, v16
	v_max_u32_e32 v20, v10, v17
	v_min_u32_e32 v10, v10, v17
	v_max_u32_e32 v17, v13, v18
	v_min_u32_e32 v13, v13, v18
	v_max_u32_e32 v18, v7, v12
	v_min_u32_e32 v7, v7, v12
	v_max_u32_e32 v12, v15, v21
	v_min_u32_e32 v15, v15, v21
	v_max_u32_e32 v21, v8, v9
	v_min_u32_e32 v8, v8, v9
	v_max_u32_e32 v9, v18, v14
	v_min_u32_e32 v14, v18, v14
	v_max_u32_e32 v18, v12, v16
	v_min_u32_e32 v12, v12, v16
	v_max_u32_e32 v16, v21, v10
	v_min_u32_e32 v10, v21, v10
	v_max_u32_e32 v21, v57, v13
	v_min_u32_e32 v13, v57, v13
	v_max_u32_e32 v22, v20, v9
	v_min_u32_e32 v9, v20, v9
	v_max_u32_e32 v20, v17, v18
	v_min_u32_e32 v17, v17, v18
	v_max_u32_e32 v18, v16, v14
	v_min_u32_e32 v14, v16, v14
	v_max_u32_e32 v16, v21, v12
	v_min_u32_e32 v12, v21, v12
	v_max_u32_e32 v21, v10, v7
	v_min_u32_e32 v7, v10, v7
	v_max_u32_e32 v10, v13, v15
	v_min_u32_e32 v13, v13, v15
	v_max_u32_e32 v6, v55, v6
	v_min_u32_e32 v15, v19, v22
	v_min_u32_e32 v55, v20, v9
	v_min_u32_e32 v56, v17, v18
	v_min_u32_e32 v57, v16, v14
	v_min_u32_e32 v58, v12, v21
	v_min_u32_e32 v59, v10, v7
	v_min_u32_e32 v60, v13, v8
	v_max3_u32 v8, v54, v13, v8
	v_max3_u32 v7, v52, v10, v7
	v_max3_u32 v10, v53, v12, v21
	v_max3_u32 v12, v50, v16, v14
	v_max3_u32 v13, v51, v17, v18
	v_max3_u32 v9, v47, v20, v9
	v_max3_u32 v14, v48, v19, v22
	v_max_u32_e32 v16, v49, v60
	v_max_u32_e32 v17, v46, v59
	v_max_u32_e32 v18, v45, v58
	v_max_u32_e32 v19, v44, v57
	v_max_u32_e32 v20, v43, v56
	v_max_u32_e32 v21, v42, v55
	v_max_u32_e32 v15, v23, v15
	v_max_u32_e32 v22, v6, v12
	v_min_u32_e32 v6, v6, v12
	v_max_u32_e32 v12, v8, v13
	v_min_u32_e32 v8, v8, v13
	v_max_u32_e32 v13, v7, v9
	v_min_u32_e32 v7, v7, v9
	v_max_u32_e32 v9, v10, v14
	v_min_u32_e32 v10, v10, v14
	v_max_u32_e32 v14, v16, v20
	v_min_u32_e32 v16, v16, v20
	v_max_u32_e32 v20, v17, v21
	v_min_u32_e32 v17, v17, v21
	v_max_u32_e32 v21, v18, v15
	v_min_u32_e32 v15, v18, v15
	v_max_u32_e32 v18, v19, v11
	v_min_u32_e32 v11, v19, v11
	v_max_u32_e32 v19, v22, v13
	v_min_u32_e32 v13, v22, v13
	v_max_u32_e32 v22, v12, v9
	v_min_u32_e32 v9, v12, v9
	v_max_u32_e32 v12, v6, v7
	v_min_u32_e32 v6, v6, v7
	v_max_u32_e32 v7, v8, v10
	v_min_u32_e32 v8, v8, v10
	v_max_u32_e32 v10, v14, v21
	v_min_u32_e32 v14, v14, v21
	v_max_u32_e32 v21, v20, v18
	v_min_u32_e32 v18, v20, v18
	v_max_u32_e32 v20, v16, v15
	v_min_u32_e32 v15, v16, v15
	v_max_u32_e32 v16, v17, v11
	v_min_u32_e32 v11, v17, v11
	s_add_i32 s91, s91, -16
	v_max_u32_e32 v17, v19, v22
	v_min_u32_e32 v19, v19, v22
	v_max_u32_e32 v22, v13, v9
	v_min_u32_e32 v9, v13, v9
	v_max_u32_e32 v13, v12, v7
	v_min_u32_e32 v7, v12, v7
	v_max_u32_e32 v12, v6, v8
	v_min_u32_e32 v6, v6, v8
	v_max_u32_e32 v8, v10, v21
	v_min_u32_e32 v10, v10, v21
	v_max_u32_e32 v21, v14, v18
	v_min_u32_e32 v14, v14, v18
	v_max_u32_e32 v18, v20, v16
	v_min_u32_e32 v16, v20, v16
	v_max_u32_e32 v20, v15, v11
	v_min_u32_e32 v11, v15, v11
	v_max_u32_e32 v55, v17, v8
	v_min_u32_e32 v49, v17, v8
	v_max_u32_e32 v54, v19, v10
	v_min_u32_e32 v46, v19, v10
	v_max_u32_e32 v52, v22, v21
	v_min_u32_e32 v45, v22, v21
	v_max_u32_e32 v53, v9, v14
	v_min_u32_e32 v44, v9, v14
	v_max_u32_e32 v50, v13, v18
	v_min_u32_e32 v43, v13, v18
	v_max_u32_e32 v51, v7, v16
	v_min_u32_e32 v42, v7, v16
	v_max_u32_e32 v47, v12, v20
	v_min_u32_e32 v23, v12, v20
	v_max_u32_e32 v48, v6, v11
	v_min_u32_e32 v56, v6, v11
	s_waitcnt vmcnt(6)
	ds_write_b128 v100, v[160:163]
	ds_write_b128 v100, v[164:167] offset:1024
	s_waitcnt lgkmcnt(0)
	global_load_dwordx4 v[160:163], v86, s[40:41]
	v_add_u32_e32 v87, 0x80000, v86
	global_load_dwordx4 v[164:167], v87, s[40:41]
	v_add_u32_e32 v86, 0x100000, v86
	ds_read_u16 v22, v101
	ds_read_u16 v61, v101 offset:128
	ds_read_u16 v60, v101 offset:256
	ds_read_u16 v59, v101 offset:384
	ds_read_u16 v58, v101 offset:512
	ds_read_u16 v57, v101 offset:640
	ds_read_u16 v15, v101 offset:768
	ds_read_u16 v14, v101 offset:896
	ds_read_u16 v12, v101 offset:1024
	ds_read_u16 v11, v101 offset:1152
	ds_read_u16 v10, v101 offset:1280
	ds_read_u16 v9, v101 offset:1408
	ds_read_u16 v8, v101 offset:1536
	ds_read_u16 v7, v101 offset:1664
	ds_read_u16 v6, v101 offset:1792
	ds_read_u16 v13, v101 offset:1920
	s_waitcnt lgkmcnt(0)
; DI void topk_half(const _Float16* __restrict__ sp, unsigned (&R)[16]) {
; #pragma unroll
;   for (int e = 0; e < 16; ++e) R[e] = 0u;
; #pragma unroll 1
;   for (int gi = 0; gi < 8; ++gi) {
;     unsigned Gk[16];
; #pragma unroll
;     for (int e = 0; e < 16; ++e) {
;       const int n = gi * 16 + e;
;       const unsigned bits = __builtin_bit_cast(unsigned short, sp[(long)n * NTOK]);
;       const unsigned o = (bits & 0x8000u) ? (~bits & 0xffffu) : (bits | 0x8000u);
;       Gk[e] = (o << 16) | (unsigned)(127 - n);
;     }
;     SORT16(Gk)
;     MERGE16(R, Gk)
	v_and_b32_e32 v16, 0xffff, v22
	v_bitop3_b32 v17, v16, s57, v16 bitop3:0xc
	v_or_b32_e32 v16, 0x8000, v16
	v_cmp_gt_i16_e32 vcc, 0, v22
	v_and_b32_e32 v18, 0xffff, v61
	v_and_b32_e32 v19, 0xffff, v60
	v_and_b32_e32 v20, 0xffff, v59
	v_and_b32_e32 v21, 0xffff, v58
	v_and_b32_e32 v62, 0xffff, v57
	v_and_b32_e32 v63, 0xffff, v15
	v_and_b32_e32 v64, 0xffff, v14
	v_and_b32_e32 v65, 0xffff, v12
	v_and_b32_e32 v66, 0xffff, v11
	v_and_b32_e32 v67, 0xffff, v10
	v_and_b32_e32 v68, 0xffff, v9
	v_and_b32_e32 v69, 0xffff, v8
	v_and_b32_e32 v70, 0xffff, v7
	v_and_b32_e32 v71, 0xffff, v6
	v_and_b32_e32 v72, 0xffff, v13
	v_cndmask_b32_e32 v16, v16, v17, vcc
	v_bitop3_b32 v17, v18, s57, v18 bitop3:0xc
	v_or_b32_e32 v18, 0x8000, v18
	v_cmp_gt_i16_e32 vcc, 0, v61
	v_bitop3_b32 v22, v19, s57, v19 bitop3:0xc
	v_or_b32_e32 v19, 0x8000, v19
	v_cmp_gt_i16_e64 s[0:1], 0, v60
	v_bitop3_b32 v60, v20, s57, v20 bitop3:0xc
	v_or_b32_e32 v20, 0x8000, v20
	v_cmp_gt_i16_e64 s[6:7], 0, v59
	v_bitop3_b32 v59, v21, s57, v21 bitop3:0xc
	v_or_b32_e32 v21, 0x8000, v21
	v_cmp_gt_i16_e64 s[8:9], 0, v58
	v_bitop3_b32 v58, v62, s57, v62 bitop3:0xc
	v_or_b32_e32 v61, 0x8000, v62
	v_cmp_gt_i16_e64 s[10:11], 0, v57
	v_bitop3_b32 v57, v63, s57, v63 bitop3:0xc
	v_or_b32_e32 v62, 0x8000, v63
	v_cmp_gt_i16_e64 s[12:13], 0, v15
	v_bitop3_b32 v15, v64, s57, v64 bitop3:0xc
	v_or_b32_e32 v63, 0x8000, v64
	v_cmp_gt_i16_e64 s[14:15], 0, v14
	v_bitop3_b32 v14, v65, s57, v65 bitop3:0xc
	v_or_b32_e32 v64, 0x8000, v65
	v_cmp_gt_i16_e64 s[16:17], 0, v12
	v_bitop3_b32 v12, v66, s57, v66 bitop3:0xc
	v_or_b32_e32 v65, 0x8000, v66
	v_cmp_gt_i16_e64 s[18:19], 0, v11
	v_bitop3_b32 v11, v67, s57, v67 bitop3:0xc
	v_or_b32_e32 v66, 0x8000, v67
	v_cmp_gt_i16_e64 s[20:21], 0, v10
	v_bitop3_b32 v10, v68, s57, v68 bitop3:0xc
	v_or_b32_e32 v67, 0x8000, v68
	v_cmp_gt_i16_e64 s[24:25], 0, v9
	v_bitop3_b32 v9, v69, s57, v69 bitop3:0xc
	v_or_b32_e32 v68, 0x8000, v69
	v_cmp_gt_i16_e64 s[26:27], 0, v8
	v_bitop3_b32 v8, v70, s57, v70 bitop3:0xc
	v_or_b32_e32 v69, 0x8000, v70
	v_cmp_gt_i16_e64 s[28:29], 0, v7
	v_bitop3_b32 v7, v71, s57, v71 bitop3:0xc
	v_or_b32_e32 v70, 0x8000, v71
	v_cmp_gt_i16_e64 s[30:31], 0, v6
	v_bitop3_b32 v6, v72, s57, v72 bitop3:0xc
	v_or_b32_e32 v71, 0x8000, v72
	v_cmp_gt_i16_e64 s[34:35], 0, v13
	v_lshlrev_b32_e32 v13, 16, v16
	v_cndmask_b32_e32 v16, v18, v17, vcc
	v_cndmask_b32_e64 v17, v19, v22, s[0:1]
	v_cndmask_b32_e64 v18, v20, v60, s[6:7]
	v_cndmask_b32_e64 v19, v21, v59, s[8:9]
	v_cndmask_b32_e64 v20, v61, v58, s[10:11]
	v_cndmask_b32_e64 v21, v62, v57, s[12:13]
	v_cndmask_b32_e64 v15, v63, v15, s[14:15]
	v_cndmask_b32_e64 v14, v64, v14, s[16:17]
	v_cndmask_b32_e64 v12, v65, v12, s[18:19]
	v_cndmask_b32_e64 v11, v66, v11, s[20:21]
	v_cndmask_b32_e64 v10, v67, v10, s[24:25]
	v_cndmask_b32_e64 v9, v68, v9, s[26:27]
	v_cndmask_b32_e64 v8, v69, v8, s[28:29]
	v_cndmask_b32_e64 v7, v70, v7, s[30:31]
	v_cndmask_b32_e64 v6, v71, v6, s[34:35]
	v_lshlrev_b32_e32 v16, 16, v16
	v_lshlrev_b32_e32 v17, 16, v17
	v_lshlrev_b32_e32 v18, 16, v18
	v_lshlrev_b32_e32 v19, 16, v19
	v_lshlrev_b32_e32 v20, 16, v20
	v_lshlrev_b32_e32 v21, 16, v21
	v_lshlrev_b32_e32 v15, 16, v15
	v_lshlrev_b32_e32 v14, 16, v14
	v_lshlrev_b32_e32 v12, 16, v12
	v_lshlrev_b32_e32 v11, 16, v11
	v_lshlrev_b32_e32 v10, 16, v10
	v_lshlrev_b32_e32 v9, 16, v9
	v_lshlrev_b32_e32 v8, 16, v8
	v_lshlrev_b32_e32 v7, 16, v7
	v_add3_u32 v13, s91, v13, 15
	v_lshl_add_u32 v6, v6, 16, s91
	v_add3_u32 v16, s91, v16, 14
	v_add3_u32 v17, s91, v17, 13
	v_add3_u32 v18, s91, v18, 12
	v_add3_u32 v19, s91, v19, 11
	v_add3_u32 v20, s91, v20, 10
	v_add3_u32 v21, s91, v21, 9
	v_add3_u32 v15, s91, v15, 8
	v_add3_u32 v14, s91, v14, 7
	v_add3_u32 v12, s91, v12, 6
	v_add3_u32 v11, s91, v11, 5
	v_add3_u32 v10, s91, v10, 4
	v_add3_u32 v9, s91, v9, 3
	v_add3_u32 v8, s91, v8, 2
	v_add3_u32 v7, s91, v7, 1
	v_max_u32_e32 v22, v13, v16
	v_min_u32_e32 v13, v13, v16
	v_max_u32_e32 v16, v17, v18
	v_min_u32_e32 v17, v17, v18
	v_max_u32_e32 v18, v19, v20
	v_min_u32_e32 v19, v19, v20
	v_max_u32_e32 v20, v21, v15
	v_min_u32_e32 v15, v21, v15
	v_max_u32_e32 v21, v14, v12
	v_min_u32_e32 v12, v14, v12
	v_max_u32_e32 v14, v11, v10
	v_min_u32_e32 v10, v11, v10
	v_max_u32_e32 v11, v9, v8
	v_min_u32_e32 v8, v9, v8
	v_max_u32_e32 v9, v7, v6
	v_min_u32_e32 v6, v7, v6
	v_max_u32_e32 v7, v22, v16
	v_min_u32_e32 v16, v22, v16
	v_max_u32_e32 v22, v13, v17
	v_min_u32_e32 v13, v13, v17
	v_max_u32_e32 v17, v18, v20
	v_min_u32_e32 v18, v18, v20
	v_max_u32_e32 v20, v19, v15
	v_min_u32_e32 v15, v19, v15
	v_max_u32_e32 v19, v21, v14
	v_min_u32_e32 v14, v21, v14
	v_max_u32_e32 v21, v12, v10
	v_min_u32_e32 v10, v12, v10
	v_max_u32_e32 v12, v11, v9
	v_min_u32_e32 v9, v11, v9
	v_max_u32_e32 v11, v8, v6
	v_min_u32_e32 v6, v8, v6
	v_max_u32_e32 v8, v22, v16
	v_min_u32_e32 v16, v22, v16
	v_max_u32_e32 v22, v20, v18
	v_min_u32_e32 v18, v20, v18
	v_max_u32_e32 v20, v21, v14
	v_min_u32_e32 v14, v21, v14
	v_max_u32_e32 v21, v11, v9
	v_min_u32_e32 v9, v11, v9
	v_max_u32_e32 v11, v7, v17
	v_min_u32_e32 v7, v7, v17
	v_max_u32_e32 v17, v13, v15
	v_min_u32_e32 v13, v13, v15
	v_max_u32_e32 v15, v19, v12
	v_min_u32_e32 v12, v19, v12
	v_max_u32_e32 v19, v10, v6
	v_min_u32_e32 v6, v10, v6
	v_max_u32_e32 v10, v8, v22
	v_min_u32_e32 v8, v8, v22
	v_max_u32_e32 v22, v16, v18
	v_min_u32_e32 v16, v16, v18
	v_max_u32_e32 v18, v20, v21
	v_min_u32_e32 v20, v20, v21
	v_max_u32_e32 v21, v14, v9
	v_min_u32_e32 v9, v14, v9
	v_min_u32_e32 v14, v11, v15
	v_max_u32_e32 v57, v13, v6
	v_min_u32_e32 v6, v13, v6
	v_max3_u32 v11, v56, v11, v15
	v_max_u32_e32 v13, v22, v7
	v_min_u32_e32 v7, v22, v7
	v_max_u32_e32 v15, v17, v8
; DI float key_val16(unsigned k) { const unsigned o = k >> 16; const unsigned short b = (unsigned short)((o & 0x8000u) ? (o & 0x7fffu) : (~o & 0xffffu)); return (float)__builtin_bit_cast(_Float16, b); }
; DI void topk_half(const _Float16* __restrict__ sp, unsigned (&R)[16]) {
; #pragma unroll
;   for (int e = 0; e < 16; ++e) R[e] = 0u;
; #pragma unroll 1
;   for (int gi = 0; gi < 8; ++gi) {
;     unsigned Gk[16];
; #pragma unroll
;     for (int e = 0; e < 16; ++e) {
;       const int n = gi * 16 + e;
;       const unsigned bits = __builtin_bit_cast(unsigned short, sp[(long)n * NTOK]);
;       const unsigned o = (bits & 0x8000u) ? (~bits & 0xffffu) : (bits | 0x8000u);
;       Gk[e] = (o << 16) | (unsigned)(127 - n);
;     }
;     SORT16(Gk)
;     MERGE16(R, Gk)
;   }
; }
; DI void phase10(const Params& P, char* smem) {
;     ...
;     float v1[16], v2[16]; unsigned W1[4] = {0u, 0u, 0u, 0u}, W2[4] = {0u, 0u, 0u, 0u};
; #pragma unroll
;     for (int k = 0; k < 16; ++k) {
;       v1[k] = key_val16(R1[k]); v2[k] = key_val16(R2[k]);
;       W1[k >> 2] |= (127u - (R1[k] & 127u)) << ((k & 3) * 8);
;       W2[k >> 2] |= (127u - (R2[k] & 127u)) << ((k & 3) * 8);
;     }
	v_min_u32_e32 v8, v17, v8
	v_max_u32_e32 v17, v21, v12
	v_min_u32_e32 v12, v21, v12
	v_max_u32_e32 v21, v19, v20
	v_min_u32_e32 v19, v19, v20
	v_max_u32_e32 v20, v10, v13
	v_min_u32_e32 v10, v10, v13
	v_max_u32_e32 v13, v15, v7
	v_min_u32_e32 v7, v15, v7
	v_max_u32_e32 v15, v8, v16
	v_min_u32_e32 v8, v8, v16
	v_max_u32_e32 v16, v18, v17
	v_min_u32_e32 v17, v18, v17
	v_max_u32_e32 v18, v21, v12
	v_min_u32_e32 v12, v21, v12
	v_max_u32_e32 v21, v19, v9
	v_min_u32_e32 v9, v19, v9
	v_max_u32_e32 v19, v20, v16
	v_min_u32_e32 v16, v20, v16
	v_max_u32_e32 v20, v10, v17
	v_min_u32_e32 v10, v10, v17
	v_max_u32_e32 v17, v13, v18
	v_min_u32_e32 v13, v13, v18
	v_max_u32_e32 v18, v7, v12
	v_min_u32_e32 v7, v7, v12
	v_max_u32_e32 v12, v15, v21
	v_min_u32_e32 v15, v15, v21
	v_max_u32_e32 v21, v8, v9
	v_min_u32_e32 v8, v8, v9
	v_max_u32_e32 v9, v18, v14
	v_min_u32_e32 v14, v18, v14
	v_max_u32_e32 v18, v12, v16
	v_min_u32_e32 v12, v12, v16
	v_max_u32_e32 v16, v21, v10
	v_min_u32_e32 v10, v21, v10
	v_max_u32_e32 v21, v57, v13
	v_min_u32_e32 v13, v57, v13
	v_max_u32_e32 v22, v20, v9
	v_min_u32_e32 v9, v20, v9
	v_max_u32_e32 v20, v17, v18
	v_min_u32_e32 v17, v17, v18
	v_max_u32_e32 v18, v16, v14
	v_min_u32_e32 v14, v16, v14
	v_max_u32_e32 v16, v21, v12
	v_min_u32_e32 v12, v21, v12
	v_max_u32_e32 v21, v10, v7
	v_min_u32_e32 v7, v10, v7
	v_max_u32_e32 v10, v13, v15
	v_min_u32_e32 v13, v13, v15
	v_max_u32_e32 v6, v55, v6
	v_min_u32_e32 v15, v19, v22
	v_min_u32_e32 v55, v20, v9
	v_min_u32_e32 v56, v17, v18
	v_min_u32_e32 v57, v16, v14
	v_min_u32_e32 v58, v12, v21
	v_min_u32_e32 v59, v10, v7
	v_min_u32_e32 v60, v13, v8
	v_max3_u32 v8, v54, v13, v8
	v_max3_u32 v7, v52, v10, v7
	v_max3_u32 v10, v53, v12, v21
	v_max3_u32 v12, v50, v16, v14
	v_max3_u32 v13, v51, v17, v18
	v_max3_u32 v9, v47, v20, v9
	v_max3_u32 v14, v48, v19, v22
	v_max_u32_e32 v16, v49, v60
	v_max_u32_e32 v17, v46, v59
	v_max_u32_e32 v18, v45, v58
	v_max_u32_e32 v19, v44, v57
	v_max_u32_e32 v20, v43, v56
	v_max_u32_e32 v21, v42, v55
	v_max_u32_e32 v15, v23, v15
	v_max_u32_e32 v22, v6, v12
	v_min_u32_e32 v6, v6, v12
	v_max_u32_e32 v12, v8, v13
	v_min_u32_e32 v8, v8, v13
	v_max_u32_e32 v13, v7, v9
	v_min_u32_e32 v7, v7, v9
	v_max_u32_e32 v9, v10, v14
	v_min_u32_e32 v10, v10, v14
	v_max_u32_e32 v14, v16, v20
	v_min_u32_e32 v16, v16, v20
	v_max_u32_e32 v20, v17, v21
	v_min_u32_e32 v17, v17, v21
	v_max_u32_e32 v21, v18, v15
	v_min_u32_e32 v15, v18, v15
	v_max_u32_e32 v18, v19, v11
	v_min_u32_e32 v11, v19, v11
	v_max_u32_e32 v19, v22, v13
	v_min_u32_e32 v13, v22, v13
	v_max_u32_e32 v22, v12, v9
	v_min_u32_e32 v9, v12, v9
	v_max_u32_e32 v12, v6, v7
	v_min_u32_e32 v6, v6, v7
	v_max_u32_e32 v7, v8, v10
	v_min_u32_e32 v8, v8, v10
	v_max_u32_e32 v10, v14, v21
	v_min_u32_e32 v14, v14, v21
	v_max_u32_e32 v21, v20, v18
	v_min_u32_e32 v18, v20, v18
	v_max_u32_e32 v20, v16, v15
	v_min_u32_e32 v15, v16, v15
	v_max_u32_e32 v16, v17, v11
	v_min_u32_e32 v11, v17, v11
	s_add_i32 s91, s91, -16
	v_max_u32_e32 v17, v19, v22
	v_min_u32_e32 v19, v19, v22
	v_max_u32_e32 v22, v13, v9
	v_min_u32_e32 v9, v13, v9
	v_max_u32_e32 v13, v12, v7
	v_min_u32_e32 v7, v12, v7
	v_max_u32_e32 v12, v6, v8
	v_min_u32_e32 v6, v6, v8
	v_max_u32_e32 v8, v10, v21
	v_min_u32_e32 v10, v10, v21
	v_max_u32_e32 v21, v14, v18
	v_min_u32_e32 v14, v14, v18
	v_max_u32_e32 v18, v20, v16
	v_min_u32_e32 v16, v20, v16
	v_max_u32_e32 v20, v15, v11
	v_min_u32_e32 v11, v15, v11
	s_cmp_lg_u32 s91, -16
	v_max_u32_e32 v55, v17, v8
	v_min_u32_e32 v49, v17, v8
	v_max_u32_e32 v54, v19, v10
	v_min_u32_e32 v46, v19, v10
	v_max_u32_e32 v52, v22, v21
	v_min_u32_e32 v45, v22, v21
	v_max_u32_e32 v53, v9, v14
	v_min_u32_e32 v44, v9, v14
	v_max_u32_e32 v50, v13, v18
	v_min_u32_e32 v43, v13, v18
	v_max_u32_e32 v51, v7, v16
	v_min_u32_e32 v42, v7, v16
	v_max_u32_e32 v47, v12, v20
	v_min_u32_e32 v23, v12, v20
	v_max_u32_e32 v48, v6, v11
	v_min_u32_e32 v56, v6, v11
	s_cbranch_scc1 .LBB0_1186
	v_lshlrev_b32_e32 v5, 8, v24
	v_lshlrev_b32_e32 v6, 16, v40
	v_and_b32_e32 v4, 0x7f, v35
	v_and_b32_e32 v5, 0x7f00, v5
	v_and_b32_e32 v6, 0x7f0000, v6
	v_or3_b32 v4, v5, v4, v6
	v_and_b32_sdwa v5, v46, s57 dst_sel:DWORD dst_unused:UNUSED_PAD src0_sel:WORD_1 src1_sel:DWORD
	v_xor_b32_sdwa v7, v46, v27 dst_sel:DWORD dst_unused:UNUSED_PAD src0_sel:WORD_1 src1_sel:DWORD
	v_cmp_gt_i32_e32 vcc, 0, v46
	v_and_b32_sdwa v6, v41, s57 dst_sel:DWORD dst_unused:UNUSED_PAD src0_sel:WORD_1 src1_sel:DWORD
	v_xor_b32_sdwa v8, v41, v27 dst_sel:DWORD dst_unused:UNUSED_PAD src0_sel:WORD_1 src1_sel:DWORD
	v_cndmask_b32_e32 v5, v7, v5, vcc
	v_cmp_gt_i32_e32 vcc, 0, v41
	v_xor_b32_sdwa v7, v39, v27 dst_sel:DWORD dst_unused:UNUSED_PAD src0_sel:WORD_1 src1_sel:DWORD
	v_xor_b32_sdwa v11, v36, v27 dst_sel:DWORD dst_unused:UNUSED_PAD src0_sel:WORD_1 src1_sel:DWORD
	v_cndmask_b32_e32 v6, v8, v6, vcc
	v_cvt_f32_f16_e32 v8, v5
	v_lshlrev_b32_e32 v5, 24, v41
	v_and_b32_e32 v5, 0x7f000000, v5
	v_cvt_f32_f16_e32 v12, v6
	v_bitop3_b32 v15, v4, s75, v5 bitop3:0x36
	v_and_b32_sdwa v4, v54, s57 dst_sel:DWORD dst_unused:UNUSED_PAD src0_sel:WORD_1 src1_sel:DWORD
	v_xor_b32_sdwa v6, v54, v27 dst_sel:DWORD dst_unused:UNUSED_PAD src0_sel:WORD_1 src1_sel:DWORD
	v_cmp_gt_i32_e32 vcc, 0, v54
	v_and_b32_sdwa v5, v39, s57 dst_sel:DWORD dst_unused:UNUSED_PAD src0_sel:WORD_1 src1_sel:DWORD
	v_xor_b32_sdwa v13, v24, v27 dst_sel:DWORD dst_unused:UNUSED_PAD src0_sel:WORD_1 src1_sel:DWORD
	v_cndmask_b32_e32 v4, v6, v4, vcc
	v_cmp_gt_i32_e32 vcc, 0, v39
	v_cvt_f32_f16_e32 v9, v4
	v_and_b32_sdwa v4, v52, s57 dst_sel:DWORD dst_unused:UNUSED_PAD src0_sel:WORD_1 src1_sel:DWORD
	v_cndmask_b32_e32 v5, v7, v5, vcc
; DI float key_val16(unsigned k) { const unsigned o = k >> 16; const unsigned short b = (unsigned short)((o & 0x8000u) ? (o & 0x7fffu) : (~o & 0xffffu)); return (float)__builtin_bit_cast(_Float16, b); }
; DI unsigned candkey(float s, int pos) { const unsigned b = __float_as_uint(s); const unsigned o = (b >> 31) ? ~b : (b ^ 0x80000000u); return (o & 0xffffff00u) | (unsigned)(255 - pos); }
; DI void phase10(const Params& P, char* smem) {
;     ...
;     float v1[16], v2[16]; unsigned W1[4] = {0u, 0u, 0u, 0u}, W2[4] = {0u, 0u, 0u, 0u};
; #pragma unroll
;     for (int k = 0; k < 16; ++k) {
;       v1[k] = key_val16(R1[k]); v2[k] = key_val16(R2[k]);
;       W1[k >> 2] |= (127u - (R1[k] & 127u)) << ((k & 3) * 8);
;       W2[k >> 2] |= (127u - (R2[k] & 127u)) << ((k & 3) * 8);
;     }
;     unsigned C0[16], C1[16], C2[16], C3[16];
;     C0[0] = candkey(v1[0] + v2[0], 0);
;     C0[1] = candkey(v1[0] + v2[1], 1);
;     C0[2] = candkey(v1[0] + v2[2], 2);
;     C0[3] = candkey(v1[0] + v2[3], 3);
;     C0[4] = candkey(v1[0] + v2[4], 4);
;     C0[5] = candkey(v1[0] + v2[5], 5);
;     C0[6] = candkey(v1[0] + v2[6], 6);
;     C0[7] = candkey(v1[0] + v2[7], 7);
;     C0[8] = candkey(v1[0] + v2[8], 8);
;     C0[9] = candkey(v1[0] + v2[9], 9);
;     C0[10] = candkey(v1[0] + v2[10], 10);
;     C0[11] = candkey(v1[0] + v2[11], 11);
;     C0[12] = candkey(v1[0] + v2[12], 12);
;     C0[13] = candkey(v1[0] + v2[13], 13);
;     C0[14] = candkey(v1[0] + v2[14], 14);
;     C0[15] = candkey(v1[0] + v2[15], 15);
	v_xor_b32_sdwa v6, v52, v27 dst_sel:DWORD dst_unused:UNUSED_PAD src0_sel:WORD_1 src1_sel:DWORD
	v_cmp_gt_i32_e32 vcc, 0, v52
	v_cvt_f32_f16_e32 v10, v5
	v_and_b32_sdwa v5, v40, s57 dst_sel:DWORD dst_unused:UNUSED_PAD src0_sel:WORD_1 src1_sel:DWORD
	v_xor_b32_sdwa v7, v40, v27 dst_sel:DWORD dst_unused:UNUSED_PAD src0_sel:WORD_1 src1_sel:DWORD
	v_cndmask_b32_e32 v4, v6, v4, vcc
	v_cmp_gt_i32_e32 vcc, 0, v40
	v_not_b32_sdwa v6, v25 dst_sel:DWORD dst_unused:UNUSED_PAD src0_sel:WORD_1
	v_cvt_f32_f16_e32 v21, v4
	v_cndmask_b32_e32 v5, v7, v5, vcc
	v_cvt_f32_f16_e32 v22, v5
	v_bfe_u32 v5, v25, 16, 15
	v_cmp_gt_i32_e32 vcc, 0, v25
	v_not_b32_sdwa v7, v38 dst_sel:DWORD dst_unused:UNUSED_PAD src0_sel:WORD_1
	v_and_b32_e32 v4, 0x7f, v39
	v_cndmask_b32_e32 v5, v6, v5, vcc
	v_cvt_f32_f16_e32 v14, v5
	v_bfe_u32 v5, v45, 16, 15
	v_not_b32_sdwa v6, v45 dst_sel:DWORD dst_unused:UNUSED_PAD src0_sel:WORD_1
	v_cmp_gt_i32_e32 vcc, 0, v45
	s_movk_i32 s0, 0xfe
	v_xor_b32_sdwa v57, v50, v27 dst_sel:DWORD dst_unused:UNUSED_PAD src0_sel:WORD_1 src1_sel:DWORD
	v_cndmask_b32_e32 v5, v6, v5, vcc
	v_bfe_u32 v6, v38, 16, 15
	v_cmp_gt_i32_e32 vcc, 0, v38
	v_cvt_f32_f16_e32 v20, v5
	v_lshlrev_b32_e32 v5, 8, v25
	v_cndmask_b32_e32 v6, v7, v6, vcc
	v_cvt_f32_f16_e32 v16, v6
	v_bfe_u32 v6, v53, 16, 15
	v_not_b32_sdwa v7, v53 dst_sel:DWORD dst_unused:UNUSED_PAD src0_sel:WORD_1
	v_cmp_gt_i32_e32 vcc, 0, v53
	v_and_b32_e32 v5, 0x7f00, v5
	v_xor_b32_sdwa v81, v32, v27 dst_sel:DWORD dst_unused:UNUSED_PAD src0_sel:WORD_1 src1_sel:DWORD
	v_cndmask_b32_e32 v6, v7, v6, vcc
	v_cvt_f32_f16_e32 v25, v6
	v_lshlrev_b32_e32 v6, 16, v38
	v_and_b32_e32 v6, 0x7f0000, v6
	v_or3_b32 v4, v5, v4, v6
	v_and_b32_sdwa v5, v49, s57 dst_sel:DWORD dst_unused:UNUSED_PAD src0_sel:WORD_1 src1_sel:DWORD
	v_xor_b32_sdwa v7, v49, v27 dst_sel:DWORD dst_unused:UNUSED_PAD src0_sel:WORD_1 src1_sel:DWORD
	v_cmp_gt_i32_e32 vcc, 0, v49
	v_and_b32_sdwa v6, v36, s57 dst_sel:DWORD dst_unused:UNUSED_PAD src0_sel:WORD_1 src1_sel:DWORD
	v_xor_b32_sdwa v38, v35, v27 dst_sel:DWORD dst_unused:UNUSED_PAD src0_sel:WORD_1 src1_sel:DWORD
	v_cndmask_b32_e32 v5, v7, v5, vcc
	v_cmp_gt_i32_e32 vcc, 0, v36
	s_nop 1
	v_cndmask_b32_e32 v7, v11, v6, vcc
	v_cvt_f32_f16_e32 v18, v7
	v_and_b32_sdwa v7, v24, s57 dst_sel:DWORD dst_unused:UNUSED_PAD src0_sel:WORD_1 src1_sel:DWORD
	v_cmp_gt_i32_e32 vcc, 0, v24
	v_cvt_f32_f16_e32 v6, v5
	v_and_b32_sdwa v5, v44, s57 dst_sel:DWORD dst_unused:UNUSED_PAD src0_sel:WORD_1 src1_sel:DWORD
	v_xor_b32_sdwa v11, v44, v27 dst_sel:DWORD dst_unused:UNUSED_PAD src0_sel:WORD_1 src1_sel:DWORD
	v_cndmask_b32_e32 v7, v13, v7, vcc
	v_cmp_gt_i32_e32 vcc, 0, v44
	v_cvt_f32_f16_e32 v64, v7
	v_lshlrev_b32_e32 v7, 16, v31
	v_cndmask_b32_e32 v5, v11, v5, vcc
	v_cvt_f32_f16_e32 v24, v5
	v_lshlrev_b32_e32 v5, 24, v36
	v_and_b32_e32 v5, 0x7f000000, v5
	v_bitop3_b32 v17, v4, s75, v5 bitop3:0x36
	v_lshlrev_b32_e32 v5, 8, v32
	v_and_b32_e32 v4, 0x7f, v33
	v_and_b32_e32 v5, 0x7f00, v5
	v_and_b32_e32 v7, 0x7f0000, v7
	v_or3_b32 v4, v5, v4, v7
	v_lshlrev_b32_e32 v5, 24, v30
	v_and_b32_e32 v5, 0x7f000000, v5
	v_bitop3_b32 v19, v4, s75, v5 bitop3:0x36
	v_lshlrev_b32_e32 v5, 8, v1
	v_and_b32_e32 v11, 0x7f00, v5
	v_and_b32_sdwa v5, v55, s57 dst_sel:DWORD dst_unused:UNUSED_PAD src0_sel:WORD_1 src1_sel:DWORD
	v_xor_b32_sdwa v13, v55, v27 dst_sel:DWORD dst_unused:UNUSED_PAD src0_sel:WORD_1 src1_sel:DWORD
	v_cmp_gt_i32_e32 vcc, 0, v55
	v_and_b32_sdwa v7, v34, s57 dst_sel:DWORD dst_unused:UNUSED_PAD src0_sel:WORD_1 src1_sel:DWORD
	v_xor_b32_sdwa v36, v34, v27 dst_sel:DWORD dst_unused:UNUSED_PAD src0_sel:WORD_1 src1_sel:DWORD
	v_cndmask_b32_e32 v5, v13, v5, vcc
	v_cmp_gt_i32_e32 vcc, 0, v34
	v_and_b32_e32 v4, 0x7f, v3
	s_nop 0
	v_cndmask_b32_e32 v13, v36, v7, vcc
	v_cvt_f32_f16_e32 v7, v5
	v_cvt_f32_f16_e32 v5, v13
	v_bfe_u32 v13, v48, 16, 15
	v_not_b32_sdwa v36, v48 dst_sel:DWORD dst_unused:UNUSED_PAD src0_sel:WORD_1
	v_cmp_gt_i32_e32 vcc, 0, v48
	s_nop 1
	v_cndmask_b32_e32 v13, v36, v13, vcc
	v_cvt_f32_f16_e32 v67, v13
	v_lshlrev_b32_e32 v13, 16, v34
	v_and_b32_e32 v13, 0x7f0000, v13
	v_or3_b32 v11, v11, v4, v13
	v_bfe_u32 v4, v37, 16, 15
	v_not_b32_sdwa v13, v37 dst_sel:DWORD dst_unused:UNUSED_PAD src0_sel:WORD_1
	v_cmp_gt_i32_e32 vcc, 0, v37
	v_xor_b32_sdwa v36, v56, v27 dst_sel:DWORD dst_unused:UNUSED_PAD src0_sel:WORD_1 src1_sel:DWORD
	v_and_b32_sdwa v34, v35, s57 dst_sel:DWORD dst_unused:UNUSED_PAD src0_sel:WORD_1 src1_sel:DWORD
	v_cndmask_b32_e32 v4, v13, v4, vcc
	v_and_b32_sdwa v13, v56, s57 dst_sel:DWORD dst_unused:UNUSED_PAD src0_sel:WORD_1 src1_sel:DWORD
	v_cmp_gt_i32_e32 vcc, 0, v56
	v_cvt_f32_f16_e32 v4, v4
	s_nop 0
	v_cndmask_b32_e32 v13, v36, v13, vcc
	v_cmp_gt_i32_e32 vcc, 0, v35
	v_cvt_f32_f16_e32 v66, v13
	v_lshlrev_b32_e32 v13, 24, v37
	v_cndmask_b32_e32 v34, v38, v34, vcc
	v_cvt_f32_f16_e32 v68, v34
	v_and_b32_e32 v13, 0x7f000000, v13
	v_bitop3_b32 v34, v11, s75, v13 bitop3:0x36
	v_pk_add_f32 v[36:37], v[68:69], v[6:7] op_sel_hi:[0,1]
	v_cmp_lt_i32_e32 vcc, -1, v37
	v_pk_add_f32 v[38:39], v[68:69], v[8:9] op_sel_hi:[0,1]
	v_and_b32_e32 v13, 0xffffff00, v36
	v_cndmask_b32_e32 v11, v28, v29, vcc
	v_cmp_lt_i32_e32 vcc, -1, v36
	v_bitop3_b32 v35, v11, s3, v37 bitop3:0xde
	v_pk_add_f32 v[40:41], v[68:69], v[20:21] op_sel_hi:[0,1]
	v_cndmask_b32_e32 v11, v28, v29, vcc
	v_cmp_lt_i32_e32 vcc, -1, v39
	v_bitop3_b32 v36, v11, s0, v13 bitop3:0xde
	v_and_b32_e32 v13, 0xffffff00, v39
	v_cndmask_b32_e32 v11, v28, v29, vcc
	s_movk_i32 s0, 0xfd
	v_cmp_lt_i32_e32 vcc, -1, v38
	v_bitop3_b32 v37, v11, s0, v13 bitop3:0xde
	v_and_b32_e32 v13, 0xffffff00, v38
	v_cndmask_b32_e32 v11, v28, v29, vcc
	s_movk_i32 s0, 0xfc
; DI unsigned candkey(float s, int pos) { const unsigned b = __float_as_uint(s); const unsigned o = (b >> 31) ? ~b : (b ^ 0x80000000u); return (o & 0xffffff00u) | (unsigned)(255 - pos); }
; DI void phase10(const Params& P, char* smem) {
;     ...
;     C0[0] = candkey(v1[0] + v2[0], 0);
;     C0[1] = candkey(v1[0] + v2[1], 1);
;     C0[2] = candkey(v1[0] + v2[2], 2);
;     C0[3] = candkey(v1[0] + v2[3], 3);
;     C0[4] = candkey(v1[0] + v2[4], 4);
;     C0[5] = candkey(v1[0] + v2[5], 5);
;     C0[6] = candkey(v1[0] + v2[6], 6);
;     C0[7] = candkey(v1[0] + v2[7], 7);
;     C0[8] = candkey(v1[0] + v2[8], 8);
;     C0[9] = candkey(v1[0] + v2[9], 9);
;     C0[10] = candkey(v1[0] + v2[10], 10);
;     C0[11] = candkey(v1[0] + v2[11], 11);
;     C0[12] = candkey(v1[0] + v2[12], 12);
;     C0[13] = candkey(v1[0] + v2[13], 13);
;     C0[14] = candkey(v1[0] + v2[14], 14);
;     C0[15] = candkey(v1[0] + v2[15], 15);
;     C1[0] = candkey(v1[1] + v2[0], 16);
;     C1[1] = candkey(v1[1] + v2[1], 17);
;     C1[2] = candkey(v1[1] + v2[2], 18);
;     C1[3] = candkey(v1[1] + v2[3], 19);
;     C1[4] = candkey(v1[1] + v2[4], 20);
;     C1[5] = candkey(v1[1] + v2[5], 21);
;     C1[6] = candkey(v1[1] + v2[6], 22);
;     C1[7] = candkey(v1[1] + v2[7], 23);
;     C1[8] = candkey(v1[2] + v2[0], 32);
;     C1[9] = candkey(v1[2] + v2[1], 33);
;     C1[10] = candkey(v1[2] + v2[2], 34);
;     C1[11] = candkey(v1[2] + v2[3], 35);
;     C1[12] = candkey(v1[2] + v2[4], 36);
;     C1[13] = candkey(v1[3] + v2[0], 48);
;     C1[14] = candkey(v1[3] + v2[1], 49);
;     C1[15] = candkey(v1[3] + v2[2], 50);
	v_cmp_lt_i32_e32 vcc, -1, v41
	v_bitop3_b32 v38, v11, s0, v13 bitop3:0xde
	v_and_b32_e32 v13, 0xffffff00, v41
	v_cndmask_b32_e32 v11, v28, v29, vcc
	s_movk_i32 s0, 0xfb
	v_cmp_lt_i32_e32 vcc, -1, v40
	v_pk_add_f32 v[58:59], v[68:69], v[24:25] op_sel_hi:[0,1]
	v_bitop3_b32 v39, v11, s0, v13 bitop3:0xde
	v_cndmask_b32_e32 v11, v28, v29, vcc
	v_and_b32_e32 v13, 0xffffff00, v40
	s_movk_i32 s0, 0xfa
	v_cmp_lt_i32_e32 vcc, -1, v59
	v_bitop3_b32 v40, v11, s0, v13 bitop3:0xde
	v_and_b32_e32 v13, 0xffffff00, v59
	v_cndmask_b32_e32 v11, v28, v29, vcc
	s_movk_i32 s0, 0xf9
	v_bitop3_b32 v41, v11, s0, v13 bitop3:0xde
	v_and_b32_sdwa v11, v50, s57 dst_sel:DWORD dst_unused:UNUSED_PAD src0_sel:WORD_1 src1_sel:DWORD
	v_cmp_gt_i32_e32 vcc, 0, v50
	v_and_b32_sdwa v13, v43, s57 dst_sel:DWORD dst_unused:UNUSED_PAD src0_sel:WORD_1 src1_sel:DWORD
	v_xor_b32_sdwa v59, v43, v27 dst_sel:DWORD dst_unused:UNUSED_PAD src0_sel:WORD_1 src1_sel:DWORD
	v_cndmask_b32_e32 v11, v57, v11, vcc
	v_cmp_gt_i32_e32 vcc, 0, v43
	v_cvt_f32_f16_e32 v61, v11
	s_movk_i32 s0, 0xf8
	v_cndmask_b32_e32 v13, v59, v13, vcc
	v_cvt_f32_f16_e32 v60, v13
	v_cmp_lt_i32_e32 vcc, -1, v58
	v_and_b32_e32 v13, 0xffffff00, v58
	v_xor_b32_sdwa v59, v51, v27 dst_sel:DWORD dst_unused:UNUSED_PAD src0_sel:WORD_1 src1_sel:DWORD
	v_pk_add_f32 v[60:61], v[68:69], v[60:61] op_sel_hi:[0,1]
	v_cndmask_b32_e32 v11, v28, v29, vcc
	v_cmp_lt_i32_e32 vcc, -1, v61
	v_bitop3_b32 v57, v11, s0, v13 bitop3:0xde
	v_and_b32_e32 v13, 0xffffff00, v61
	v_cndmask_b32_e32 v11, v28, v29, vcc
	s_movk_i32 s0, 0xf7
	v_bitop3_b32 v58, v11, s0, v13 bitop3:0xde
	v_and_b32_sdwa v11, v51, s57 dst_sel:DWORD dst_unused:UNUSED_PAD src0_sel:WORD_1 src1_sel:DWORD
	v_cmp_gt_i32_e32 vcc, 0, v51
	v_and_b32_sdwa v13, v42, s57 dst_sel:DWORD dst_unused:UNUSED_PAD src0_sel:WORD_1 src1_sel:DWORD
	v_xor_b32_sdwa v61, v42, v27 dst_sel:DWORD dst_unused:UNUSED_PAD src0_sel:WORD_1 src1_sel:DWORD
	v_cndmask_b32_e32 v11, v59, v11, vcc
	v_cmp_gt_i32_e32 vcc, 0, v42
	v_cvt_f32_f16_e32 v63, v11
	s_movk_i32 s0, 0xf6
	v_cndmask_b32_e32 v13, v61, v13, vcc
	v_cvt_f32_f16_e32 v62, v13
	v_cmp_lt_i32_e32 vcc, -1, v60
	v_and_b32_e32 v13, 0xffffff00, v60
	v_xor_b32_sdwa v61, v47, v27 dst_sel:DWORD dst_unused:UNUSED_PAD src0_sel:WORD_1 src1_sel:DWORD
	v_pk_add_f32 v[62:63], v[68:69], v[62:63] op_sel_hi:[0,1]
	v_cndmask_b32_e32 v11, v28, v29, vcc
	v_cmp_lt_i32_e32 vcc, -1, v63
	v_bitop3_b32 v59, v11, s0, v13 bitop3:0xde
	v_and_b32_e32 v13, 0xffffff00, v63
	v_cndmask_b32_e32 v11, v28, v29, vcc
	s_movk_i32 s0, 0xf5
	v_bitop3_b32 v60, v11, s0, v13 bitop3:0xde
	v_and_b32_sdwa v11, v47, s57 dst_sel:DWORD dst_unused:UNUSED_PAD src0_sel:WORD_1 src1_sel:DWORD
	v_cmp_gt_i32_e32 vcc, 0, v47
	v_and_b32_sdwa v13, v23, s57 dst_sel:DWORD dst_unused:UNUSED_PAD src0_sel:WORD_1 src1_sel:DWORD
	v_xor_b32_sdwa v63, v23, v27 dst_sel:DWORD dst_unused:UNUSED_PAD src0_sel:WORD_1 src1_sel:DWORD
	v_cndmask_b32_e32 v11, v61, v11, vcc
	v_cmp_gt_i32_e32 vcc, 0, v23
	v_cvt_f32_f16_e32 v71, v11
	s_movk_i32 s0, 0xf4
	v_cndmask_b32_e32 v13, v63, v13, vcc
	v_cvt_f32_f16_e32 v70, v13
	v_cmp_lt_i32_e32 vcc, -1, v62
	v_and_b32_e32 v13, 0xffffff00, v62
	v_pk_add_f32 v[66:67], v[68:69], v[66:67] op_sel_hi:[0,1]
	v_pk_add_f32 v[70:71], v[68:69], v[70:71] op_sel_hi:[0,1]
	v_cndmask_b32_e32 v11, v28, v29, vcc
	v_cmp_lt_i32_e32 vcc, -1, v71
	v_bitop3_b32 v61, v11, s0, v13 bitop3:0xde
	v_and_b32_e32 v13, 0xffffff00, v71
	v_cndmask_b32_e32 v11, v28, v29, vcc
	s_movk_i32 s0, 0xf3
	v_cmp_lt_i32_e32 vcc, -1, v70
	v_bitop3_b32 v62, v11, s0, v13 bitop3:0xde
	v_and_b32_e32 v13, 0xffffff00, v70
	v_cndmask_b32_e32 v11, v28, v29, vcc
	s_movk_i32 s0, 0xf2
	v_cmp_lt_i32_e32 vcc, -1, v67
	v_bitop3_b32 v63, v11, s0, v13 bitop3:0xde
	v_and_b32_e32 v13, 0xffffff00, v67
	v_cndmask_b32_e32 v11, v28, v29, vcc
	s_movk_i32 s0, 0xf1
	v_bitop3_b32 v65, v11, s0, v13 bitop3:0xde
	v_cmp_lt_i32_e32 vcc, -1, v66
	v_and_b32_e32 v13, 0xffffff00, v66
	v_pk_add_f32 v[66:67], v[64:65], v[6:7] op_sel_hi:[0,1]
	v_cndmask_b32_e32 v11, v28, v29, vcc
	s_movk_i32 s0, 0xf0
	v_cmp_lt_i32_e32 vcc, -1, v67
	v_bitop3_b32 v68, v11, s0, v13 bitop3:0xde
	v_and_b32_e32 v13, 0xffffff00, v67
	v_cndmask_b32_e32 v11, v28, v29, vcc
	s_movk_i32 s0, 0xef
	v_bitop3_b32 v69, v11, s0, v13 bitop3:0xde
	v_cmp_lt_i32_e32 vcc, -1, v66
	v_and_b32_e32 v13, 0xffffff00, v66
	v_pk_add_f32 v[66:67], v[64:65], v[8:9] op_sel_hi:[0,1]
	v_cndmask_b32_e32 v11, v28, v29, vcc
	s_movk_i32 s0, 0xee
	v_cmp_lt_i32_e32 vcc, -1, v67
	v_bitop3_b32 v70, v11, s0, v13 bitop3:0xde
	v_and_b32_e32 v13, 0xffffff00, v67
	v_cndmask_b32_e32 v11, v28, v29, vcc
	s_movk_i32 s0, 0xed
	v_bitop3_b32 v71, v11, s0, v13 bitop3:0xde
	v_cmp_lt_i32_e32 vcc, -1, v66
	v_and_b32_e32 v13, 0xffffff00, v66
	v_pk_add_f32 v[66:67], v[64:65], v[20:21] op_sel_hi:[0,1]
	v_cndmask_b32_e32 v11, v28, v29, vcc
	s_movk_i32 s0, 0xec
	v_cmp_lt_i32_e32 vcc, -1, v67
	v_bitop3_b32 v72, v11, s0, v13 bitop3:0xde
	v_and_b32_e32 v13, 0xffffff00, v67
	v_cndmask_b32_e32 v11, v28, v29, vcc
	s_movk_i32 s0, 0xeb
	v_cmp_lt_i32_e32 vcc, -1, v66
	v_pk_add_f32 v[24:25], v[64:65], v[24:25] op_sel_hi:[0,1]
	v_bitop3_b32 v67, v11, s0, v13 bitop3:0xde
	v_cndmask_b32_e32 v11, v28, v29, vcc
	v_and_b32_e32 v13, 0xffffff00, v66
	s_movk_i32 s0, 0xea
	v_cmp_lt_i32_e32 vcc, -1, v25
	v_bitop3_b32 v66, v11, s0, v13 bitop3:0xde
	v_and_b32_e32 v13, 0xffffff00, v25
	v_cndmask_b32_e32 v11, v28, v29, vcc
	s_movk_i32 s0, 0xe9
	v_bitop3_b32 v64, v11, s0, v13 bitop3:0xde
	v_cmp_lt_i32_e32 vcc, -1, v24
	v_and_b32_e32 v13, 0xffffff00, v24
	v_pk_add_f32 v[24:25], v[22:23], v[6:7] op_sel_hi:[0,1]
	v_cndmask_b32_e32 v11, v28, v29, vcc
	v_cmp_lt_i32_e32 vcc, -1, v25
; DI unsigned candkey(float s, int pos) { const unsigned b = __float_as_uint(s); const unsigned o = (b >> 31) ? ~b : (b ^ 0x80000000u); return (o & 0xffffff00u) | (unsigned)(255 - pos); }
; DI void phase10(const Params& P, char* smem) {
;     ...
;     C1[0] = candkey(v1[1] + v2[0], 16);
;     C1[1] = candkey(v1[1] + v2[1], 17);
;     C1[2] = candkey(v1[1] + v2[2], 18);
;     C1[3] = candkey(v1[1] + v2[3], 19);
;     C1[4] = candkey(v1[1] + v2[4], 20);
;     C1[5] = candkey(v1[1] + v2[5], 21);
;     C1[6] = candkey(v1[1] + v2[6], 22);
;     C1[7] = candkey(v1[1] + v2[7], 23);
;     C1[8] = candkey(v1[2] + v2[0], 32);
;     C1[9] = candkey(v1[2] + v2[1], 33);
;     C1[10] = candkey(v1[2] + v2[2], 34);
;     C1[11] = candkey(v1[2] + v2[3], 35);
;     C1[12] = candkey(v1[2] + v2[4], 36);
;     C1[13] = candkey(v1[3] + v2[0], 48);
;     C1[14] = candkey(v1[3] + v2[1], 49);
;     C1[15] = candkey(v1[3] + v2[2], 50);
;     C2[0] = candkey(v1[3] + v2[3], 51);
;     C2[1] = candkey(v1[4] + v2[0], 64);
;     C2[2] = candkey(v1[4] + v2[1], 65);
;     C2[3] = candkey(v1[4] + v2[2], 66);
;     C2[4] = candkey(v1[5] + v2[0], 80);
;     C2[5] = candkey(v1[5] + v2[1], 81);
;     C2[6] = candkey(v1[6] + v2[0], 96);
;     C2[7] = candkey(v1[6] + v2[1], 97);
;     C2[8] = candkey(v1[7] + v2[0], 112);
;     C2[9] = candkey(v1[7] + v2[1], 113);
;     C2[10] = candkey(v1[8] + v2[0], 128);
;     C2[11] = candkey(v1[9] + v2[0], 144);
;     C2[12] = candkey(v1[10] + v2[0], 160);
;     C2[13] = candkey(v1[11] + v2[0], 176);
;     C2[14] = candkey(v1[12] + v2[0], 192);
;     C2[15] = candkey(v1[13] + v2[0], 208);
	v_bitop3_b32 v73, v11, s92, v13 bitop3:0xde
	v_and_b32_e32 v13, 0xffffff00, v25
	v_cndmask_b32_e32 v11, v28, v29, vcc
	v_bitop3_b32 v74, v11, s93, v13 bitop3:0xde
	v_cmp_lt_i32_e32 vcc, -1, v24
	v_and_b32_e32 v13, 0xffffff00, v24
	v_pk_add_f32 v[24:25], v[22:23], v[8:9] op_sel_hi:[0,1]
	v_cndmask_b32_e32 v11, v28, v29, vcc
	v_cmp_lt_i32_e32 vcc, -1, v25
	v_bitop3_b32 v75, v11, s94, v13 bitop3:0xde
	v_and_b32_e32 v13, 0xffffff00, v25
	v_cndmask_b32_e32 v11, v28, v29, vcc
	v_cmp_lt_i32_e32 vcc, -1, v24
	v_bitop3_b32 v76, v11, s95, v13 bitop3:0xde
	v_and_b32_e32 v13, 0xffffff00, v24
	v_cndmask_b32_e32 v11, v28, v29, vcc
	v_bitop3_b32 v77, v11, s96, v13 bitop3:0xde
	v_mov_b32_e32 v13, v22
	v_mov_b32_e32 v20, v7
	v_pk_add_f32 v[20:21], v[12:13], v[20:21]
	s_movk_i32 s0, 0x7f
	v_cmp_lt_i32_e32 vcc, -1, v21
	v_and_b32_e32 v13, 0xffffff00, v21
	v_mov_b32_e32 v21, v6
	v_cndmask_b32_e32 v11, v28, v29, vcc
	v_bitop3_b32 v22, v11, s97, v13 bitop3:0xde
	v_cmp_lt_i32_e32 vcc, -1, v20
	v_and_b32_e32 v13, 0xffffff00, v20
	v_mov_b32_e32 v20, v9
	v_pk_add_f32 v[24:25], v[12:13], v[20:21] op_sel_hi:[0,1]
	v_cndmask_b32_e32 v11, v28, v29, vcc
	v_cmp_lt_i32_e32 vcc, -1, v25
	v_bitop3_b32 v78, v11, s4, v13 bitop3:0xde
	v_and_b32_e32 v11, 0xffffff00, v25
	v_cndmask_b32_e32 v9, v28, v29, vcc
	v_cmp_lt_i32_e32 vcc, -1, v24
	v_bitop3_b32 v25, v9, s5, v11 bitop3:0xde
	v_and_b32_e32 v11, 0xffffff00, v24
	v_cndmask_b32_e32 v9, v28, v29, vcc
	v_bitop3_b32 v24, v9, s80, v11 bitop3:0xde
	v_mov_b32_e32 v11, v12
	v_mov_b32_e32 v12, v7
	v_mov_b32_e32 v13, v8
	v_pk_add_f32 v[8:9], v[10:11], v[12:13]
	s_nop 0
	v_cmp_lt_i32_e32 vcc, -1, v9
	v_and_b32_e32 v9, 0xffffff00, v9
	s_nop 0
	v_cndmask_b32_e32 v11, v28, v29, vcc
	v_cmp_lt_i32_e32 vcc, -1, v8
	v_bitop3_b32 v12, v11, s81, v9 bitop3:0xde
	v_and_b32_e32 v8, 0xffffff00, v8
	v_cndmask_b32_e32 v9, v28, v29, vcc
	v_bitop3_b32 v13, v9, s22, v8 bitop3:0xde
	v_pk_add_f32 v[8:9], v[10:11], v[20:21] op_sel_hi:[0,1]
	v_cmp_lt_i32_e32 vcc, -1, v9
	v_and_b32_e32 v9, 0xffffff00, v9
	v_xor_b32_sdwa v11, v33, v27 dst_sel:DWORD dst_unused:UNUSED_PAD src0_sel:WORD_1 src1_sel:DWORD
	v_cndmask_b32_e32 v10, v28, v29, vcc
	v_cmp_lt_i32_e32 vcc, -1, v8
	v_bitop3_b32 v20, v10, s23, v9 bitop3:0xde
	v_and_b32_e32 v8, 0xffffff00, v8
	v_cndmask_b32_e32 v9, v28, v29, vcc
	v_bitop3_b32 v21, v9, s82, v8 bitop3:0xde
	v_pk_add_f32 v[8:9], v[14:15], v[6:7] op_sel_hi:[0,1]
	v_cmp_lt_i32_e32 vcc, -1, v9
	v_and_b32_e32 v9, 0xffffff00, v9
	v_max_u32_e32 v84, v12, v13
	v_cndmask_b32_e32 v10, v28, v29, vcc
	v_cmp_lt_i32_e32 vcc, -1, v8
	v_bitop3_b32 v14, v10, s83, v9 bitop3:0xde
	v_and_b32_e32 v8, 0xffffff00, v8
	v_cndmask_b32_e32 v9, v28, v29, vcc
	v_bitop3_b32 v79, v9, s44, v8 bitop3:0xde
	v_pk_add_f32 v[8:9], v[16:17], v[6:7] op_sel_hi:[0,1]
	v_cmp_lt_i32_e32 vcc, -1, v9
	v_and_b32_e32 v9, 0xffffff00, v9
	v_min_u32_e32 v12, v12, v13
	v_cndmask_b32_e32 v10, v28, v29, vcc
	v_cmp_lt_i32_e32 vcc, -1, v8
	v_bitop3_b32 v16, v10, s45, v9 bitop3:0xde
	v_and_b32_e32 v8, 0xffffff00, v8
	v_cndmask_b32_e32 v9, v28, v29, vcc
	v_bitop3_b32 v80, v9, s33, v8 bitop3:0xde
	v_pk_add_f32 v[8:9], v[18:19], v[6:7] op_sel_hi:[0,1]
	v_cmp_lt_i32_e32 vcc, -1, v9
	v_and_b32_e32 v9, 0xffffff00, v9
	v_and_b32_sdwa v10, v32, s57 dst_sel:DWORD dst_unused:UNUSED_PAD src0_sel:WORD_1 src1_sel:DWORD
	v_cndmask_b32_e32 v6, v28, v29, vcc
	v_cmp_lt_i32_e32 vcc, -1, v8
	v_bitop3_b32 v18, v6, s87, v9 bitop3:0xde
	v_and_b32_sdwa v9, v33, s57 dst_sel:DWORD dst_unused:UNUSED_PAD src0_sel:WORD_1 src1_sel:DWORD
	v_cndmask_b32_e32 v6, v28, v29, vcc
	v_cmp_gt_i32_e32 vcc, 0, v33
	v_and_b32_e32 v8, 0xffffff00, v8
	v_xor_b32_sdwa v33, v30, v27 dst_sel:DWORD dst_unused:UNUSED_PAD src0_sel:WORD_1 src1_sel:DWORD
	v_cndmask_b32_e32 v9, v11, v9, vcc
	v_cmp_gt_i32_e32 vcc, 0, v32
	v_cvt_f32_f16_e32 v11, v9
	v_bitop3_b32 v32, v6, s2, v8 bitop3:0xde
	v_cndmask_b32_e32 v10, v81, v10, vcc
	v_cvt_f32_f16_e32 v10, v10
	v_mov_b32_e32 v6, v7
	v_max_u32_e32 v13, v20, v21
	v_min_u32_e32 v20, v20, v21
	v_pk_add_f32 v[8:9], v[6:7], v[10:11] op_sel_hi:[0,1]
	v_cmp_lt_i32_e32 vcc, -1, v9
	v_and_b32_e32 v9, 0xffffff00, v9
	v_xor_b32_sdwa v11, v31, v27 dst_sel:DWORD dst_unused:UNUSED_PAD src0_sel:WORD_1 src1_sel:DWORD
	v_cndmask_b32_e32 v7, v28, v29, vcc
	v_bitop3_b32 v7, v7, s0, v9 bitop3:0xde
	v_and_b32_sdwa v9, v31, s57 dst_sel:DWORD dst_unused:UNUSED_PAD src0_sel:WORD_1 src1_sel:DWORD
	v_cmp_gt_i32_e32 vcc, 0, v31
	v_and_b32_sdwa v10, v30, s57 dst_sel:DWORD dst_unused:UNUSED_PAD src0_sel:WORD_1 src1_sel:DWORD
	v_pk_add_f32 v[4:5], v[4:5], v[6:7] op_sel_hi:[1,0]
	v_cndmask_b32_e32 v9, v11, v9, vcc
	v_cmp_gt_i32_e32 vcc, 0, v30
	v_cvt_f32_f16_e32 v11, v9
	v_max_u32_e32 v21, v14, v79
	v_cndmask_b32_e32 v10, v33, v10, vcc
	v_cvt_f32_f16_e32 v10, v10
	v_cmp_lt_i32_e32 vcc, -1, v8
	v_and_b32_e32 v8, 0xffffff00, v8
	v_xor_b32_sdwa v33, v1, v27 dst_sel:DWORD dst_unused:UNUSED_PAD src0_sel:WORD_1 src1_sel:DWORD
	v_cndmask_b32_e32 v9, v28, v29, vcc
	v_bitop3_b32 v30, v9, s88, v8 bitop3:0xde
	v_pk_add_f32 v[8:9], v[6:7], v[10:11] op_sel_hi:[0,1]
	v_cmp_lt_i32_e32 vcc, -1, v9
	v_and_b32_e32 v9, 0xffffff00, v9
	v_xor_b32_sdwa v11, v3, v27 dst_sel:DWORD dst_unused:UNUSED_PAD src0_sel:WORD_1 src1_sel:DWORD
	v_cndmask_b32_e32 v10, v28, v29, vcc
	v_bitop3_b32 v31, v10, s89, v9 bitop3:0xde
	v_and_b32_sdwa v9, v3, s57 dst_sel:DWORD dst_unused:UNUSED_PAD src0_sel:WORD_1 src1_sel:DWORD
	v_cmp_gt_i32_e32 vcc, 0, v3
	v_and_b32_sdwa v10, v1, s57 dst_sel:DWORD dst_unused:UNUSED_PAD src0_sel:WORD_1 src1_sel:DWORD
	v_min_u32_e32 v14, v14, v79
	v_cndmask_b32_e32 v3, v11, v9, vcc
	v_cmp_gt_i32_e32 vcc, 0, v1
	v_cvt_f32_f16_e32 v11, v3
; DI unsigned candkey(float s, int pos) { const unsigned b = __float_as_uint(s); const unsigned o = (b >> 31) ? ~b : (b ^ 0x80000000u); return (o & 0xffffff00u) | (unsigned)(255 - pos); }
; DI void phase10(const Params& P, char* smem) {
;     ...
;     C2[0] = candkey(v1[3] + v2[3], 51);
;     C2[1] = candkey(v1[4] + v2[0], 64);
;     C2[2] = candkey(v1[4] + v2[1], 65);
;     C2[3] = candkey(v1[4] + v2[2], 66);
;     C2[4] = candkey(v1[5] + v2[0], 80);
;     C2[5] = candkey(v1[5] + v2[1], 81);
;     C2[6] = candkey(v1[6] + v2[0], 96);
;     C2[7] = candkey(v1[6] + v2[1], 97);
;     C2[8] = candkey(v1[7] + v2[0], 112);
;     C2[9] = candkey(v1[7] + v2[1], 113);
;     C2[10] = candkey(v1[8] + v2[0], 128);
;     C2[11] = candkey(v1[9] + v2[0], 144);
;     C2[12] = candkey(v1[10] + v2[0], 160);
;     C2[13] = candkey(v1[11] + v2[0], 176);
;     C2[14] = candkey(v1[12] + v2[0], 192);
;     C2[15] = candkey(v1[13] + v2[0], 208);
;     C3[0] = candkey(v1[14] + v2[0], 224);
;     C3[1] = candkey(v1[15] + v2[0], 240);
;     C3[2] = 0u;
;     C3[3] = 0u;
;     C3[4] = 0u;
;     C3[5] = 0u;
;     C3[6] = 0u;
;     C3[7] = 0u;
;     C3[8] = 0u;
;     C3[9] = 0u;
;     C3[10] = 0u;
;     C3[11] = 0u;
;     C3[12] = 0u;
;     C3[13] = 0u;
;     C3[14] = 0u;
;     C3[15] = 0u;
;     SORT16(C1) SORT16(C2) SORT16(C3)
	v_and_b32_e32 v3, 0xffffff00, v8
	v_cndmask_b32_e32 v1, v33, v10, vcc
	v_cvt_f32_f16_e32 v10, v1
	v_cmp_lt_i32_e32 vcc, -1, v8
	v_max_u32_e32 v33, v67, v66
	v_min_u32_e32 v66, v67, v66
	v_pk_add_f32 v[8:9], v[6:7], v[10:11] op_sel_hi:[0,1]
	v_cndmask_b32_e32 v1, v28, v29, vcc
	v_cmp_lt_i32_e32 vcc, -1, v9
	v_bitop3_b32 v1, v1, s90, v3 bitop3:0xde
	v_and_b32_e32 v9, 0xffffff00, v9
	v_cndmask_b32_e32 v3, v28, v29, vcc
	v_cmp_lt_i32_e32 vcc, -1, v8
	v_bitop3_b32 v3, v3, 63, v9 bitop3:0xde
	v_and_b32_e32 v8, 0xffffff00, v8
	v_cndmask_b32_e32 v9, v28, v29, vcc
	v_cmp_lt_i32_e32 vcc, -1, v5
	v_and_b32_e32 v5, 0xffffff00, v5
	v_bitop3_b32 v8, v9, 47, v8 bitop3:0xde
	v_cndmask_b32_e32 v6, v28, v29, vcc
	v_cmp_lt_i32_e32 vcc, -1, v4
	v_bitop3_b32 v5, v6, 31, v5 bitop3:0xde
	v_and_b32_e32 v4, 0xffffff00, v4
	v_cndmask_b32_e32 v6, v28, v29, vcc
	v_bitop3_b32 v4, v6, 15, v4 bitop3:0xde
	v_max_u32_e32 v6, v69, v70
	v_min_u32_e32 v9, v69, v70
	v_max_u32_e32 v10, v71, v72
	v_min_u32_e32 v11, v71, v72
	v_max_u32_e32 v67, v64, v73
	v_min_u32_e32 v64, v64, v73
	v_max_u32_e32 v69, v74, v75
	v_min_u32_e32 v70, v74, v75
	v_max_u32_e32 v71, v76, v77
	v_min_u32_e32 v72, v76, v77
	v_max_u32_e32 v73, v22, v78
	v_min_u32_e32 v22, v22, v78
	v_max_u32_e32 v74, v25, v24
	v_min_u32_e32 v24, v25, v24
	v_max_u32_e32 v25, v6, v10
	v_min_u32_e32 v6, v6, v10
	v_max_u32_e32 v10, v9, v11
	v_min_u32_e32 v9, v9, v11
	v_max_u32_e32 v11, v33, v67
	v_min_u32_e32 v33, v33, v67
	v_max_u32_e32 v67, v66, v64
	v_min_u32_e32 v64, v66, v64
	v_max_u32_e32 v66, v69, v71
	v_min_u32_e32 v69, v69, v71
	v_max_u32_e32 v71, v70, v72
	v_min_u32_e32 v70, v70, v72
	v_max_u32_e32 v72, v73, v74
	v_min_u32_e32 v73, v73, v74
	v_max_u32_e32 v74, v22, v24
	v_min_u32_e32 v22, v22, v24
	v_max_u32_e32 v24, v10, v6
	v_min_u32_e32 v6, v10, v6
	v_max_u32_e32 v10, v67, v33
	v_min_u32_e32 v33, v67, v33
	v_max_u32_e32 v67, v71, v69
	v_min_u32_e32 v69, v71, v69
	v_max_u32_e32 v71, v74, v73
	v_min_u32_e32 v73, v74, v73
	v_max_u32_e32 v74, v25, v11
	v_min_u32_e32 v11, v25, v11
	v_max_u32_e32 v25, v24, v10
	v_min_u32_e32 v10, v24, v10
	v_max_u32_e32 v24, v6, v33
	v_min_u32_e32 v6, v6, v33
	v_max_u32_e32 v33, v9, v64
	v_min_u32_e32 v9, v9, v64
	v_max_u32_e32 v64, v66, v72
	v_min_u32_e32 v66, v66, v72
	v_max_u32_e32 v72, v67, v71
	v_min_u32_e32 v67, v67, v71
	v_max_u32_e32 v71, v69, v73
	v_min_u32_e32 v69, v69, v73
	v_max_u32_e32 v73, v70, v22
	v_min_u32_e32 v22, v70, v22
	v_max_u32_e32 v70, v24, v11
	v_min_u32_e32 v11, v24, v11
	v_max_u32_e32 v24, v33, v10
	v_min_u32_e32 v10, v33, v10
	v_max_u32_e32 v33, v71, v66
	v_min_u32_e32 v66, v71, v66
	v_max_u32_e32 v71, v73, v67
	v_min_u32_e32 v67, v73, v67
	v_max_u32_e32 v73, v25, v70
	v_min_u32_e32 v25, v25, v70
	v_max_u32_e32 v70, v24, v11
	v_min_u32_e32 v11, v24, v11
	v_max_u32_e32 v24, v10, v6
	v_min_u32_e32 v6, v10, v6
	v_max_u32_e32 v10, v72, v33
	v_min_u32_e32 v33, v72, v33
	v_max_u32_e32 v72, v71, v66
	v_min_u32_e32 v66, v71, v66
	v_max_u32_e32 v71, v67, v69
	v_min_u32_e32 v67, v67, v69
	v_max_u32_e32 v79, v16, v80
	v_min_u32_e32 v16, v16, v80
	v_max_u32_e32 v80, v18, v32
	v_min_u32_e32 v18, v18, v32
	v_max_u32_e32 v32, v7, v30
	v_min_u32_e32 v7, v7, v30
	v_max_u32_e32 v30, v31, v1
	v_min_u32_e32 v1, v31, v1
	v_max_u32_e32 v31, v3, v8
	v_min_u32_e32 v3, v3, v8
	v_min_u32_e32 v69, v74, v64
	v_max_u32_e32 v75, v73, v10
	v_min_u32_e32 v10, v73, v10
	v_max_u32_e32 v73, v25, v33
	v_min_u32_e32 v25, v25, v33
	v_max_u32_e32 v33, v70, v72
	v_min_u32_e32 v70, v70, v72
	v_max_u32_e32 v72, v11, v66
	v_min_u32_e32 v11, v11, v66
	v_max_u32_e32 v66, v24, v71
	v_min_u32_e32 v24, v24, v71
	v_max_u32_e32 v71, v6, v67
	v_min_u32_e32 v6, v6, v67
	v_max_u32_e32 v67, v9, v22
	v_max_u32_e32 v8, v84, v13
	v_min_u32_e32 v13, v84, v13
	v_max_u32_e32 v84, v12, v20
	v_min_u32_e32 v12, v12, v20
	v_max_u32_e32 v20, v21, v79
	v_min_u32_e32 v21, v21, v79
	v_max_u32_e32 v79, v14, v16
	v_min_u32_e32 v14, v14, v16
	v_max_u32_e32 v16, v80, v32
	v_min_u32_e32 v32, v80, v32
	v_max_u32_e32 v80, v18, v7
	v_min_u32_e32 v7, v18, v7
	v_max_u32_e32 v18, v30, v31
	v_min_u32_e32 v30, v30, v31
	v_max_u32_e32 v31, v1, v3
	v_min_u32_e32 v9, v9, v22
	v_max_u32_e32 v22, v72, v69
	v_min_u32_e32 v69, v72, v69
	v_max_u32_e32 v72, v66, v10
	v_min_u32_e32 v10, v66, v10
	v_max_u32_e32 v66, v71, v25
	v_min_u32_e32 v25, v71, v25
	v_max_u32_e32 v71, v67, v70
	v_min_u32_e32 v67, v67, v70
	v_min_u32_e32 v1, v1, v3
	v_max_u32_e32 v3, v84, v13
	v_min_u32_e32 v13, v84, v13
	v_max_u32_e32 v84, v79, v21
	v_min_u32_e32 v21, v79, v21
	v_max_u32_e32 v79, v80, v32
	v_min_u32_e32 v32, v80, v32
	v_max_u32_e32 v80, v31, v30
	v_min_u32_e32 v30, v31, v30
	v_max_u32_e32 v70, v73, v22
	v_min_u32_e32 v22, v73, v22
	v_max_u32_e32 v73, v33, v72
	v_min_u32_e32 v33, v33, v72
	v_max_u32_e32 v72, v66, v69
	v_min_u32_e32 v66, v66, v69
	v_max_u32_e32 v69, v71, v10
	v_min_u32_e32 v10, v71, v10
	v_max_u32_e32 v71, v25, v11
	v_min_u32_e32 v11, v25, v11
	v_max_u32_e32 v25, v67, v24
	v_min_u32_e32 v24, v67, v24
	v_max_u32_e32 v31, v8, v20
	v_min_u32_e32 v8, v8, v20
	v_max_u32_e32 v20, v3, v84
	v_min_u32_e32 v3, v3, v84
	v_max_u32_e32 v84, v13, v21
	v_min_u32_e32 v13, v13, v21
	v_max_u32_e32 v21, v12, v14
	v_min_u32_e32 v12, v12, v14
	v_max_u32_e32 v14, v16, v18
	v_min_u32_e32 v16, v16, v18
	v_max_u32_e32 v18, v79, v80
	v_min_u32_e32 v79, v79, v80
	v_max_u32_e32 v80, v32, v30
	v_min_u32_e32 v30, v32, v30
	v_max_u32_e32 v32, v7, v1
	v_min_u32_e32 v67, v75, v70
	v_min_u32_e32 v76, v73, v22
	v_min_u32_e32 v77, v33, v72
	v_min_u32_e32 v78, v69, v66
	v_min_u32_e32 v81, v10, v71
	v_min_u32_e32 v82, v25, v11
	v_min_u32_e32 v83, v24, v6
	v_min_u32_e32 v1, v7, v1
; DI unsigned lut4(const unsigned (&W)[4], int a) { const int j = a >> 2; const unsigned w = j == 0 ? W[0] : (j == 1 ? W[1] : (j == 2 ? W[2] : W[3])); return (w >> ((a & 3) * 8)) & 0xffu; }
; DI void phase10(const Params& P, char* smem) {
;     ...
;     SORT16(C1) SORT16(C2) SORT16(C3)
;     MERGE16(C0, C1) MERGE16(C0, C2) MERGE16(C0, C3)
;     float e[16]; int te[16]; float sum = 0.f;
;     const float tv0 = [&]() { const unsigned o = C0[0] & 0xffffff00u; return __uint_as_float((o >> 31) ? (o ^ 0x80000000u) : ~o); }();
; #pragma unroll
;     for (int k = 0; k < 16; ++k) {
;       const unsigned key = C0[k]; const unsigned o = key & 0xffffff00u;
;       const float val = __uint_as_float((o >> 31) ? (o ^ 0x80000000u) : ~o);
;       const int pos = 255 - (int)(key & 255u);
;       te[k] = (int)(lut4(W1, pos >> 4) * 128u + lut4(W2, pos & 15));
;       e[k] = __expf(val - tv0); sum += e[k];
	v_max_u32_e32 v7, v84, v8
	v_min_u32_e32 v8, v84, v8
	v_max_u32_e32 v84, v21, v3
	v_min_u32_e32 v3, v21, v3
	v_max_u32_e32 v21, v80, v16
	v_min_u32_e32 v16, v80, v16
	v_max_u32_e32 v80, v32, v79
	v_min_u32_e32 v32, v32, v79
	v_max_u32_e32 v79, v20, v7
	v_min_u32_e32 v7, v20, v7
	v_max_u32_e32 v20, v84, v8
	v_min_u32_e32 v8, v84, v8
	v_max_u32_e32 v84, v3, v13
	v_min_u32_e32 v3, v3, v13
	v_max_u32_e32 v13, v18, v21
	v_min_u32_e32 v18, v18, v21
	v_max_u32_e32 v21, v80, v16
	v_min_u32_e32 v16, v80, v16
	v_max_u32_e32 v80, v32, v30
	v_min_u32_e32 v30, v32, v30
	v_max_u32_e32 v9, v35, v9
	v_max_u32_e32 v35, v36, v83
	v_max3_u32 v6, v37, v24, v6
	v_max_u32_e32 v24, v38, v82
	v_max3_u32 v11, v39, v25, v11
	v_max_u32_e32 v25, v40, v81
	v_max3_u32 v10, v41, v10, v71
	v_max_u32_e32 v36, v57, v78
	v_max3_u32 v37, v58, v69, v66
	v_max_u32_e32 v38, v59, v77
	v_max3_u32 v33, v60, v33, v72
	v_max_u32_e32 v39, v61, v76
	v_max3_u32 v22, v62, v73, v22
	v_max_u32_e32 v40, v63, v67
	v_max3_u32 v41, v65, v75, v70
	v_max3_u32 v57, v68, v74, v64
	v_min_u32_e32 v32, v31, v14
	v_max_u32_e32 v85, v79, v13
	v_min_u32_e32 v13, v79, v13
	v_max_u32_e32 v79, v7, v18
	v_min_u32_e32 v7, v7, v18
	v_max_u32_e32 v18, v20, v21
	v_min_u32_e32 v20, v20, v21
	v_max_u32_e32 v21, v8, v16
	v_min_u32_e32 v8, v8, v16
	v_max_u32_e32 v16, v84, v80
	v_min_u32_e32 v80, v84, v80
	v_max_u32_e32 v84, v3, v30
	v_min_u32_e32 v3, v3, v30
	v_max_u32_e32 v30, v12, v1
	v_max_u32_e32 v58, v9, v37
	v_min_u32_e32 v9, v9, v37
	v_max_u32_e32 v37, v35, v38
	v_min_u32_e32 v35, v35, v38
	v_max_u32_e32 v38, v6, v33
	v_min_u32_e32 v6, v6, v33
	v_max_u32_e32 v33, v24, v39
	v_min_u32_e32 v24, v24, v39
	v_max_u32_e32 v39, v11, v22
	v_min_u32_e32 v11, v11, v22
	v_max_u32_e32 v22, v25, v40
	v_min_u32_e32 v25, v25, v40
	v_max_u32_e32 v40, v10, v41
	v_min_u32_e32 v10, v10, v41
	v_max_u32_e32 v41, v36, v57
	v_min_u32_e32 v36, v36, v57
	v_min_u32_e32 v1, v12, v1
	v_max_u32_e32 v12, v21, v32
	v_min_u32_e32 v21, v21, v32
	v_max_u32_e32 v32, v16, v13
	v_min_u32_e32 v13, v16, v13
	v_max_u32_e32 v16, v84, v7
	v_min_u32_e32 v7, v84, v7
	v_max_u32_e32 v84, v30, v20
	v_min_u32_e32 v20, v30, v20
	v_max_u32_e32 v57, v58, v39
	v_min_u32_e32 v39, v58, v39
	v_max_u32_e32 v58, v37, v22
	v_min_u32_e32 v22, v37, v22
	v_max_u32_e32 v37, v38, v40
	v_min_u32_e32 v38, v38, v40
	v_max_u32_e32 v40, v33, v41
	v_min_u32_e32 v33, v33, v41
	v_max_u32_e32 v41, v9, v11
	v_min_u32_e32 v9, v9, v11
	v_max_u32_e32 v11, v35, v25
	v_min_u32_e32 v25, v35, v25
	v_max_u32_e32 v35, v6, v10
	v_min_u32_e32 v6, v6, v10
	v_max_u32_e32 v10, v24, v36
	v_min_u32_e32 v24, v24, v36
	v_max_u32_e32 v30, v79, v12
	v_min_u32_e32 v12, v79, v12
	v_max_u32_e32 v79, v18, v32
	v_min_u32_e32 v18, v18, v32
	v_max_u32_e32 v32, v16, v21
	v_min_u32_e32 v16, v16, v21
	v_max_u32_e32 v21, v84, v13
	v_min_u32_e32 v13, v84, v13
	v_max_u32_e32 v84, v7, v8
	v_min_u32_e32 v7, v7, v8
	v_max_u32_e32 v8, v20, v80
	v_min_u32_e32 v20, v20, v80
	v_max_u32_e32 v36, v57, v37
	v_min_u32_e32 v37, v57, v37
	v_max_u32_e32 v57, v58, v40
	v_min_u32_e32 v40, v58, v40
	v_max_u32_e32 v58, v39, v38
	v_min_u32_e32 v38, v39, v38
	v_max_u32_e32 v39, v22, v33
	v_min_u32_e32 v22, v22, v33
	v_max_u32_e32 v33, v41, v35
	v_min_u32_e32 v35, v41, v35
	v_max_u32_e32 v41, v11, v10
	v_min_u32_e32 v10, v11, v10
	v_max_u32_e32 v11, v9, v6
	v_min_u32_e32 v6, v9, v6
	v_max_u32_e32 v9, v25, v24
	v_min_u32_e32 v24, v25, v24
	v_max_u32_e32 v80, v85, v30
	v_min_u32_e32 v30, v85, v30
	v_max_u32_e32 v85, v79, v12
	v_min_u32_e32 v12, v79, v12
	v_max_u32_e32 v79, v18, v32
	v_min_u32_e32 v18, v18, v32
	v_max_u32_e32 v32, v21, v16
	v_min_u32_e32 v16, v21, v16
	v_max_u32_e32 v21, v13, v84
	v_min_u32_e32 v13, v13, v84
	v_max_u32_e32 v84, v8, v7
	v_min_u32_e32 v7, v8, v7
	v_max_u32_e32 v8, v20, v3
	v_min_u32_e32 v3, v20, v3
	v_min_u32_e32 v25, v36, v57
	v_min_u32_e32 v59, v37, v40
	v_min_u32_e32 v60, v58, v39
	v_min_u32_e32 v61, v38, v22
	v_min_u32_e32 v62, v33, v41
	v_min_u32_e32 v63, v35, v10
	v_min_u32_e32 v64, v11, v9
	v_min_u32_e32 v65, v6, v24
	v_max3_u32 v1, v36, v57, v1
	v_max_u32_e32 v3, v25, v3
	v_max3_u32 v8, v37, v40, v8
	v_max_u32_e32 v7, v59, v7
	v_max3_u32 v25, v58, v39, v84
	v_max_u32_e32 v13, v60, v13
	v_max3_u32 v21, v38, v22, v21
	v_max_u32_e32 v16, v61, v16
	v_max3_u32 v22, v33, v41, v32
	v_max_u32_e32 v18, v62, v18
	v_max3_u32 v10, v35, v10, v79
	v_max_u32_e32 v12, v63, v12
	v_max3_u32 v9, v11, v9, v85
	v_max_u32_e32 v11, v64, v30
	v_max3_u32 v6, v6, v24, v80
	v_max3_u32 v14, v65, v31, v14
	v_max_u32_e32 v24, v1, v22
	v_min_u32_e32 v1, v1, v22
	v_max_u32_e32 v22, v3, v18
	v_min_u32_e32 v3, v3, v18
	v_max_u32_e32 v18, v8, v10
	v_min_u32_e32 v8, v8, v10
	v_max_u32_e32 v10, v7, v12
	v_min_u32_e32 v7, v7, v12
	v_max_u32_e32 v12, v25, v9
	v_min_u32_e32 v9, v25, v9
	v_max_u32_e32 v25, v13, v11
	v_min_u32_e32 v11, v13, v11
	v_max_u32_e32 v13, v21, v6
	v_min_u32_e32 v6, v21, v6
	v_max_u32_e32 v21, v16, v14
	v_min_u32_e32 v14, v16, v14
	v_max_u32_e32 v16, v24, v12
	v_min_u32_e32 v12, v24, v12
	v_max_u32_e32 v24, v22, v25
	v_min_u32_e32 v22, v22, v25
	v_max_u32_e32 v25, v18, v13
	v_min_u32_e32 v13, v18, v13
	v_max_u32_e32 v18, v10, v21
	v_min_u32_e32 v10, v10, v21
	v_max_u32_e32 v21, v1, v9
	v_min_u32_e32 v1, v1, v9
	v_max_u32_e32 v9, v3, v11
	v_min_u32_e32 v3, v3, v11
	v_max_u32_e32 v11, v8, v6
	v_min_u32_e32 v6, v8, v6
	v_max_u32_e32 v8, v7, v14
	v_min_u32_e32 v7, v7, v14
	v_max_u32_e32 v14, v16, v25
	v_min_u32_e32 v16, v16, v25
	v_max_u32_e32 v25, v24, v18
	v_min_u32_e32 v18, v24, v18
	v_max_u32_e32 v24, v12, v13
	v_min_u32_e32 v12, v12, v13
	v_max_u32_e32 v13, v22, v10
	v_min_u32_e32 v10, v22, v10
	v_max_u32_e32 v22, v21, v11
	v_min_u32_e32 v11, v21, v11
	v_max_u32_e32 v21, v9, v8
	v_min_u32_e32 v8, v9, v8
	v_max_u32_e32 v9, v1, v6
	v_min_u32_e32 v1, v1, v6
	v_max_u32_e32 v6, v3, v7
	v_min_u32_e32 v3, v3, v7
	v_min_u32_e32 v20, v5, v4
	v_max_u32_e32 v69, v9, v6
	v_min_u32_e32 v70, v9, v6
	v_min_u32_e32 v6, v1, v3
	v_max_u32_e32 v57, v14, v25
	v_min_u32_e32 v58, v14, v25
	v_max_u32_e32 v59, v16, v18
	v_min_u32_e32 v60, v16, v18
	v_max_u32_e32 v61, v24, v13
	v_min_u32_e32 v62, v24, v13
	v_max_u32_e32 v63, v12, v10
	v_min_u32_e32 v64, v12, v10
	v_max_u32_e32 v65, v22, v21
	v_min_u32_e32 v66, v22, v21
	v_max_u32_e32 v67, v11, v8
	v_min_u32_e32 v68, v11, v8
	v_max3_u32 v71, v1, v3, v20
	v_max3_u32 v72, v6, v5, v4
	v_max_u32_e32 v11, v57, v65
	v_max_u32_e32 v12, v58, v66
	v_max_u32_e32 v13, v59, v67
	v_max_u32_e32 v32, v60, v68
	v_max_u32_e32 v33, v61, v69
	v_max_u32_e32 v35, v62, v70
	v_max_u32_e32 v36, v63, v71
	v_max_u32_e32 v37, v64, v72
	v_max_u32_e32 v9, v11, v33
	v_max_u32_e32 v10, v12, v35
	v_max_u32_e32 v22, v13, v36
	v_max_u32_e32 v24, v32, v37
	v_max_u32_e32 v8, v9, v22
	v_max_u32_e32 v18, v10, v24
	v_max_u32_e32 v4, v8, v18
	v_bitop3_b32 v1, v4, s3, v4 bitop3:0xc
	v_cmp_lt_u32_e32 vcc, 63, v1
	v_mov_b32_e32 v3, v15
	s_and_saveexec_b64 s[0:1], vcc
	s_cbranch_execz .LBB0_1193
; DI unsigned lut4(const unsigned (&W)[4], int a) { const int j = a >> 2; const unsigned w = j == 0 ? W[0] : (j == 1 ? W[1] : (j == 2 ? W[2] : W[3])); return (w >> ((a & 3) * 8)) & 0xffu; }
; DI void phase10(const Params& P, char* smem) {
;     ...
;     const float tv0 = [&]() { const unsigned o = C0[0] & 0xffffff00u; return __uint_as_float((o >> 31) ? (o ^ 0x80000000u) : ~o); }();
; #pragma unroll
;     for (int k = 0; k < 16; ++k) {
;       const unsigned key = C0[k]; const unsigned o = key & 0xffffff00u;
;       const float val = __uint_as_float((o >> 31) ? (o ^ 0x80000000u) : ~o);
;       const int pos = 255 - (int)(key & 255u);
;       te[k] = (int)(lut4(W1, pos >> 4) * 128u + lut4(W2, pos & 15));
	v_lshrrev_b32_e32 v5, 6, v1
	v_cmp_lt_i32_e32 vcc, 1, v5
	s_mov_b64 s[6:7], 0
	s_and_saveexec_b64 s[8:9], vcc
	s_xor_b64 s[8:9], exec, s[8:9]
	s_cbranch_execnz .LBB0_1381
	s_or_saveexec_b64 s[8:9], s[8:9]
	v_mov_b32_e32 v3, v19
	s_xor_b64 exec, exec, s[8:9]
	s_cbranch_execnz .LBB0_1384
